# GEMM K-loops (6 instances): LDB(B0) ds_reads moved one phase earlier into the read-free phases, extra counted vmcnt(10) in phases 3/7
# speedup vs baseline: 1.0084x; 1.0028x over previous
; #define LDA(dst, b, h) for (int m = 0; m < 4; ++m) for (int k = 0; k < 2; ++k) \
;     dst[m][k] = *reinterpret_cast<const bf16x8*>((char*)SA(b, h) + lds_byte(wr * 64 + m * 16 + fr, k * 32 + fq * 8))
; #define LDB(dst, b, h) for (int n = 0; n < 2; ++n) for (int k = 0; k < 2; ++k) \
;     dst[n][k] = *reinterpret_cast<const bf16x8*>((char*)SB(b, h) + lds_byte(wc * 32 + n * 16 + fr, k * 32 + fq * 8))
; #define WAIT_V(n) asm volatile("s_waitcnt vmcnt(" #n ")" ::: "memory")
; #define WAIT_L(n) asm volatile("s_waitcnt lgkmcnt(" #n ")" ::: "memory")
; #define BAR __builtin_amdgcn_s_barrier()
; #define SCHED __builtin_amdgcn_sched_barrier(0)
; template <class Epi>
; DEVI void gemm_phase(const Params& p, const u16* __restrict__ A, const u16* __restrict__ Bt, const int M, const int N, const int K, const int Msplit, const Epi& epi) {
;     ...
;     f32x4 acc[2][2][4][2] = {};
;     bf16x8 At[4][2], B0[2][2], B1[2][2];
;     if (it == 0) { WAIT_V(0); } else { if constexpr (Epi::NST == 16) WAIT_V(16); else if constexpr (Epi::NST == 32) WAIT_V(32); else WAIT_V(0); }
;     if (wr == 1) BAR;
;     BAR;
;     BAR;
;     for (int t = 0; t < nt - 2; t += 2) {
;       LDB(B0, 0, 0); SCHED; LDA(At, 0, 0); STAGE(SA(1, 1), A, brow + HALF, t + 1);
;       WAIT_L(8); BAR; WAIT_L(0); MMA(0, 0, At, B0); BAR; SCHED;
.LBB0_682:
	s_or_b64 exec, exec, s[12:13]
	s_lshl_b32 s90, s16, 8
	s_or_b32 s12, s90, 0x80
	s_mov_b32 s13, s91
	s_lshl_b32 s18, s17, 8
	s_lshl_b64 s[12:13], s[12:13], 11
	s_add_u32 s22, s68, s12
	s_mov_b32 s19, s91
	s_addc_u32 s23, s69, s13
	s_lshl_b64 s[12:13], s[18:19], 11
	s_add_u32 s19, s0, s12
	s_addc_u32 s41, s1, s13
	s_lshl_b64 s[12:13], s[90:91], 11
	s_add_u32 s42, s68, s12
	s_addc_u32 s43, s69, s13
	s_or_b32 s12, s18, 0x80
	s_mov_b32 s13, s91
	s_lshl_b64 s[12:13], s[12:13], 11
	s_add_u32 s48, s0, s12
	s_addc_u32 s49, s1, s13
	s_add_u32 s52, s22, 0x100
	s_mov_b32 s17, s91
	s_addc_u32 s53, s23, 0
	s_lshl_b64 s[12:13], s[16:17], 19
	v_readlane_b32 s17, v254, 50
	s_add_u32 s17, s17, s12
	v_readlane_b32 s12, v254, 51
	v_mov_b32_e32 v8, 0
	s_addc_u32 s56, s12, s13
	s_mov_b64 s[12:13], 0
	s_mov_b32 s57, -2
	v_mov_b32_e32 v9, v8
	v_mov_b32_e32 v10, v8
	v_mov_b32_e32 v11, v8
	v_mov_b32_e32 v12, v8
	v_mov_b32_e32 v13, v8
	v_mov_b32_e32 v14, v8
	v_mov_b32_e32 v15, v8
	v_mov_b32_e32 v16, v8
	v_mov_b32_e32 v17, v8
	v_mov_b32_e32 v18, v8
	v_mov_b32_e32 v19, v8
	v_mov_b32_e32 v20, v8
	v_mov_b32_e32 v21, v8
	v_mov_b32_e32 v22, v8
	v_mov_b32_e32 v23, v8
	v_mov_b32_e32 v24, v8
	v_mov_b32_e32 v25, v8
	v_mov_b32_e32 v26, v8
	v_mov_b32_e32 v27, v8
	v_mov_b32_e32 v28, v8
	v_mov_b32_e32 v29, v8
	v_mov_b32_e32 v30, v8
	v_mov_b32_e32 v31, v8
	v_mov_b32_e32 v32, v8
	v_mov_b32_e32 v33, v8
	v_mov_b32_e32 v34, v8
	v_mov_b32_e32 v35, v8
	v_mov_b32_e32 v36, v8
	v_mov_b32_e32 v37, v8
	v_mov_b32_e32 v38, v8
	v_mov_b32_e32 v39, v8
	v_mov_b32_e32 v40, v8
	v_mov_b32_e32 v41, v8
	v_mov_b32_e32 v42, v8
	v_mov_b32_e32 v43, v8
	v_mov_b32_e32 v44, v8
	v_mov_b32_e32 v45, v8
	v_mov_b32_e32 v46, v8
	v_mov_b32_e32 v47, v8
	v_mov_b32_e32 v48, v8
	v_mov_b32_e32 v49, v8
	v_mov_b32_e32 v50, v8
	v_mov_b32_e32 v51, v8
	v_mov_b32_e32 v52, v8
	v_mov_b32_e32 v53, v8
	v_mov_b32_e32 v54, v8
	v_mov_b32_e32 v55, v8
	v_mov_b32_e32 v56, v8
	v_mov_b32_e32 v57, v8
	v_mov_b32_e32 v58, v8
	v_mov_b32_e32 v59, v8
	v_mov_b32_e32 v60, v8
	v_mov_b32_e32 v61, v8
	v_mov_b32_e32 v62, v8
	v_mov_b32_e32 v63, v8
	v_mov_b32_e32 v64, v8
	v_mov_b32_e32 v65, v8
	v_mov_b32_e32 v66, v8
	v_mov_b32_e32 v67, v8
	v_mov_b32_e32 v68, v8
	v_mov_b32_e32 v69, v8
	v_mov_b32_e32 v70, v8
	v_mov_b32_e32 v71, v8
	v_mov_b32_e32 v72, v8
	v_mov_b32_e32 v73, v8
	v_mov_b32_e32 v74, v8
	v_mov_b32_e32 v75, v8
	v_mov_b32_e32 v76, v8
	v_mov_b32_e32 v77, v8
	v_mov_b32_e32 v78, v8
	v_mov_b32_e32 v79, v8
	v_mov_b32_e32 v80, v8
	v_mov_b32_e32 v81, v8
	v_mov_b32_e32 v82, v8
	v_mov_b32_e32 v83, v8
	v_mov_b32_e32 v84, v8
	v_mov_b32_e32 v85, v8
	v_mov_b32_e32 v86, v8
	v_mov_b32_e32 v87, v8
	v_mov_b32_e32 v88, v8
	v_mov_b32_e32 v89, v8
	v_mov_b32_e32 v90, v8
	v_mov_b32_e32 v91, v8
	v_mov_b32_e32 v92, v8
	v_mov_b32_e32 v93, v8
	v_mov_b32_e32 v94, v8
	v_mov_b32_e32 v95, v8
	v_mov_b32_e32 v96, v8
	v_mov_b32_e32 v97, v8
	v_mov_b32_e32 v98, v8
	v_mov_b32_e32 v99, v8
	v_mov_b32_e32 v100, v8
	v_mov_b32_e32 v101, v8
	v_mov_b32_e32 v102, v8
	v_mov_b32_e32 v103, v8
	v_mov_b32_e32 v104, v8
	v_mov_b32_e32 v105, v8
	v_mov_b32_e32 v106, v8
	v_mov_b32_e32 v107, v8
	v_mov_b32_e32 v108, v8
	v_mov_b32_e32 v109, v8
	v_mov_b32_e32 v110, v8
	v_mov_b32_e32 v111, v8
	v_mov_b32_e32 v112, v8
	v_mov_b32_e32 v113, v8
	v_mov_b32_e32 v114, v8
	v_mov_b32_e32 v115, v8
	v_mov_b32_e32 v116, v8
	v_mov_b32_e32 v117, v8
	v_mov_b32_e32 v118, v8
	v_mov_b32_e32 v119, v8
	v_mov_b32_e32 v120, v8
	v_mov_b32_e32 v121, v8
	v_mov_b32_e32 v122, v8
	v_mov_b32_e32 v123, v8
	v_mov_b32_e32 v124, v8
	v_mov_b32_e32 v125, v8
	v_mov_b32_e32 v126, v8
	v_mov_b32_e32 v127, v8
	v_mov_b32_e32 v128, v8
	v_mov_b32_e32 v129, v8
	v_mov_b32_e32 v130, v8
	v_mov_b32_e32 v131, v8
	v_mov_b32_e32 v132, v8
	v_mov_b32_e32 v133, v8
	v_mov_b32_e32 v134, v8
	v_mov_b32_e32 v135, v8
	s_barrier
	s_barrier
	ds_read_b128 v[136:139], v208
	ds_read_b128 v[140:143], v208 offset:1024
	ds_read_b128 v[144:147], v208 offset:2048
	ds_read_b128 v[148:151], v208 offset:3072
.LBB0_683:
	s_add_u32 s38, s17, s12
	s_addc_u32 s39, s56, s13
	s_add_u32 s38, s38, 0x80
	s_addc_u32 s39, s39, 0
	s_add_i32 s47, s2, 0xc000
	ds_read_b128 v[152:155], v209
	ds_read_b128 v[156:159], v209 offset:1024
	ds_read_b128 v[160:163], v210
	ds_read_b128 v[164:167], v210 offset:1024
	ds_read_b128 v[168:171], v211
	ds_read_b128 v[172:175], v211 offset:1024
	ds_read_b128 v[176:179], v226
	ds_read_b128 v[180:183], v226 offset:1024
	s_mov_b32 m0, s47
	v_lshl_add_u64 v[184:185], s[38:39], 0, v[206:207]
	s_add_i32 s46, s2, 0xe000
	global_load_lds_dwordx4 v[184:185], off
	v_lshl_add_u64 v[184:185], s[38:39], 0, v[204:205]
	s_mov_b32 m0, s46
	s_nop 0
	global_load_lds_dwordx4 v[184:185], off
	s_waitcnt lgkmcnt(8)
	s_barrier
	s_waitcnt lgkmcnt(0)
	s_setprio 1
	s_waitcnt lgkmcnt(0)
	v_mfma_f32_16x16x32_bf16 v[132:135], v[136:139], v[152:155], v[132:135]
	v_mfma_f32_16x16x32_bf16 v[128:131], v[144:147], v[152:155], v[128:131]
	v_mfma_f32_16x16x32_bf16 v[124:127], v[136:139], v[160:163], v[124:127]
	v_mfma_f32_16x16x32_bf16 v[120:123], v[144:147], v[160:163], v[120:123]
	v_mfma_f32_16x16x32_bf16 v[116:119], v[136:139], v[168:171], v[116:119]
	v_mfma_f32_16x16x32_bf16 v[112:115], v[144:147], v[168:171], v[112:115]
	v_mfma_f32_16x16x32_bf16 v[108:111], v[136:139], v[176:179], v[108:111]
	v_mfma_f32_16x16x32_bf16 v[104:107], v[144:147], v[176:179], v[104:107]
	v_mfma_f32_16x16x32_bf16 v[132:135], v[140:143], v[156:159], v[132:135]
	v_mfma_f32_16x16x32_bf16 v[128:131], v[148:151], v[156:159], v[128:131]
	v_mfma_f32_16x16x32_bf16 v[124:127], v[140:143], v[164:167], v[124:127]
	v_mfma_f32_16x16x32_bf16 v[120:123], v[148:151], v[164:167], v[120:123]
	v_mfma_f32_16x16x32_bf16 v[116:119], v[140:143], v[172:175], v[116:119]
	v_mfma_f32_16x16x32_bf16 v[112:115], v[148:151], v[172:175], v[112:115]
	v_mfma_f32_16x16x32_bf16 v[108:111], v[140:143], v[180:183], v[108:111]
	v_mfma_f32_16x16x32_bf16 v[104:107], v[148:151], v[180:183], v[104:107]
	s_setprio 0
	s_barrier
; #define LDA(dst, b, h) for (int m = 0; m < 4; ++m) for (int k = 0; k < 2; ++k) \
;     dst[m][k] = *reinterpret_cast<const bf16x8*>((char*)SA(b, h) + lds_byte(wr * 64 + m * 16 + fr, k * 32 + fq * 8))
; #define LDB(dst, b, h) for (int n = 0; n < 2; ++n) for (int k = 0; k < 2; ++k) \
;     dst[n][k] = *reinterpret_cast<const bf16x8*>((char*)SB(b, h) + lds_byte(wc * 32 + n * 16 + fr, k * 32 + fq * 8))
; #define WAIT_V(n) asm volatile("s_waitcnt vmcnt(" #n ")" ::: "memory")
; #define WAIT_L(n) asm volatile("s_waitcnt lgkmcnt(" #n ")" ::: "memory")
; #define BAR __builtin_amdgcn_s_barrier()
; #define SCHED __builtin_amdgcn_sched_barrier(0)
; template <class Epi>
; DEVI void gemm_phase(const Params& p, const u16* __restrict__ A, const u16* __restrict__ Bt, const int M, const int N, const int K, const int Msplit, const Epi& epi) {
;     ...
;       LDB(B1, 0, 1); STAGE(SB(0, 0), Bt, bcol, t + 2);
;       BAR; WAIT_L(0); MMA(0, 1, At, B1); BAR;
;       LDA(At, 0, 1); STAGE(SA(0, 0), A, brow, t + 2);
;       BAR; WAIT_L(0); MMA(1, 0, At, B0); BAR; SCHED;
;       STAGE(SB(0, 1), Bt, bcol + HALF, t + 2);
;       WAIT_V(6); BAR; MMA(1, 1, At, B1); BAR;
	s_add_u32 s45, s19, s12
	s_addc_u32 s58, s41, s13
	s_add_u32 s38, s45, 0x100
	s_addc_u32 s39, s58, 0
	s_add_i32 s44, s2, 0x10000
	ds_read_b128 v[184:187], v227
	ds_read_b128 v[188:191], v227 offset:1024
	ds_read_b128 v[192:195], v227 offset:2048
	ds_read_b128 v[196:199], v227 offset:3072
	s_mov_b32 m0, s44
	v_lshl_add_u64 v[200:201], s[38:39], 0, v[206:207]
	s_add_i32 s76, s2, 0x12000
	global_load_lds_dwordx4 v[200:201], off
	v_lshl_add_u64 v[200:201], s[38:39], 0, v[204:205]
	s_mov_b32 m0, s76
	s_nop 0
	global_load_lds_dwordx4 v[200:201], off
	s_barrier
	s_waitcnt lgkmcnt(0)
	s_setprio 1
	s_waitcnt lgkmcnt(0)
	v_mfma_f32_16x16x32_bf16 v[100:103], v[184:187], v[152:155], v[100:103]
	v_mfma_f32_16x16x32_bf16 v[96:99], v[192:195], v[152:155], v[96:99]
	v_mfma_f32_16x16x32_bf16 v[92:95], v[184:187], v[160:163], v[92:95]
	v_mfma_f32_16x16x32_bf16 v[88:91], v[192:195], v[160:163], v[88:91]
	v_mfma_f32_16x16x32_bf16 v[84:87], v[184:187], v[168:171], v[84:87]
	v_mfma_f32_16x16x32_bf16 v[80:83], v[192:195], v[168:171], v[80:83]
	v_mfma_f32_16x16x32_bf16 v[76:79], v[184:187], v[176:179], v[76:79]
	v_mfma_f32_16x16x32_bf16 v[72:75], v[192:195], v[176:179], v[72:75]
	v_mfma_f32_16x16x32_bf16 v[100:103], v[188:191], v[156:159], v[100:103]
	v_mfma_f32_16x16x32_bf16 v[96:99], v[196:199], v[156:159], v[96:99]
	v_mfma_f32_16x16x32_bf16 v[92:95], v[188:191], v[164:167], v[92:95]
	v_mfma_f32_16x16x32_bf16 v[88:91], v[196:199], v[164:167], v[88:91]
	v_mfma_f32_16x16x32_bf16 v[84:87], v[188:191], v[172:175], v[84:87]
	v_mfma_f32_16x16x32_bf16 v[80:83], v[196:199], v[172:175], v[80:83]
	v_mfma_f32_16x16x32_bf16 v[76:79], v[188:191], v[180:183], v[76:79]
	v_mfma_f32_16x16x32_bf16 v[72:75], v[196:199], v[180:183], v[72:75]
	s_setprio 0
	s_add_u32 s59, s42, s12
	s_addc_u32 s77, s43, s13
	s_add_u32 s38, s59, 0x100
	s_addc_u32 s39, s77, 0
	s_mov_b32 m0, s2
	s_barrier
	ds_read_b128 v[152:155], v209 offset:16384
	ds_read_b128 v[156:159], v209 offset:17408
	ds_read_b128 v[160:163], v210 offset:16384
	ds_read_b128 v[164:167], v210 offset:17408
	ds_read_b128 v[168:171], v211 offset:16384
	ds_read_b128 v[172:175], v211 offset:17408
	ds_read_b128 v[176:179], v226 offset:16384
	ds_read_b128 v[180:183], v226 offset:17408
	s_nop 0
	v_lshl_add_u64 v[200:201], s[38:39], 0, v[206:207]
	global_load_lds_dwordx4 v[200:201], off
	v_lshl_add_u64 v[200:201], s[38:39], 0, v[204:205]
	s_mov_b32 m0, s15
	s_nop 0
	global_load_lds_dwordx4 v[200:201], off
	s_waitcnt vmcnt(10)
	s_barrier
	s_waitcnt lgkmcnt(0)
	s_setprio 1
	s_waitcnt lgkmcnt(0)
	v_mfma_f32_16x16x32_bf16 v[68:71], v[136:139], v[152:155], v[68:71]
	v_mfma_f32_16x16x32_bf16 v[64:67], v[144:147], v[152:155], v[64:67]
	v_mfma_f32_16x16x32_bf16 v[60:63], v[136:139], v[160:163], v[60:63]
	v_mfma_f32_16x16x32_bf16 v[56:59], v[144:147], v[160:163], v[56:59]
	v_mfma_f32_16x16x32_bf16 v[52:55], v[136:139], v[168:171], v[52:55]
	v_mfma_f32_16x16x32_bf16 v[48:51], v[144:147], v[168:171], v[48:51]
	v_mfma_f32_16x16x32_bf16 v[44:47], v[136:139], v[176:179], v[44:47]
	v_mfma_f32_16x16x32_bf16 v[40:43], v[144:147], v[176:179], v[40:43]
	v_mfma_f32_16x16x32_bf16 v[68:71], v[140:143], v[156:159], v[68:71]
	v_mfma_f32_16x16x32_bf16 v[64:67], v[148:151], v[156:159], v[64:67]
	v_mfma_f32_16x16x32_bf16 v[60:63], v[140:143], v[164:167], v[60:63]
	v_mfma_f32_16x16x32_bf16 v[56:59], v[148:151], v[164:167], v[56:59]
	v_mfma_f32_16x16x32_bf16 v[52:55], v[140:143], v[172:175], v[52:55]
	v_mfma_f32_16x16x32_bf16 v[48:51], v[148:151], v[172:175], v[48:51]
	v_mfma_f32_16x16x32_bf16 v[44:47], v[140:143], v[180:183], v[44:47]
	v_mfma_f32_16x16x32_bf16 v[40:43], v[148:151], v[180:183], v[40:43]
	s_setprio 0
	s_barrier
	ds_read_b128 v[136:139], v228
	ds_read_b128 v[140:143], v228 offset:1024
	ds_read_b128 v[144:147], v228 offset:2048
	ds_read_b128 v[148:151], v228 offset:3072
	s_add_u32 s88, s48, s12
	s_addc_u32 s89, s49, s13
	s_add_u32 s54, s88, 0x100
	s_addc_u32 s55, s89, 0
	s_add_i32 s38, s2, 0x14000
	s_mov_b32 m0, s38
	v_lshl_add_u64 v[238:239], s[54:55], 0, v[206:207]
	s_add_i32 s39, s2, 0x16000
	global_load_lds_dwordx4 v[238:239], off
	v_lshl_add_u64 v[238:239], s[54:55], 0, v[204:205]
	s_mov_b32 m0, s39
	s_nop 0
	global_load_lds_dwordx4 v[238:239], off
	s_waitcnt vmcnt(6)
	s_barrier
	s_setprio 1
	v_mfma_f32_16x16x32_bf16 v[36:39], v[184:187], v[152:155], v[36:39]
	v_mfma_f32_16x16x32_bf16 v[32:35], v[192:195], v[152:155], v[32:35]
	v_mfma_f32_16x16x32_bf16 v[28:31], v[184:187], v[160:163], v[28:31]
	v_mfma_f32_16x16x32_bf16 v[24:27], v[192:195], v[160:163], v[24:27]
	v_mfma_f32_16x16x32_bf16 v[20:23], v[184:187], v[168:171], v[20:23]
	v_mfma_f32_16x16x32_bf16 v[16:19], v[192:195], v[168:171], v[16:19]
	v_mfma_f32_16x16x32_bf16 v[12:15], v[184:187], v[176:179], v[12:15]
	v_mfma_f32_16x16x32_bf16 v[8:11], v[192:195], v[176:179], v[8:11]
	v_mfma_f32_16x16x32_bf16 v[36:39], v[188:191], v[156:159], v[36:39]
	v_mfma_f32_16x16x32_bf16 v[32:35], v[196:199], v[156:159], v[32:35]
	v_mfma_f32_16x16x32_bf16 v[28:31], v[188:191], v[164:167], v[28:31]
	v_mfma_f32_16x16x32_bf16 v[24:27], v[196:199], v[164:167], v[24:27]
	v_mfma_f32_16x16x32_bf16 v[20:23], v[188:191], v[172:175], v[20:23]
	v_mfma_f32_16x16x32_bf16 v[16:19], v[196:199], v[172:175], v[16:19]
	v_mfma_f32_16x16x32_bf16 v[12:15], v[188:191], v[180:183], v[12:15]
	v_mfma_f32_16x16x32_bf16 v[8:11], v[196:199], v[180:183], v[8:11]
	s_setprio 0
	s_barrier
; #define LDA(dst, b, h) for (int m = 0; m < 4; ++m) for (int k = 0; k < 2; ++k) \
;     dst[m][k] = *reinterpret_cast<const bf16x8*>((char*)SA(b, h) + lds_byte(wr * 64 + m * 16 + fr, k * 32 + fq * 8))
; #define LDB(dst, b, h) for (int n = 0; n < 2; ++n) for (int k = 0; k < 2; ++k) \
;     dst[n][k] = *reinterpret_cast<const bf16x8*>((char*)SB(b, h) + lds_byte(wc * 32 + n * 16 + fr, k * 32 + fq * 8))
; #define WAIT_L(n) asm volatile("s_waitcnt lgkmcnt(" #n ")" ::: "memory")
; #define BAR __builtin_amdgcn_s_barrier()
; #define SCHED __builtin_amdgcn_sched_barrier(0)
; template <class Epi>
; DEVI void gemm_phase(const Params& p, const u16* __restrict__ A, const u16* __restrict__ Bt, const int M, const int N, const int K, const int Msplit, const Epi& epi) {
;     ...
;       LDB(B0, 1, 0); SCHED; LDA(At, 1, 0); STAGE(SA(0, 1), A, brow + HALF, t + 2);
;       WAIT_L(8); BAR; WAIT_L(0); MMA(0, 0, At, B0); BAR; SCHED;
;       LDB(B1, 1, 1); STAGE(SB(1, 0), Bt, bcol, t + 3);
;       BAR; WAIT_L(0); MMA(0, 1, At, B1); BAR;
;       LDA(At, 1, 1); STAGE(SA(1, 0), A, brow, t + 3);
;       BAR; WAIT_L(0); MMA(1, 0, At, B0); BAR; SCHED;
	s_add_u32 s54, s52, s12
	s_addc_u32 s55, s53, s13
	s_mov_b32 m0, s24
	ds_read_b128 v[152:155], v209 offset:32768
	ds_read_b128 v[156:159], v209 offset:33792
	ds_read_b128 v[160:163], v210 offset:32768
	ds_read_b128 v[164:167], v210 offset:33792
	ds_read_b128 v[168:171], v211 offset:32768
	ds_read_b128 v[172:175], v211 offset:33792
	ds_read_b128 v[176:179], v226 offset:32768
	ds_read_b128 v[180:183], v226 offset:33792
	s_nop 0
	v_lshl_add_u64 v[184:185], s[54:55], 0, v[206:207]
	global_load_lds_dwordx4 v[184:185], off
	v_lshl_add_u64 v[184:185], s[54:55], 0, v[204:205]
	s_mov_b32 m0, s25
	s_nop 0
	global_load_lds_dwordx4 v[184:185], off
	s_waitcnt lgkmcnt(8)
	s_barrier
	s_waitcnt lgkmcnt(0)
	s_setprio 1
	s_waitcnt lgkmcnt(0)
	v_mfma_f32_16x16x32_bf16 v[132:135], v[136:139], v[152:155], v[132:135]
	v_mfma_f32_16x16x32_bf16 v[128:131], v[144:147], v[152:155], v[128:131]
	v_mfma_f32_16x16x32_bf16 v[124:127], v[136:139], v[160:163], v[124:127]
	v_mfma_f32_16x16x32_bf16 v[120:123], v[144:147], v[160:163], v[120:123]
	v_mfma_f32_16x16x32_bf16 v[116:119], v[136:139], v[168:171], v[116:119]
	v_mfma_f32_16x16x32_bf16 v[112:115], v[144:147], v[168:171], v[112:115]
	v_mfma_f32_16x16x32_bf16 v[108:111], v[136:139], v[176:179], v[108:111]
	v_mfma_f32_16x16x32_bf16 v[104:107], v[144:147], v[176:179], v[104:107]
	v_mfma_f32_16x16x32_bf16 v[132:135], v[140:143], v[156:159], v[132:135]
	v_mfma_f32_16x16x32_bf16 v[128:131], v[148:151], v[156:159], v[128:131]
	v_mfma_f32_16x16x32_bf16 v[124:127], v[140:143], v[164:167], v[124:127]
	v_mfma_f32_16x16x32_bf16 v[120:123], v[148:151], v[164:167], v[120:123]
	v_mfma_f32_16x16x32_bf16 v[116:119], v[140:143], v[172:175], v[116:119]
	v_mfma_f32_16x16x32_bf16 v[112:115], v[148:151], v[172:175], v[112:115]
	v_mfma_f32_16x16x32_bf16 v[108:111], v[140:143], v[180:183], v[108:111]
	v_mfma_f32_16x16x32_bf16 v[104:107], v[148:151], v[180:183], v[104:107]
	s_setprio 0
	s_barrier
	s_add_u32 s54, s45, 0x180
	s_addc_u32 s55, s58, 0
	s_add_i32 s63, s2, 0x18000
	ds_read_b128 v[184:187], v229
	ds_read_b128 v[188:191], v229 offset:1024
	ds_read_b128 v[192:195], v229 offset:2048
	ds_read_b128 v[196:199], v229 offset:3072
	s_mov_b32 m0, s63
	v_lshl_add_u64 v[200:201], s[54:55], 0, v[206:207]
	s_add_i32 s62, s2, 0x1a000
	global_load_lds_dwordx4 v[200:201], off
	v_lshl_add_u64 v[200:201], s[54:55], 0, v[204:205]
	s_mov_b32 m0, s62
	s_nop 0
	global_load_lds_dwordx4 v[200:201], off
	s_barrier
	s_waitcnt lgkmcnt(0)
	s_setprio 1
	s_waitcnt lgkmcnt(0)
	v_mfma_f32_16x16x32_bf16 v[100:103], v[184:187], v[152:155], v[100:103]
	v_mfma_f32_16x16x32_bf16 v[96:99], v[192:195], v[152:155], v[96:99]
	v_mfma_f32_16x16x32_bf16 v[92:95], v[184:187], v[160:163], v[92:95]
	v_mfma_f32_16x16x32_bf16 v[88:91], v[192:195], v[160:163], v[88:91]
	v_mfma_f32_16x16x32_bf16 v[84:87], v[184:187], v[168:171], v[84:87]
	v_mfma_f32_16x16x32_bf16 v[80:83], v[192:195], v[168:171], v[80:83]
	v_mfma_f32_16x16x32_bf16 v[76:79], v[184:187], v[176:179], v[76:79]
	v_mfma_f32_16x16x32_bf16 v[72:75], v[192:195], v[176:179], v[72:75]
	v_mfma_f32_16x16x32_bf16 v[100:103], v[188:191], v[156:159], v[100:103]
	v_mfma_f32_16x16x32_bf16 v[96:99], v[196:199], v[156:159], v[96:99]
	v_mfma_f32_16x16x32_bf16 v[92:95], v[188:191], v[164:167], v[92:95]
	v_mfma_f32_16x16x32_bf16 v[88:91], v[196:199], v[164:167], v[88:91]
	v_mfma_f32_16x16x32_bf16 v[84:87], v[188:191], v[172:175], v[84:87]
	v_mfma_f32_16x16x32_bf16 v[80:83], v[196:199], v[172:175], v[80:83]
	v_mfma_f32_16x16x32_bf16 v[76:79], v[188:191], v[180:183], v[76:79]
	v_mfma_f32_16x16x32_bf16 v[72:75], v[196:199], v[180:183], v[72:75]
	s_setprio 0
	s_add_u32 s54, s59, 0x180
	s_addc_u32 s55, s77, 0
	s_mov_b32 m0, s26
	s_barrier
	ds_read_b128 v[152:155], v209 offset:49152
	ds_read_b128 v[156:159], v209 offset:50176
	ds_read_b128 v[160:163], v210 offset:49152
	ds_read_b128 v[164:167], v210 offset:50176
	ds_read_b128 v[168:171], v211 offset:49152
	ds_read_b128 v[172:175], v211 offset:50176
	ds_read_b128 v[176:179], v226 offset:49152
	ds_read_b128 v[180:183], v226 offset:50176
	s_nop 0
	v_lshl_add_u64 v[200:201], s[54:55], 0, v[206:207]
	global_load_lds_dwordx4 v[200:201], off
	v_lshl_add_u64 v[200:201], s[54:55], 0, v[204:205]
	s_mov_b32 m0, s27
	s_nop 0
	global_load_lds_dwordx4 v[200:201], off
	s_waitcnt vmcnt(10)
	s_barrier
	s_waitcnt lgkmcnt(0)
	s_setprio 1
	s_waitcnt lgkmcnt(0)
	v_mfma_f32_16x16x32_bf16 v[68:71], v[136:139], v[152:155], v[68:71]
	v_mfma_f32_16x16x32_bf16 v[64:67], v[144:147], v[152:155], v[64:67]
	v_mfma_f32_16x16x32_bf16 v[60:63], v[136:139], v[160:163], v[60:63]
	v_mfma_f32_16x16x32_bf16 v[56:59], v[144:147], v[160:163], v[56:59]
	v_mfma_f32_16x16x32_bf16 v[52:55], v[136:139], v[168:171], v[52:55]
	v_mfma_f32_16x16x32_bf16 v[48:51], v[144:147], v[168:171], v[48:51]
	v_mfma_f32_16x16x32_bf16 v[44:47], v[136:139], v[176:179], v[44:47]
	v_mfma_f32_16x16x32_bf16 v[40:43], v[144:147], v[176:179], v[40:43]
	v_mfma_f32_16x16x32_bf16 v[68:71], v[140:143], v[156:159], v[68:71]
	v_mfma_f32_16x16x32_bf16 v[64:67], v[148:151], v[156:159], v[64:67]
	v_mfma_f32_16x16x32_bf16 v[60:63], v[140:143], v[164:167], v[60:63]
	v_mfma_f32_16x16x32_bf16 v[56:59], v[148:151], v[164:167], v[56:59]
	v_mfma_f32_16x16x32_bf16 v[52:55], v[140:143], v[172:175], v[52:55]
	v_mfma_f32_16x16x32_bf16 v[48:51], v[148:151], v[172:175], v[48:51]
	v_mfma_f32_16x16x32_bf16 v[44:47], v[140:143], v[180:183], v[44:47]
	v_mfma_f32_16x16x32_bf16 v[40:43], v[148:151], v[180:183], v[40:43]
	s_setprio 0
	s_barrier
; #define LDA(dst, b, h) for (int m = 0; m < 4; ++m) for (int k = 0; k < 2; ++k) \
;     dst[m][k] = *reinterpret_cast<const bf16x8*>((char*)SA(b, h) + lds_byte(wr * 64 + m * 16 + fr, k * 32 + fq * 8))
; #define LDB(dst, b, h) for (int n = 0; n < 2; ++n) for (int k = 0; k < 2; ++k) \
;     dst[n][k] = *reinterpret_cast<const bf16x8*>((char*)SB(b, h) + lds_byte(wc * 32 + n * 16 + fr, k * 32 + fq * 8))
; #define WAIT_V(n) asm volatile("s_waitcnt vmcnt(" #n ")" ::: "memory")
; #define WAIT_L(n) asm volatile("s_waitcnt lgkmcnt(" #n ")" ::: "memory")
; #define BAR __builtin_amdgcn_s_barrier()
; template <class Epi>
; DEVI void gemm_phase(const Params& p, const u16* __restrict__ A, const u16* __restrict__ Bt, const int M, const int N, const int K, const int Msplit, const Epi& epi) {
;     ...
;       STAGE(SB(1, 1), Bt, bcol + HALF, t + 3);
;       WAIT_V(6); BAR; MMA(1, 1, At, B1); BAR;
;     }
;     { LDB(B0, 0, 0); LDA(At, 0, 0); STAGE(SA(1, 1), A, brow + HALF, nt - 1);
;       BAR; WAIT_L(0); MMA(0, 0, At, B0); BAR;
;       LDB(B1, 0, 1); BAR; WAIT_L(0); MMA(0, 1, At, B1); BAR;
;       LDA(At, 0, 1); WAIT_V(4); BAR; WAIT_L(0); MMA(1, 0, At, B0); MMA(1, 1, At, B1); BAR; }
	ds_read_b128 v[136:139], v208
	ds_read_b128 v[140:143], v208 offset:1024
	ds_read_b128 v[144:147], v208 offset:2048
	ds_read_b128 v[148:151], v208 offset:3072
	s_add_u32 s54, s88, 0x180
	s_addc_u32 s55, s89, 0
	s_add_i32 s45, s2, 0x1c000
	s_mov_b32 m0, s45
	v_lshl_add_u64 v[238:239], s[54:55], 0, v[206:207]
	global_load_lds_dwordx4 v[238:239], off
	v_lshl_add_u64 v[238:239], s[54:55], 0, v[204:205]
	s_add_i32 s54, s2, 0x1e000
	s_mov_b32 m0, s54
	s_nop 0
	global_load_lds_dwordx4 v[238:239], off
	s_waitcnt vmcnt(6)
	s_barrier
	s_setprio 1
	v_mfma_f32_16x16x32_bf16 v[36:39], v[184:187], v[152:155], v[36:39]
	v_mfma_f32_16x16x32_bf16 v[32:35], v[192:195], v[152:155], v[32:35]
	v_mfma_f32_16x16x32_bf16 v[28:31], v[184:187], v[160:163], v[28:31]
	v_mfma_f32_16x16x32_bf16 v[24:27], v[192:195], v[160:163], v[24:27]
	v_mfma_f32_16x16x32_bf16 v[20:23], v[184:187], v[168:171], v[20:23]
	v_mfma_f32_16x16x32_bf16 v[16:19], v[192:195], v[168:171], v[16:19]
	v_mfma_f32_16x16x32_bf16 v[12:15], v[184:187], v[176:179], v[12:15]
	v_mfma_f32_16x16x32_bf16 v[8:11], v[192:195], v[176:179], v[8:11]
	v_mfma_f32_16x16x32_bf16 v[36:39], v[188:191], v[156:159], v[36:39]
	v_mfma_f32_16x16x32_bf16 v[32:35], v[196:199], v[156:159], v[32:35]
	v_mfma_f32_16x16x32_bf16 v[28:31], v[188:191], v[164:167], v[28:31]
	v_mfma_f32_16x16x32_bf16 v[24:27], v[196:199], v[164:167], v[24:27]
	v_mfma_f32_16x16x32_bf16 v[20:23], v[188:191], v[172:175], v[20:23]
	v_mfma_f32_16x16x32_bf16 v[16:19], v[196:199], v[172:175], v[16:19]
	v_mfma_f32_16x16x32_bf16 v[12:15], v[188:191], v[180:183], v[12:15]
	v_mfma_f32_16x16x32_bf16 v[8:11], v[196:199], v[180:183], v[8:11]
	s_setprio 0
	s_add_u32 s12, s12, 0x100
	s_addc_u32 s13, s13, 0
	s_add_i32 s57, s57, 2
	s_cmp_lt_u32 s57, 12
	s_barrier
	s_cbranch_scc1 .LBB0_683
	s_add_u32 s12, s22, 0x780
	s_addc_u32 s13, s23, 0
	s_mov_b32 m0, s47
	ds_read_b128 v[164:167], v208
	ds_read_b128 v[168:171], v208 offset:1024
	ds_read_b128 v[172:175], v208 offset:2048
	ds_read_b128 v[176:179], v208 offset:3072
	ds_read_b128 v[136:139], v209
	ds_read_b128 v[140:143], v209 offset:1024
	ds_read_b128 v[144:147], v210
	ds_read_b128 v[148:151], v210 offset:1024
	ds_read_b128 v[152:155], v211
	ds_read_b128 v[156:159], v211 offset:1024
	ds_read_b128 v[160:163], v226
	ds_read_b128 v[180:183], v226 offset:1024
	s_nop 0
	v_lshl_add_u64 v[184:185], s[12:13], 0, v[206:207]
	global_load_lds_dwordx4 v[184:185], off
	v_lshl_add_u64 v[184:185], s[12:13], 0, v[204:205]
	s_mov_b32 m0, s46
	s_nop 0
	global_load_lds_dwordx4 v[184:185], off
	s_barrier
	s_waitcnt lgkmcnt(0)
	s_setprio 1
	s_waitcnt lgkmcnt(0)
	v_mfma_f32_16x16x32_bf16 v[132:135], v[164:167], v[136:139], v[132:135]
	v_mfma_f32_16x16x32_bf16 v[128:131], v[172:175], v[136:139], v[128:131]
	v_mfma_f32_16x16x32_bf16 v[124:127], v[164:167], v[144:147], v[124:127]
	v_mfma_f32_16x16x32_bf16 v[120:123], v[172:175], v[144:147], v[120:123]
	v_mfma_f32_16x16x32_bf16 v[116:119], v[164:167], v[152:155], v[116:119]
	v_mfma_f32_16x16x32_bf16 v[112:115], v[172:175], v[152:155], v[112:115]
	v_mfma_f32_16x16x32_bf16 v[108:111], v[164:167], v[160:163], v[108:111]
	v_mfma_f32_16x16x32_bf16 v[104:107], v[172:175], v[160:163], v[104:107]
	v_mfma_f32_16x16x32_bf16 v[132:135], v[168:171], v[140:143], v[132:135]
	v_mfma_f32_16x16x32_bf16 v[184:187], v[176:179], v[140:143], v[128:131]
	v_mfma_f32_16x16x32_bf16 v[124:127], v[168:171], v[148:151], v[124:127]
	v_mfma_f32_16x16x32_bf16 v[188:191], v[176:179], v[148:151], v[120:123]
	v_mfma_f32_16x16x32_bf16 v[116:119], v[168:171], v[156:159], v[116:119]
	v_mfma_f32_16x16x32_bf16 v[192:195], v[176:179], v[156:159], v[112:115]
	v_mfma_f32_16x16x32_bf16 v[108:111], v[168:171], v[180:183], v[108:111]
	v_mfma_f32_16x16x32_bf16 v[196:199], v[176:179], v[180:183], v[104:107]
	s_setprio 0
	s_barrier
	s_nop 0
	ds_read_b128 v[104:107], v227
	ds_read_b128 v[112:115], v227 offset:1024
	ds_read_b128 v[120:123], v227 offset:2048
	ds_read_b128 v[128:131], v227 offset:3072
	s_barrier
	s_waitcnt lgkmcnt(0)
	s_setprio 1
	s_waitcnt lgkmcnt(0)
	v_mfma_f32_16x16x32_bf16 v[100:103], v[104:107], v[136:139], v[100:103]
	v_mfma_f32_16x16x32_bf16 v[96:99], v[120:123], v[136:139], v[96:99]
	v_mfma_f32_16x16x32_bf16 v[92:95], v[104:107], v[144:147], v[92:95]
	v_mfma_f32_16x16x32_bf16 v[88:91], v[120:123], v[144:147], v[88:91]
	v_mfma_f32_16x16x32_bf16 v[84:87], v[104:107], v[152:155], v[84:87]
	v_mfma_f32_16x16x32_bf16 v[80:83], v[120:123], v[152:155], v[80:83]
	v_mfma_f32_16x16x32_bf16 v[76:79], v[104:107], v[160:163], v[76:79]
	v_mfma_f32_16x16x32_bf16 v[72:75], v[120:123], v[160:163], v[72:75]
	v_mfma_f32_16x16x32_bf16 v[100:103], v[112:115], v[140:143], v[100:103]
	v_mfma_f32_16x16x32_bf16 v[136:139], v[128:131], v[140:143], v[96:99]
	v_mfma_f32_16x16x32_bf16 v[92:95], v[112:115], v[148:151], v[92:95]
	v_mfma_f32_16x16x32_bf16 v[140:143], v[128:131], v[148:151], v[88:91]
	v_mfma_f32_16x16x32_bf16 v[84:87], v[112:115], v[156:159], v[84:87]
	v_mfma_f32_16x16x32_bf16 v[144:147], v[128:131], v[156:159], v[80:83]
	v_mfma_f32_16x16x32_bf16 v[76:79], v[112:115], v[180:183], v[76:79]
	v_mfma_f32_16x16x32_bf16 v[148:151], v[128:131], v[180:183], v[72:75]
	s_setprio 0
	s_barrier
; #define LDA(dst, b, h) for (int m = 0; m < 4; ++m) for (int k = 0; k < 2; ++k) \
;     dst[m][k] = *reinterpret_cast<const bf16x8*>((char*)SA(b, h) + lds_byte(wr * 64 + m * 16 + fr, k * 32 + fq * 8))
; #define LDB(dst, b, h) for (int n = 0; n < 2; ++n) for (int k = 0; k < 2; ++k) \
;     dst[n][k] = *reinterpret_cast<const bf16x8*>((char*)SB(b, h) + lds_byte(wc * 32 + n * 16 + fr, k * 32 + fq * 8))
; #define WAIT_V(n) asm volatile("s_waitcnt vmcnt(" #n ")" ::: "memory")
; #define WAIT_L(n) asm volatile("s_waitcnt lgkmcnt(" #n ")" ::: "memory")
; #define BAR __builtin_amdgcn_s_barrier()
; #define PRO_K0(brow_, bcol_) do { STAGE(SB(0, 0), Bt, bcol_, 0); STAGE(SA(0, 0), A, brow_, 0); STAGE(SB(0, 1), Bt, (bcol_) + HALF, 0); STAGE(SA(0, 1), A, (brow_) + HALF, 0); } while (0)
; template <class Epi>
; DEVI void gemm_phase(const Params& p, const u16* __restrict__ A, const u16* __restrict__ Bt, const int M, const int N, const int K, const int Msplit, const Epi& epi) {
;     ...
;       LDA(At, 0, 1); WAIT_V(4); BAR; WAIT_L(0); MMA(1, 0, At, B0); MMA(1, 1, At, B1); BAR; }
;     { LDB(B0, 1, 0); LDA(At, 1, 0); WAIT_V(2); BAR;
;       if (have2) { const u16* Asv = A; const u16* Bsv = Bt; A = An; Bt = Bn; PRO_K0(pm * BM, pn * BM); A = Asv; Bt = Bsv; }
	s_nop 0
	ds_read_b128 v[72:75], v209 offset:16384
	ds_read_b128 v[80:83], v209 offset:17408
	ds_read_b128 v[88:91], v210 offset:16384
	ds_read_b128 v[96:99], v210 offset:17408
	ds_read_b128 v[180:183], v211 offset:16384
	ds_read_b128 v[200:203], v211 offset:17408
	ds_read_b128 v[246:249], v226 offset:16384
	ds_read_b128 v[214:217], v226 offset:17408
	s_waitcnt vmcnt(4)
	s_barrier
	s_waitcnt lgkmcnt(0)
	s_setprio 1
	s_waitcnt lgkmcnt(0)
	v_mfma_f32_16x16x32_bf16 v[68:71], v[164:167], v[72:75], v[68:71]
	v_mfma_f32_16x16x32_bf16 v[64:67], v[172:175], v[72:75], v[64:67]
	v_mfma_f32_16x16x32_bf16 v[60:63], v[164:167], v[88:91], v[60:63]
	v_mfma_f32_16x16x32_bf16 v[56:59], v[172:175], v[88:91], v[56:59]
	v_mfma_f32_16x16x32_bf16 v[52:55], v[164:167], v[180:183], v[52:55]
	v_mfma_f32_16x16x32_bf16 v[48:51], v[172:175], v[180:183], v[48:51]
	v_mfma_f32_16x16x32_bf16 v[44:47], v[164:167], v[246:249], v[44:47]
	v_mfma_f32_16x16x32_bf16 v[40:43], v[172:175], v[246:249], v[40:43]
	v_mfma_f32_16x16x32_bf16 v[68:71], v[168:171], v[80:83], v[68:71]
	v_mfma_f32_16x16x32_bf16 v[152:155], v[176:179], v[80:83], v[64:67]
	v_mfma_f32_16x16x32_bf16 v[60:63], v[168:171], v[96:99], v[60:63]
	v_mfma_f32_16x16x32_bf16 v[156:159], v[176:179], v[96:99], v[56:59]
	v_mfma_f32_16x16x32_bf16 v[52:55], v[168:171], v[200:203], v[52:55]
	v_mfma_f32_16x16x32_bf16 v[160:163], v[176:179], v[200:203], v[48:51]
	v_mfma_f32_16x16x32_bf16 v[44:47], v[168:171], v[214:217], v[44:47]
	v_mfma_f32_16x16x32_bf16 v[164:167], v[176:179], v[214:217], v[40:43]
	s_setprio 0
	s_setprio 1
	v_mfma_f32_16x16x32_bf16 v[36:39], v[104:107], v[72:75], v[36:39]
	v_mfma_f32_16x16x32_bf16 v[32:35], v[120:123], v[72:75], v[32:35]
	v_mfma_f32_16x16x32_bf16 v[28:31], v[104:107], v[88:91], v[28:31]
	v_mfma_f32_16x16x32_bf16 v[24:27], v[120:123], v[88:91], v[24:27]
	v_mfma_f32_16x16x32_bf16 v[20:23], v[104:107], v[180:183], v[20:23]
	v_mfma_f32_16x16x32_bf16 v[16:19], v[120:123], v[180:183], v[16:19]
	v_mfma_f32_16x16x32_bf16 v[12:15], v[104:107], v[246:249], v[12:15]
	v_mfma_f32_16x16x32_bf16 v[8:11], v[120:123], v[246:249], v[8:11]
	v_mfma_f32_16x16x32_bf16 v[36:39], v[112:115], v[80:83], v[36:39]
	v_mfma_f32_16x16x32_bf16 v[168:171], v[128:131], v[80:83], v[32:35]
	v_mfma_f32_16x16x32_bf16 v[28:31], v[112:115], v[96:99], v[28:31]
	v_mfma_f32_16x16x32_bf16 v[172:175], v[128:131], v[96:99], v[24:27]
	v_mfma_f32_16x16x32_bf16 v[20:23], v[112:115], v[200:203], v[20:23]
	v_mfma_f32_16x16x32_bf16 v[176:179], v[128:131], v[200:203], v[16:19]
	v_mfma_f32_16x16x32_bf16 v[12:15], v[112:115], v[214:217], v[12:15]
	v_mfma_f32_16x16x32_bf16 v[180:183], v[128:131], v[214:217], v[8:11]
	s_setprio 0
	s_barrier
	s_nop 0
	ds_read_b128 v[8:11], v228
	ds_read_b128 v[16:19], v228 offset:1024
	ds_read_b128 v[24:27], v228 offset:2048
	ds_read_b128 v[32:35], v228 offset:3072
	ds_read_b128 v[88:91], v209 offset:32768
	ds_read_b128 v[200:203], v209 offset:33792
	ds_read_b128 v[72:75], v210 offset:32768
	ds_read_b128 v[80:83], v210 offset:33792
	ds_read_b128 v[56:59], v211 offset:32768
	ds_read_b128 v[64:67], v211 offset:33792
	ds_read_b128 v[40:43], v226 offset:32768
	ds_read_b128 v[48:51], v226 offset:33792
	s_waitcnt vmcnt(2)
	v_cndmask_b32_e64 v96, 0, 1, s[10:11]
	v_cmp_ne_u32_e64 s[12:13], 1, v96
	s_andn2_b64 vcc, exec, s[10:11]
	s_barrier
	s_cbranch_vccnz .LBB0_686
	s_lshl_b32 s10, s36, 8
	s_mov_b32 s11, s91
	s_lshl_b64 s[22:23], s[10:11], 11
	s_add_u32 s22, s0, s22
	s_addc_u32 s23, s1, s23
	s_mov_b32 m0, s44
	s_nop 0
	v_lshl_add_u64 v[96:97], s[22:23], 0, v[206:207]
	global_load_lds_dwordx4 v[96:97], off
	v_lshl_add_u64 v[96:97], s[22:23], 0, v[204:205]
	s_lshl_b32 s22, s40, 8
	s_mov_b32 s23, s91
	s_lshl_b64 s[42:43], s[22:23], 11
	s_add_u32 s42, s68, s42
	s_addc_u32 s43, s69, s43
	s_bitset1_b32 s10, 7
	s_mov_b32 m0, s76
	s_lshl_b64 s[10:11], s[10:11], 11
	global_load_lds_dwordx4 v[96:97], off
	s_mov_b32 m0, s2
	v_lshl_add_u64 v[96:97], s[42:43], 0, v[206:207]
	s_add_u32 s10, s0, s10
	global_load_lds_dwordx4 v[96:97], off
	v_lshl_add_u64 v[96:97], s[42:43], 0, v[204:205]
	s_mov_b32 m0, s15
	s_addc_u32 s11, s1, s11
	global_load_lds_dwordx4 v[96:97], off
	s_mov_b32 m0, s38
	v_lshl_add_u64 v[96:97], s[10:11], 0, v[206:207]
	global_load_lds_dwordx4 v[96:97], off
	v_lshl_add_u64 v[96:97], s[10:11], 0, v[204:205]
	s_or_b32 s10, s22, 0x80
	s_mov_b32 s11, s91
	s_lshl_b64 s[10:11], s[10:11], 11
	s_add_u32 s10, s68, s10
	s_mov_b32 m0, s39
	s_addc_u32 s11, s69, s11
	global_load_lds_dwordx4 v[96:97], off
	s_mov_b32 m0, s24
	v_lshl_add_u64 v[96:97], s[10:11], 0, v[206:207]
	global_load_lds_dwordx4 v[96:97], off
	v_lshl_add_u64 v[96:97], s[10:11], 0, v[204:205]
	s_mov_b32 m0, s25
	s_nop 0
	global_load_lds_dwordx4 v[96:97], off

; #define LDA(dst, b, h) for (int m = 0; m < 4; ++m) for (int k = 0; k < 2; ++k) \
;     dst[m][k] = *reinterpret_cast<const bf16x8*>((char*)SA(b, h) + lds_byte(wr * 64 + m * 16 + fr, k * 32 + fq * 8))
; #define LDB(dst, b, h) for (int n = 0; n < 2; ++n) for (int k = 0; k < 2; ++k) \
;     dst[n][k] = *reinterpret_cast<const bf16x8*>((char*)SB(b, h) + lds_byte(wc * 32 + n * 16 + fr, k * 32 + fq * 8))
; #define WAIT_V(n) asm volatile("s_waitcnt vmcnt(" #n ")" ::: "memory")
; #define WAIT_L(n) asm volatile("s_waitcnt lgkmcnt(" #n ")" ::: "memory")
; #define BAR __builtin_amdgcn_s_barrier()
; #define SCHED __builtin_amdgcn_sched_barrier(0)
; template <class Epi>
; DEVI void gemm_phase(const Params& p, const u16* __restrict__ A, const u16* __restrict__ Bt, const int M, const int N, const int K, const int Msplit, const Epi& epi) {
;     ...
;     f32x4 acc[2][2][4][2] = {};
;     bf16x8 At[4][2], B0[2][2], B1[2][2];
;     if (it == 0) { WAIT_V(0); } else { if constexpr (Epi::NST == 16) WAIT_V(16); else if constexpr (Epi::NST == 32) WAIT_V(32); else WAIT_V(0); }
;     if (wr == 1) BAR;
;     BAR;
;     BAR;
;     for (int t = 0; t < nt - 2; t += 2) {
;       LDB(B0, 0, 0); SCHED; LDA(At, 0, 0); STAGE(SA(1, 1), A, brow + HALF, t + 1);
;       WAIT_L(8); BAR; WAIT_L(0); MMA(0, 0, At, B0); BAR; SCHED;
.LBB0_812:
	s_or_b64 exec, exec, s[12:13]
	s_lshl_b32 s18, s1, 8
	s_or_b32 s12, s18, 0x80
	s_xor_b64 s[16:17], s[10:11], -1
	s_lshl_b32 s42, s2, 8
	s_add_i32 s27, s24, -2
	s_mul_hi_i32 s13, s12, 0x1600
	s_mulk_i32 s12, 0x1600
	s_add_u32 s25, s20, s12
	s_addc_u32 s26, s21, s13
	s_mul_i32 s12, s2, 0x160000
	s_mul_hi_i32 s13, s42, 0x1600
	s_add_u32 s43, s22, s12
	s_addc_u32 s52, s23, s13
	s_ashr_i32 s19, s18, 31
	s_mul_i32 s12, s1, 0x160000
	s_mul_hi_i32 s13, s18, 0x1600
	s_add_u32 s20, s20, s12
	s_addc_u32 s21, s21, s13
	s_or_b32 s12, s42, 0x80
	s_mul_hi_i32 s13, s12, 0x1600
	s_mulk_i32 s12, 0x1600
	s_add_u32 s22, s22, s12
	s_waitcnt lgkmcnt(0)
	v_mov_b32_e32 v16, 0
	s_addc_u32 s23, s23, s13
	s_mov_b32 s53, 0
	s_mov_b64 s[12:13], 0
	v_mov_b32_e32 v17, v16
	v_mov_b32_e32 v18, v16
	v_mov_b32_e32 v19, v16
	v_mov_b32_e32 v20, v16
	v_mov_b32_e32 v21, v16
	v_mov_b32_e32 v22, v16
	v_mov_b32_e32 v23, v16
	v_mov_b32_e32 v24, v16
	v_mov_b32_e32 v25, v16
	v_mov_b32_e32 v26, v16
	v_mov_b32_e32 v27, v16
	v_mov_b32_e32 v28, v16
	v_mov_b32_e32 v29, v16
	v_mov_b32_e32 v30, v16
	v_mov_b32_e32 v31, v16
	v_mov_b32_e32 v32, v16
	v_mov_b32_e32 v33, v16
	v_mov_b32_e32 v34, v16
	v_mov_b32_e32 v35, v16
	v_mov_b32_e32 v36, v16
	v_mov_b32_e32 v37, v16
	v_mov_b32_e32 v38, v16
	v_mov_b32_e32 v39, v16
	v_mov_b32_e32 v40, v16
	v_mov_b32_e32 v41, v16
	v_mov_b32_e32 v42, v16
	v_mov_b32_e32 v43, v16
	v_mov_b32_e32 v44, v16
	v_mov_b32_e32 v45, v16
	v_mov_b32_e32 v46, v16
	v_mov_b32_e32 v47, v16
	v_mov_b32_e32 v48, v16
	v_mov_b32_e32 v49, v16
	v_mov_b32_e32 v50, v16
	v_mov_b32_e32 v51, v16
	v_mov_b32_e32 v52, v16
	v_mov_b32_e32 v53, v16
	v_mov_b32_e32 v54, v16
	v_mov_b32_e32 v55, v16
	v_mov_b32_e32 v56, v16
	v_mov_b32_e32 v57, v16
	v_mov_b32_e32 v58, v16
	v_mov_b32_e32 v59, v16
	v_mov_b32_e32 v60, v16
	v_mov_b32_e32 v61, v16
	v_mov_b32_e32 v62, v16
	v_mov_b32_e32 v63, v16
	v_mov_b32_e32 v64, v16
	v_mov_b32_e32 v65, v16
	v_mov_b32_e32 v66, v16
	v_mov_b32_e32 v67, v16
	v_mov_b32_e32 v68, v16
	v_mov_b32_e32 v69, v16
	v_mov_b32_e32 v70, v16
	v_mov_b32_e32 v71, v16
	v_mov_b32_e32 v72, v16
	v_mov_b32_e32 v73, v16
	v_mov_b32_e32 v74, v16
	v_mov_b32_e32 v75, v16
	v_mov_b32_e32 v76, v16
	v_mov_b32_e32 v77, v16
	v_mov_b32_e32 v78, v16
	v_mov_b32_e32 v79, v16
	v_mov_b32_e32 v80, v16
	v_mov_b32_e32 v81, v16
	v_mov_b32_e32 v82, v16
	v_mov_b32_e32 v83, v16
	v_mov_b32_e32 v84, v16
	v_mov_b32_e32 v85, v16
	v_mov_b32_e32 v86, v16
	v_mov_b32_e32 v87, v16
	v_mov_b32_e32 v88, v16
	v_mov_b32_e32 v89, v16
	v_mov_b32_e32 v90, v16
	v_mov_b32_e32 v91, v16
	v_mov_b32_e32 v92, v16
	v_mov_b32_e32 v93, v16
	v_mov_b32_e32 v94, v16
	v_mov_b32_e32 v95, v16
	v_mov_b32_e32 v96, v16
	v_mov_b32_e32 v97, v16
	v_mov_b32_e32 v98, v16
	v_mov_b32_e32 v99, v16
	v_mov_b32_e32 v100, v16
	v_mov_b32_e32 v101, v16
	v_mov_b32_e32 v102, v16
	v_mov_b32_e32 v103, v16
	v_mov_b32_e32 v104, v16
	v_mov_b32_e32 v105, v16
	v_mov_b32_e32 v106, v16
	v_mov_b32_e32 v107, v16
	v_mov_b32_e32 v108, v16
	v_mov_b32_e32 v109, v16
	v_mov_b32_e32 v110, v16
	v_mov_b32_e32 v111, v16
	v_mov_b32_e32 v112, v16
	v_mov_b32_e32 v113, v16
	v_mov_b32_e32 v114, v16
	v_mov_b32_e32 v115, v16
	v_mov_b32_e32 v116, v16
	v_mov_b32_e32 v117, v16
	v_mov_b32_e32 v118, v16
	v_mov_b32_e32 v119, v16
	v_mov_b32_e32 v120, v16
	v_mov_b32_e32 v121, v16
	v_mov_b32_e32 v122, v16
	v_mov_b32_e32 v123, v16
	v_mov_b32_e32 v124, v16
	v_mov_b32_e32 v125, v16
	v_mov_b32_e32 v126, v16
	v_mov_b32_e32 v127, v16
	v_mov_b32_e32 v128, v16
	v_mov_b32_e32 v129, v16
	v_mov_b32_e32 v130, v16
	v_mov_b32_e32 v131, v16
	v_mov_b32_e32 v132, v16
	v_mov_b32_e32 v133, v16
	v_mov_b32_e32 v134, v16
	v_mov_b32_e32 v135, v16
	v_mov_b32_e32 v136, v16
	v_mov_b32_e32 v137, v16
	v_mov_b32_e32 v138, v16
	v_mov_b32_e32 v139, v16
	v_mov_b32_e32 v140, v16
	v_mov_b32_e32 v141, v16
	v_mov_b32_e32 v142, v16
	v_mov_b32_e32 v143, v16
	s_barrier
	s_barrier
	ds_read_b128 v[144:147], v246
	ds_read_b128 v[148:151], v246 offset:1024
	ds_read_b128 v[152:155], v246 offset:2048
	ds_read_b128 v[156:159], v246 offset:3072
.LBB0_813:
	s_add_u32 s46, s25, s12
	s_addc_u32 s55, s26, s13
	s_add_u32 s38, s46, 0x80
	s_addc_u32 s39, s55, 0
	s_add_i32 s56, s78, 0
	s_add_i32 s90, s56, 0xc000
	ds_read_b128 v[160:163], v247
	ds_read_b128 v[164:167], v247 offset:1024
	ds_read_b128 v[168:171], v248
	ds_read_b128 v[172:175], v248 offset:1024
	ds_read_b128 v[176:179], v249
	ds_read_b128 v[180:183], v249 offset:1024
	ds_read_b128 v[184:187], v250
	ds_read_b128 v[188:191], v250 offset:1024
	s_mov_b32 m0, s90
	v_lshl_add_u64 v[192:193], s[38:39], 0, v[226:227]
	s_add_i32 s47, s56, 0xe000
	global_load_lds_dwordx4 v[192:193], off
	v_lshl_add_u64 v[192:193], s[38:39], 0, v[228:229]
	s_mov_b32 m0, s47
	s_nop 0
	global_load_lds_dwordx4 v[192:193], off
	s_waitcnt lgkmcnt(8)
	s_barrier
	s_waitcnt lgkmcnt(0)
	s_setprio 1
	s_waitcnt lgkmcnt(0)
	v_mfma_f32_16x16x32_bf16 v[140:143], v[144:147], v[160:163], v[140:143]
	v_mfma_f32_16x16x32_bf16 v[136:139], v[152:155], v[160:163], v[136:139]
	v_mfma_f32_16x16x32_bf16 v[132:135], v[144:147], v[168:171], v[132:135]
	v_mfma_f32_16x16x32_bf16 v[128:131], v[152:155], v[168:171], v[128:131]
	v_mfma_f32_16x16x32_bf16 v[124:127], v[144:147], v[176:179], v[124:127]
	v_mfma_f32_16x16x32_bf16 v[120:123], v[152:155], v[176:179], v[120:123]
	v_mfma_f32_16x16x32_bf16 v[116:119], v[144:147], v[184:187], v[116:119]
	v_mfma_f32_16x16x32_bf16 v[112:115], v[152:155], v[184:187], v[112:115]
	v_mfma_f32_16x16x32_bf16 v[140:143], v[148:151], v[164:167], v[140:143]
	v_mfma_f32_16x16x32_bf16 v[136:139], v[156:159], v[164:167], v[136:139]
	v_mfma_f32_16x16x32_bf16 v[132:135], v[148:151], v[172:175], v[132:135]
	v_mfma_f32_16x16x32_bf16 v[128:131], v[156:159], v[172:175], v[128:131]
	v_mfma_f32_16x16x32_bf16 v[124:127], v[148:151], v[180:183], v[124:127]
	v_mfma_f32_16x16x32_bf16 v[120:123], v[156:159], v[180:183], v[120:123]
	v_mfma_f32_16x16x32_bf16 v[116:119], v[148:151], v[188:191], v[116:119]
	v_mfma_f32_16x16x32_bf16 v[112:115], v[156:159], v[188:191], v[112:115]
	s_setprio 0
	s_barrier
; #define LDA(dst, b, h) for (int m = 0; m < 4; ++m) for (int k = 0; k < 2; ++k) \
;     dst[m][k] = *reinterpret_cast<const bf16x8*>((char*)SA(b, h) + lds_byte(wr * 64 + m * 16 + fr, k * 32 + fq * 8))
; #define LDB(dst, b, h) for (int n = 0; n < 2; ++n) for (int k = 0; k < 2; ++k) \
;     dst[n][k] = *reinterpret_cast<const bf16x8*>((char*)SB(b, h) + lds_byte(wc * 32 + n * 16 + fr, k * 32 + fq * 8))
; #define WAIT_V(n) asm volatile("s_waitcnt vmcnt(" #n ")" ::: "memory")
; #define WAIT_L(n) asm volatile("s_waitcnt lgkmcnt(" #n ")" ::: "memory")
; #define BAR __builtin_amdgcn_s_barrier()
; #define SCHED __builtin_amdgcn_sched_barrier(0)
; template <class Epi>
; DEVI void gemm_phase(const Params& p, const u16* __restrict__ A, const u16* __restrict__ Bt, const int M, const int N, const int K, const int Msplit, const Epi& epi) {
;     ...
;       LDB(B1, 0, 1); STAGE(SB(0, 0), Bt, bcol, t + 2);
;       BAR; WAIT_L(0); MMA(0, 1, At, B1); BAR;
;       LDA(At, 0, 1); STAGE(SA(0, 0), A, brow, t + 2);
;       BAR; WAIT_L(0); MMA(1, 0, At, B0); BAR; SCHED;
;       STAGE(SB(0, 1), Bt, bcol + HALF, t + 2);
;       WAIT_V(6); BAR; MMA(1, 1, At, B1); BAR;
	s_add_i32 s53, s53, 2
	s_add_u32 s57, s43, s12
	s_addc_u32 s58, s52, s13
	s_add_u32 s38, s57, 0x100
	s_addc_u32 s39, s58, 0
	s_add_i32 s89, s56, 0x10000
	ds_read_b128 v[192:195], v251
	ds_read_b128 v[196:199], v251 offset:1024
	ds_read_b128 v[200:203], v251 offset:2048
	ds_read_b128 v[204:207], v251 offset:3072
	s_mov_b32 m0, s89
	v_lshl_add_u64 v[208:209], s[38:39], 0, v[226:227]
	s_add_i32 s63, s56, 0x12000
	global_load_lds_dwordx4 v[208:209], off
	v_lshl_add_u64 v[208:209], s[38:39], 0, v[228:229]
	s_mov_b32 m0, s63
	s_nop 0
	global_load_lds_dwordx4 v[208:209], off
	s_barrier
	s_waitcnt lgkmcnt(0)
	s_setprio 1
	s_waitcnt lgkmcnt(0)
	v_mfma_f32_16x16x32_bf16 v[108:111], v[192:195], v[160:163], v[108:111]
	v_mfma_f32_16x16x32_bf16 v[104:107], v[200:203], v[160:163], v[104:107]
	v_mfma_f32_16x16x32_bf16 v[100:103], v[192:195], v[168:171], v[100:103]
	v_mfma_f32_16x16x32_bf16 v[96:99], v[200:203], v[168:171], v[96:99]
	v_mfma_f32_16x16x32_bf16 v[92:95], v[192:195], v[176:179], v[92:95]
	v_mfma_f32_16x16x32_bf16 v[88:91], v[200:203], v[176:179], v[88:91]
	v_mfma_f32_16x16x32_bf16 v[84:87], v[192:195], v[184:187], v[84:87]
	v_mfma_f32_16x16x32_bf16 v[80:83], v[200:203], v[184:187], v[80:83]
	v_mfma_f32_16x16x32_bf16 v[108:111], v[196:199], v[164:167], v[108:111]
	v_mfma_f32_16x16x32_bf16 v[104:107], v[204:207], v[164:167], v[104:107]
	v_mfma_f32_16x16x32_bf16 v[100:103], v[196:199], v[172:175], v[100:103]
	v_mfma_f32_16x16x32_bf16 v[96:99], v[204:207], v[172:175], v[96:99]
	v_mfma_f32_16x16x32_bf16 v[92:95], v[196:199], v[180:183], v[92:95]
	v_mfma_f32_16x16x32_bf16 v[88:91], v[204:207], v[180:183], v[88:91]
	v_mfma_f32_16x16x32_bf16 v[84:87], v[196:199], v[188:191], v[84:87]
	v_mfma_f32_16x16x32_bf16 v[80:83], v[204:207], v[188:191], v[80:83]
	s_setprio 0
	s_add_u32 s59, s20, s12
	s_addc_u32 s77, s21, s13
	s_add_u32 s38, s59, 0x100
	s_addc_u32 s39, s77, 0
	s_mov_b32 m0, s56
	s_barrier
	ds_read_b128 v[160:163], v247 offset:16384
	ds_read_b128 v[164:167], v247 offset:17408
	ds_read_b128 v[168:171], v248 offset:16384
	ds_read_b128 v[172:175], v248 offset:17408
	ds_read_b128 v[176:179], v249 offset:16384
	ds_read_b128 v[180:183], v249 offset:17408
	ds_read_b128 v[184:187], v250 offset:16384
	ds_read_b128 v[188:191], v250 offset:17408
	s_add_i32 s44, s56, 0x2000
	v_lshl_add_u64 v[208:209], s[38:39], 0, v[226:227]
	global_load_lds_dwordx4 v[208:209], off
	v_lshl_add_u64 v[208:209], s[38:39], 0, v[228:229]
	s_mov_b32 m0, s44
	s_nop 0
	global_load_lds_dwordx4 v[208:209], off
	s_waitcnt vmcnt(10)
	s_barrier
	s_waitcnt lgkmcnt(0)
	s_setprio 1
	s_waitcnt lgkmcnt(0)
	v_mfma_f32_16x16x32_bf16 v[76:79], v[144:147], v[160:163], v[76:79]
	v_mfma_f32_16x16x32_bf16 v[72:75], v[152:155], v[160:163], v[72:75]
	v_mfma_f32_16x16x32_bf16 v[68:71], v[144:147], v[168:171], v[68:71]
	v_mfma_f32_16x16x32_bf16 v[64:67], v[152:155], v[168:171], v[64:67]
	v_mfma_f32_16x16x32_bf16 v[60:63], v[144:147], v[176:179], v[60:63]
	v_mfma_f32_16x16x32_bf16 v[56:59], v[152:155], v[176:179], v[56:59]
	v_mfma_f32_16x16x32_bf16 v[52:55], v[144:147], v[184:187], v[52:55]
	v_mfma_f32_16x16x32_bf16 v[48:51], v[152:155], v[184:187], v[48:51]
	v_mfma_f32_16x16x32_bf16 v[76:79], v[148:151], v[164:167], v[76:79]
	v_mfma_f32_16x16x32_bf16 v[72:75], v[156:159], v[164:167], v[72:75]
	v_mfma_f32_16x16x32_bf16 v[68:71], v[148:151], v[172:175], v[68:71]
	v_mfma_f32_16x16x32_bf16 v[64:67], v[156:159], v[172:175], v[64:67]
	v_mfma_f32_16x16x32_bf16 v[60:63], v[148:151], v[180:183], v[60:63]
	v_mfma_f32_16x16x32_bf16 v[56:59], v[156:159], v[180:183], v[56:59]
	v_mfma_f32_16x16x32_bf16 v[52:55], v[148:151], v[188:191], v[52:55]
	v_mfma_f32_16x16x32_bf16 v[48:51], v[156:159], v[188:191], v[48:51]
	s_setprio 0
	s_barrier
	ds_read_b128 v[144:147], v245
	ds_read_b128 v[148:151], v245 offset:1024
	ds_read_b128 v[152:155], v245 offset:2048
	ds_read_b128 v[156:159], v245 offset:3072
	s_add_u32 vcc_lo, s22, s12
	s_addc_u32 vcc_hi, s23, s13
	s_add_u32 s38, vcc_lo, 0x100
	s_addc_u32 s39, vcc_hi, 0
	s_add_i32 s45, s56, 0x14000
	s_mov_b32 m0, s45
	v_lshl_add_u64 v[214:215], s[38:39], 0, v[226:227]
	global_load_lds_dwordx4 v[214:215], off
	v_lshl_add_u64 v[214:215], s[38:39], 0, v[228:229]
	s_add_i32 s38, s56, 0x16000
	s_mov_b32 m0, s38
	s_nop 0
	global_load_lds_dwordx4 v[214:215], off
	s_waitcnt vmcnt(6)
	s_barrier
	s_setprio 1
	v_mfma_f32_16x16x32_bf16 v[44:47], v[192:195], v[160:163], v[44:47]
	v_mfma_f32_16x16x32_bf16 v[40:43], v[200:203], v[160:163], v[40:43]
	v_mfma_f32_16x16x32_bf16 v[36:39], v[192:195], v[168:171], v[36:39]
	v_mfma_f32_16x16x32_bf16 v[32:35], v[200:203], v[168:171], v[32:35]
	v_mfma_f32_16x16x32_bf16 v[28:31], v[192:195], v[176:179], v[28:31]
	v_mfma_f32_16x16x32_bf16 v[24:27], v[200:203], v[176:179], v[24:27]
	v_mfma_f32_16x16x32_bf16 v[20:23], v[192:195], v[184:187], v[20:23]
	v_mfma_f32_16x16x32_bf16 v[16:19], v[200:203], v[184:187], v[16:19]
	v_mfma_f32_16x16x32_bf16 v[44:47], v[196:199], v[164:167], v[44:47]
	v_mfma_f32_16x16x32_bf16 v[40:43], v[204:207], v[164:167], v[40:43]
	v_mfma_f32_16x16x32_bf16 v[36:39], v[196:199], v[172:175], v[36:39]
	v_mfma_f32_16x16x32_bf16 v[32:35], v[204:207], v[172:175], v[32:35]
	v_mfma_f32_16x16x32_bf16 v[28:31], v[196:199], v[180:183], v[28:31]
	v_mfma_f32_16x16x32_bf16 v[24:27], v[204:207], v[180:183], v[24:27]
	v_mfma_f32_16x16x32_bf16 v[20:23], v[196:199], v[188:191], v[20:23]
	v_mfma_f32_16x16x32_bf16 v[16:19], v[204:207], v[188:191], v[16:19]
	s_setprio 0
	s_barrier
; #define LDA(dst, b, h) for (int m = 0; m < 4; ++m) for (int k = 0; k < 2; ++k) \
;     dst[m][k] = *reinterpret_cast<const bf16x8*>((char*)SA(b, h) + lds_byte(wr * 64 + m * 16 + fr, k * 32 + fq * 8))
; #define LDB(dst, b, h) for (int n = 0; n < 2; ++n) for (int k = 0; k < 2; ++k) \
;     dst[n][k] = *reinterpret_cast<const bf16x8*>((char*)SB(b, h) + lds_byte(wc * 32 + n * 16 + fr, k * 32 + fq * 8))
; #define WAIT_L(n) asm volatile("s_waitcnt lgkmcnt(" #n ")" ::: "memory")
; #define BAR __builtin_amdgcn_s_barrier()
; #define SCHED __builtin_amdgcn_sched_barrier(0)
; template <class Epi>
; DEVI void gemm_phase(const Params& p, const u16* __restrict__ A, const u16* __restrict__ Bt, const int M, const int N, const int K, const int Msplit, const Epi& epi) {
;     ...
;       LDB(B0, 1, 0); SCHED; LDA(At, 1, 0); STAGE(SA(0, 1), A, brow + HALF, t + 2);
;       WAIT_L(8); BAR; WAIT_L(0); MMA(0, 0, At, B0); BAR; SCHED;
;       LDB(B1, 1, 1); STAGE(SB(1, 0), Bt, bcol, t + 3);
;       BAR; WAIT_L(0); MMA(0, 1, At, B1); BAR;
;       LDA(At, 1, 1); STAGE(SA(1, 0), A, brow, t + 3);
;       BAR; WAIT_L(0); MMA(1, 0, At, B0); BAR; SCHED;
	s_add_u32 s54, s46, 0x100
	s_addc_u32 s55, s55, 0
	s_add_i32 s39, s56, 0x4000
	ds_read_b128 v[160:163], v247 offset:32768
	ds_read_b128 v[164:167], v247 offset:33792
	ds_read_b128 v[168:171], v248 offset:32768
	ds_read_b128 v[172:175], v248 offset:33792
	ds_read_b128 v[176:179], v249 offset:32768
	ds_read_b128 v[180:183], v249 offset:33792
	ds_read_b128 v[184:187], v250 offset:32768
	ds_read_b128 v[188:191], v250 offset:33792
	s_mov_b32 m0, s39
	v_lshl_add_u64 v[192:193], s[54:55], 0, v[226:227]
	s_add_i32 s46, s56, 0x6000
	global_load_lds_dwordx4 v[192:193], off
	v_lshl_add_u64 v[192:193], s[54:55], 0, v[228:229]
	s_mov_b32 m0, s46
	s_nop 0
	global_load_lds_dwordx4 v[192:193], off
	s_waitcnt lgkmcnt(8)
	s_barrier
	s_waitcnt lgkmcnt(0)
	s_setprio 1
	s_waitcnt lgkmcnt(0)
	v_mfma_f32_16x16x32_bf16 v[140:143], v[144:147], v[160:163], v[140:143]
	v_mfma_f32_16x16x32_bf16 v[136:139], v[152:155], v[160:163], v[136:139]
	v_mfma_f32_16x16x32_bf16 v[132:135], v[144:147], v[168:171], v[132:135]
	v_mfma_f32_16x16x32_bf16 v[128:131], v[152:155], v[168:171], v[128:131]
	v_mfma_f32_16x16x32_bf16 v[124:127], v[144:147], v[176:179], v[124:127]
	v_mfma_f32_16x16x32_bf16 v[120:123], v[152:155], v[176:179], v[120:123]
	v_mfma_f32_16x16x32_bf16 v[116:119], v[144:147], v[184:187], v[116:119]
	v_mfma_f32_16x16x32_bf16 v[112:115], v[152:155], v[184:187], v[112:115]
	v_mfma_f32_16x16x32_bf16 v[140:143], v[148:151], v[164:167], v[140:143]
	v_mfma_f32_16x16x32_bf16 v[136:139], v[156:159], v[164:167], v[136:139]
	v_mfma_f32_16x16x32_bf16 v[132:135], v[148:151], v[172:175], v[132:135]
	v_mfma_f32_16x16x32_bf16 v[128:131], v[156:159], v[172:175], v[128:131]
	v_mfma_f32_16x16x32_bf16 v[124:127], v[148:151], v[180:183], v[124:127]
	v_mfma_f32_16x16x32_bf16 v[120:123], v[156:159], v[180:183], v[120:123]
	v_mfma_f32_16x16x32_bf16 v[116:119], v[148:151], v[188:191], v[116:119]
	v_mfma_f32_16x16x32_bf16 v[112:115], v[156:159], v[188:191], v[112:115]
	s_setprio 0
	s_barrier
	s_add_u32 s54, s57, 0x180
	s_addc_u32 s55, s58, 0
	s_add_i32 s62, s56, 0x18000
	ds_read_b128 v[192:195], v232
	ds_read_b128 v[196:199], v232 offset:1024
	ds_read_b128 v[200:203], v232 offset:2048
	ds_read_b128 v[204:207], v232 offset:3072
	s_mov_b32 m0, s62
	v_lshl_add_u64 v[208:209], s[54:55], 0, v[226:227]
	s_add_i32 s57, s56, 0x1a000
	global_load_lds_dwordx4 v[208:209], off
	v_lshl_add_u64 v[208:209], s[54:55], 0, v[228:229]
	s_mov_b32 m0, s57
	s_nop 0
	global_load_lds_dwordx4 v[208:209], off
	s_barrier
	s_waitcnt lgkmcnt(0)
	s_setprio 1
	s_waitcnt lgkmcnt(0)
	v_mfma_f32_16x16x32_bf16 v[108:111], v[192:195], v[160:163], v[108:111]
	v_mfma_f32_16x16x32_bf16 v[104:107], v[200:203], v[160:163], v[104:107]
	v_mfma_f32_16x16x32_bf16 v[100:103], v[192:195], v[168:171], v[100:103]
	v_mfma_f32_16x16x32_bf16 v[96:99], v[200:203], v[168:171], v[96:99]
	v_mfma_f32_16x16x32_bf16 v[92:95], v[192:195], v[176:179], v[92:95]
	v_mfma_f32_16x16x32_bf16 v[88:91], v[200:203], v[176:179], v[88:91]
	v_mfma_f32_16x16x32_bf16 v[84:87], v[192:195], v[184:187], v[84:87]
	v_mfma_f32_16x16x32_bf16 v[80:83], v[200:203], v[184:187], v[80:83]
	v_mfma_f32_16x16x32_bf16 v[108:111], v[196:199], v[164:167], v[108:111]
	v_mfma_f32_16x16x32_bf16 v[104:107], v[204:207], v[164:167], v[104:107]
	v_mfma_f32_16x16x32_bf16 v[100:103], v[196:199], v[172:175], v[100:103]
	v_mfma_f32_16x16x32_bf16 v[96:99], v[204:207], v[172:175], v[96:99]
	v_mfma_f32_16x16x32_bf16 v[92:95], v[196:199], v[180:183], v[92:95]
	v_mfma_f32_16x16x32_bf16 v[88:91], v[204:207], v[180:183], v[88:91]
	v_mfma_f32_16x16x32_bf16 v[84:87], v[196:199], v[188:191], v[84:87]
	v_mfma_f32_16x16x32_bf16 v[80:83], v[204:207], v[188:191], v[80:83]
	s_setprio 0
	s_add_u32 s54, s59, 0x180
	s_addc_u32 s55, s77, 0
	s_add_i32 s77, s56, 0x8000
	s_barrier
	ds_read_b128 v[160:163], v247 offset:49152
	ds_read_b128 v[164:167], v247 offset:50176
	ds_read_b128 v[168:171], v248 offset:49152
	ds_read_b128 v[172:175], v248 offset:50176
	ds_read_b128 v[176:179], v249 offset:49152
	ds_read_b128 v[180:183], v249 offset:50176
	ds_read_b128 v[184:187], v250 offset:49152
	ds_read_b128 v[188:191], v250 offset:50176
	s_mov_b32 m0, s77
	v_lshl_add_u64 v[208:209], s[54:55], 0, v[226:227]
	s_add_i32 s88, s56, 0xa000
	global_load_lds_dwordx4 v[208:209], off
	v_lshl_add_u64 v[208:209], s[54:55], 0, v[228:229]
	s_mov_b32 m0, s88
	s_nop 0
	global_load_lds_dwordx4 v[208:209], off
	s_waitcnt vmcnt(10)
	s_barrier
	s_waitcnt lgkmcnt(0)
	s_setprio 1
	s_waitcnt lgkmcnt(0)
	v_mfma_f32_16x16x32_bf16 v[76:79], v[144:147], v[160:163], v[76:79]
	v_mfma_f32_16x16x32_bf16 v[72:75], v[152:155], v[160:163], v[72:75]
	v_mfma_f32_16x16x32_bf16 v[68:71], v[144:147], v[168:171], v[68:71]
	v_mfma_f32_16x16x32_bf16 v[64:67], v[152:155], v[168:171], v[64:67]
	v_mfma_f32_16x16x32_bf16 v[60:63], v[144:147], v[176:179], v[60:63]
	v_mfma_f32_16x16x32_bf16 v[56:59], v[152:155], v[176:179], v[56:59]
	v_mfma_f32_16x16x32_bf16 v[52:55], v[144:147], v[184:187], v[52:55]
	v_mfma_f32_16x16x32_bf16 v[48:51], v[152:155], v[184:187], v[48:51]
	v_mfma_f32_16x16x32_bf16 v[76:79], v[148:151], v[164:167], v[76:79]
	v_mfma_f32_16x16x32_bf16 v[72:75], v[156:159], v[164:167], v[72:75]
	v_mfma_f32_16x16x32_bf16 v[68:71], v[148:151], v[172:175], v[68:71]
	v_mfma_f32_16x16x32_bf16 v[64:67], v[156:159], v[172:175], v[64:67]
	v_mfma_f32_16x16x32_bf16 v[60:63], v[148:151], v[180:183], v[60:63]
	v_mfma_f32_16x16x32_bf16 v[56:59], v[156:159], v[180:183], v[56:59]
	v_mfma_f32_16x16x32_bf16 v[52:55], v[148:151], v[188:191], v[52:55]
	v_mfma_f32_16x16x32_bf16 v[48:51], v[156:159], v[188:191], v[48:51]
	s_setprio 0
	s_barrier
; #define LDA(dst, b, h) for (int m = 0; m < 4; ++m) for (int k = 0; k < 2; ++k) \
;     dst[m][k] = *reinterpret_cast<const bf16x8*>((char*)SA(b, h) + lds_byte(wr * 64 + m * 16 + fr, k * 32 + fq * 8))
; #define LDB(dst, b, h) for (int n = 0; n < 2; ++n) for (int k = 0; k < 2; ++k) \
;     dst[n][k] = *reinterpret_cast<const bf16x8*>((char*)SB(b, h) + lds_byte(wc * 32 + n * 16 + fr, k * 32 + fq * 8))
; #define WAIT_V(n) asm volatile("s_waitcnt vmcnt(" #n ")" ::: "memory")
; #define WAIT_L(n) asm volatile("s_waitcnt lgkmcnt(" #n ")" ::: "memory")
; #define BAR __builtin_amdgcn_s_barrier()
; template <class Epi>
; DEVI void gemm_phase(const Params& p, const u16* __restrict__ A, const u16* __restrict__ Bt, const int M, const int N, const int K, const int Msplit, const Epi& epi) {
;     ...
;       STAGE(SB(1, 1), Bt, bcol + HALF, t + 3);
;       WAIT_V(6); BAR; MMA(1, 1, At, B1); BAR;
;     }
;     { LDB(B0, 0, 0); LDA(At, 0, 0); STAGE(SA(1, 1), A, brow + HALF, nt - 1);
;       BAR; WAIT_L(0); MMA(0, 0, At, B0); BAR;
;       LDB(B1, 0, 1); BAR; WAIT_L(0); MMA(0, 1, At, B1); BAR;
;       LDA(At, 0, 1); WAIT_V(4); BAR; WAIT_L(0); MMA(1, 0, At, B0); MMA(1, 1, At, B1); BAR; }
	ds_read_b128 v[144:147], v246
	ds_read_b128 v[148:151], v246 offset:1024
	ds_read_b128 v[152:155], v246 offset:2048
	ds_read_b128 v[156:159], v246 offset:3072
	s_add_u32 s58, vcc_lo, 0x180
	s_addc_u32 s59, vcc_hi, 0
	s_add_i32 s54, s56, 0x1c000
	s_mov_b32 m0, s54
	v_lshl_add_u64 v[214:215], s[58:59], 0, v[226:227]
	s_add_i32 s55, s56, 0x1e000
	global_load_lds_dwordx4 v[214:215], off
	v_lshl_add_u64 v[214:215], s[58:59], 0, v[228:229]
	s_mov_b32 m0, s55
	s_nop 0
	global_load_lds_dwordx4 v[214:215], off
	s_waitcnt vmcnt(6)
	s_barrier
	s_setprio 1
	v_mfma_f32_16x16x32_bf16 v[44:47], v[192:195], v[160:163], v[44:47]
	v_mfma_f32_16x16x32_bf16 v[40:43], v[200:203], v[160:163], v[40:43]
	v_mfma_f32_16x16x32_bf16 v[36:39], v[192:195], v[168:171], v[36:39]
	v_mfma_f32_16x16x32_bf16 v[32:35], v[200:203], v[168:171], v[32:35]
	v_mfma_f32_16x16x32_bf16 v[28:31], v[192:195], v[176:179], v[28:31]
	v_mfma_f32_16x16x32_bf16 v[24:27], v[200:203], v[176:179], v[24:27]
	v_mfma_f32_16x16x32_bf16 v[20:23], v[192:195], v[184:187], v[20:23]
	v_mfma_f32_16x16x32_bf16 v[16:19], v[200:203], v[184:187], v[16:19]
	v_mfma_f32_16x16x32_bf16 v[44:47], v[196:199], v[164:167], v[44:47]
	v_mfma_f32_16x16x32_bf16 v[40:43], v[204:207], v[164:167], v[40:43]
	v_mfma_f32_16x16x32_bf16 v[36:39], v[196:199], v[172:175], v[36:39]
	v_mfma_f32_16x16x32_bf16 v[32:35], v[204:207], v[172:175], v[32:35]
	v_mfma_f32_16x16x32_bf16 v[28:31], v[196:199], v[180:183], v[28:31]
	v_mfma_f32_16x16x32_bf16 v[24:27], v[204:207], v[180:183], v[24:27]
	v_mfma_f32_16x16x32_bf16 v[20:23], v[196:199], v[188:191], v[20:23]
	v_mfma_f32_16x16x32_bf16 v[16:19], v[204:207], v[188:191], v[16:19]
	s_setprio 0
	s_add_u32 s12, s12, 0x100
	s_addc_u32 s13, s13, 0
	s_cmp_ge_i32 s53, s27
	s_barrier
	s_cbranch_scc0 .LBB0_813
	s_lshl_b32 s12, s49, 7
	s_add_u32 s20, s60, s12
	s_addc_u32 s21, s61, 0
	s_add_u32 s22, s4, s12
	s_mov_b32 m0, s90
	s_addc_u32 s23, s5, 0
	s_add_i32 s90, s24, -1
	s_lshl_b64 s[12:13], s[90:91], 7
	s_add_u32 s12, s25, s12
	s_addc_u32 s13, s26, s13
	ds_read_b128 v[172:175], v246
	ds_read_b128 v[176:179], v246 offset:1024
	ds_read_b128 v[180:183], v246 offset:2048
	ds_read_b128 v[184:187], v246 offset:3072
	ds_read_b128 v[144:147], v247
	ds_read_b128 v[148:151], v247 offset:1024
	ds_read_b128 v[152:155], v248
	ds_read_b128 v[156:159], v248 offset:1024
	ds_read_b128 v[160:163], v249
	ds_read_b128 v[164:167], v249 offset:1024
	ds_read_b128 v[168:171], v250
	ds_read_b128 v[188:191], v250 offset:1024
	s_nop 0
	v_lshl_add_u64 v[192:193], s[12:13], 0, v[226:227]
	global_load_lds_dwordx4 v[192:193], off
	v_lshl_add_u64 v[192:193], s[12:13], 0, v[228:229]
	s_mov_b32 m0, s47
	s_nop 0
	global_load_lds_dwordx4 v[192:193], off
	s_barrier
	s_waitcnt lgkmcnt(0)
	s_setprio 1
	s_waitcnt lgkmcnt(0)
	v_mfma_f32_16x16x32_bf16 v[140:143], v[172:175], v[144:147], v[140:143]
	v_mfma_f32_16x16x32_bf16 v[136:139], v[180:183], v[144:147], v[136:139]
	v_mfma_f32_16x16x32_bf16 v[132:135], v[172:175], v[152:155], v[132:135]
	v_mfma_f32_16x16x32_bf16 v[128:131], v[180:183], v[152:155], v[128:131]
	v_mfma_f32_16x16x32_bf16 v[124:127], v[172:175], v[160:163], v[124:127]
	v_mfma_f32_16x16x32_bf16 v[120:123], v[180:183], v[160:163], v[120:123]
	v_mfma_f32_16x16x32_bf16 v[116:119], v[172:175], v[168:171], v[116:119]
	v_mfma_f32_16x16x32_bf16 v[112:115], v[180:183], v[168:171], v[112:115]
	v_mfma_f32_16x16x32_bf16 v[140:143], v[176:179], v[148:151], v[140:143]
	v_mfma_f32_16x16x32_bf16 v[136:139], v[184:187], v[148:151], v[136:139]
	v_mfma_f32_16x16x32_bf16 v[132:135], v[176:179], v[156:159], v[132:135]
	v_mfma_f32_16x16x32_bf16 v[128:131], v[184:187], v[156:159], v[128:131]
	v_mfma_f32_16x16x32_bf16 v[124:127], v[176:179], v[164:167], v[124:127]
	v_mfma_f32_16x16x32_bf16 v[120:123], v[184:187], v[164:167], v[120:123]
	v_mfma_f32_16x16x32_bf16 v[116:119], v[176:179], v[188:191], v[116:119]
	v_mfma_f32_16x16x32_bf16 v[112:115], v[184:187], v[188:191], v[112:115]
	s_setprio 0
	s_barrier
	ds_read_b128 v[192:195], v251
	ds_read_b128 v[196:199], v251 offset:1024
	ds_read_b128 v[200:203], v251 offset:2048
	ds_read_b128 v[204:207], v251 offset:3072
	s_barrier
	s_waitcnt lgkmcnt(0)
	s_setprio 1
	s_waitcnt lgkmcnt(0)
	v_mfma_f32_16x16x32_bf16 v[108:111], v[192:195], v[144:147], v[108:111]
	v_mfma_f32_16x16x32_bf16 v[104:107], v[200:203], v[144:147], v[104:107]
	v_mfma_f32_16x16x32_bf16 v[100:103], v[192:195], v[152:155], v[100:103]
	v_mfma_f32_16x16x32_bf16 v[96:99], v[200:203], v[152:155], v[96:99]
	v_mfma_f32_16x16x32_bf16 v[92:95], v[192:195], v[160:163], v[92:95]
	v_mfma_f32_16x16x32_bf16 v[88:91], v[200:203], v[160:163], v[88:91]
	v_mfma_f32_16x16x32_bf16 v[84:87], v[192:195], v[168:171], v[84:87]
	v_mfma_f32_16x16x32_bf16 v[80:83], v[200:203], v[168:171], v[80:83]
	v_mfma_f32_16x16x32_bf16 v[108:111], v[196:199], v[148:151], v[108:111]
	v_mfma_f32_16x16x32_bf16 v[144:147], v[204:207], v[148:151], v[104:107]
	v_mfma_f32_16x16x32_bf16 v[100:103], v[196:199], v[156:159], v[100:103]
	v_mfma_f32_16x16x32_bf16 v[148:151], v[204:207], v[156:159], v[96:99]
	v_mfma_f32_16x16x32_bf16 v[92:95], v[196:199], v[164:167], v[92:95]
	v_mfma_f32_16x16x32_bf16 v[152:155], v[204:207], v[164:167], v[88:91]
	v_mfma_f32_16x16x32_bf16 v[84:87], v[196:199], v[188:191], v[84:87]
	v_mfma_f32_16x16x32_bf16 v[156:159], v[204:207], v[188:191], v[80:83]
	s_setprio 0
	s_barrier
; #define LDA(dst, b, h) for (int m = 0; m < 4; ++m) for (int k = 0; k < 2; ++k) \
;     dst[m][k] = *reinterpret_cast<const bf16x8*>((char*)SA(b, h) + lds_byte(wr * 64 + m * 16 + fr, k * 32 + fq * 8))
; #define LDB(dst, b, h) for (int n = 0; n < 2; ++n) for (int k = 0; k < 2; ++k) \
;     dst[n][k] = *reinterpret_cast<const bf16x8*>((char*)SB(b, h) + lds_byte(wc * 32 + n * 16 + fr, k * 32 + fq * 8))
; #define WAIT_V(n) asm volatile("s_waitcnt vmcnt(" #n ")" ::: "memory")
; #define WAIT_L(n) asm volatile("s_waitcnt lgkmcnt(" #n ")" ::: "memory")
; #define BAR __builtin_amdgcn_s_barrier()
; #define PRO_K0(brow_, bcol_) do { STAGE(SB(0, 0), Bt, bcol_, 0); STAGE(SA(0, 0), A, brow_, 0); STAGE(SB(0, 1), Bt, (bcol_) + HALF, 0); STAGE(SA(0, 1), A, (brow_) + HALF, 0); } while (0)
; template <class Epi>
; DEVI void gemm_phase(const Params& p, const u16* __restrict__ A, const u16* __restrict__ Bt, const int M, const int N, const int K, const int Msplit, const Epi& epi) {
;     ...
;       LDA(At, 0, 1); WAIT_V(4); BAR; WAIT_L(0); MMA(1, 0, At, B0); MMA(1, 1, At, B1); BAR; }
;     { LDB(B0, 1, 0); LDA(At, 1, 0); WAIT_V(2); BAR;
;       if (have2) { const u16* Asv = A; const u16* Bsv = Bt; A = An; Bt = Bn; PRO_K0(pm * BM, pn * BM); A = Asv; Bt = Bsv; }
	s_nop 0
	ds_read_b128 v[80:83], v247 offset:16384
	ds_read_b128 v[88:91], v247 offset:17408
	ds_read_b128 v[96:99], v248 offset:16384
	ds_read_b128 v[104:107], v248 offset:17408
	ds_read_b128 v[188:191], v249 offset:16384
	ds_read_b128 v[208:211], v249 offset:17408
	ds_read_b128 v[214:217], v250 offset:16384
	ds_read_b128 v[220:223], v250 offset:17408
	s_waitcnt vmcnt(4)
	s_barrier
	s_waitcnt lgkmcnt(0)
	s_setprio 1
	s_waitcnt lgkmcnt(0)
	v_mfma_f32_16x16x32_bf16 v[76:79], v[172:175], v[80:83], v[76:79]
	v_mfma_f32_16x16x32_bf16 v[72:75], v[180:183], v[80:83], v[72:75]
	v_mfma_f32_16x16x32_bf16 v[68:71], v[172:175], v[96:99], v[68:71]
	v_mfma_f32_16x16x32_bf16 v[64:67], v[180:183], v[96:99], v[64:67]
	v_mfma_f32_16x16x32_bf16 v[60:63], v[172:175], v[188:191], v[60:63]
	v_mfma_f32_16x16x32_bf16 v[56:59], v[180:183], v[188:191], v[56:59]
	v_mfma_f32_16x16x32_bf16 v[52:55], v[172:175], v[214:217], v[52:55]
	v_mfma_f32_16x16x32_bf16 v[48:51], v[180:183], v[214:217], v[48:51]
	v_mfma_f32_16x16x32_bf16 v[76:79], v[176:179], v[88:91], v[76:79]
	v_mfma_f32_16x16x32_bf16 v[160:163], v[184:187], v[88:91], v[72:75]
	v_mfma_f32_16x16x32_bf16 v[68:71], v[176:179], v[104:107], v[68:71]
	v_mfma_f32_16x16x32_bf16 v[164:167], v[184:187], v[104:107], v[64:67]
	v_mfma_f32_16x16x32_bf16 v[60:63], v[176:179], v[208:211], v[60:63]
	v_mfma_f32_16x16x32_bf16 v[168:171], v[184:187], v[208:211], v[56:59]
	v_mfma_f32_16x16x32_bf16 v[52:55], v[176:179], v[220:223], v[52:55]
	v_mfma_f32_16x16x32_bf16 v[172:175], v[184:187], v[220:223], v[48:51]
	s_setprio 0
	s_setprio 1
	v_mfma_f32_16x16x32_bf16 v[44:47], v[192:195], v[80:83], v[44:47]
	v_mfma_f32_16x16x32_bf16 v[40:43], v[200:203], v[80:83], v[40:43]
	v_mfma_f32_16x16x32_bf16 v[36:39], v[192:195], v[96:99], v[36:39]
	v_mfma_f32_16x16x32_bf16 v[32:35], v[200:203], v[96:99], v[32:35]
	v_mfma_f32_16x16x32_bf16 v[28:31], v[192:195], v[188:191], v[28:31]
	v_mfma_f32_16x16x32_bf16 v[24:27], v[200:203], v[188:191], v[24:27]
	v_mfma_f32_16x16x32_bf16 v[20:23], v[192:195], v[214:217], v[20:23]
	v_mfma_f32_16x16x32_bf16 v[16:19], v[200:203], v[214:217], v[16:19]
	v_mfma_f32_16x16x32_bf16 v[44:47], v[196:199], v[88:91], v[44:47]
	v_mfma_f32_16x16x32_bf16 v[176:179], v[204:207], v[88:91], v[40:43]
	v_mfma_f32_16x16x32_bf16 v[36:39], v[196:199], v[104:107], v[36:39]
	v_mfma_f32_16x16x32_bf16 v[180:183], v[204:207], v[104:107], v[32:35]
	v_mfma_f32_16x16x32_bf16 v[28:31], v[196:199], v[208:211], v[28:31]
	v_mfma_f32_16x16x32_bf16 v[184:187], v[204:207], v[208:211], v[24:27]
	v_mfma_f32_16x16x32_bf16 v[20:23], v[196:199], v[220:223], v[20:23]
	v_mfma_f32_16x16x32_bf16 v[188:191], v[204:207], v[220:223], v[16:19]
	s_setprio 0
	s_barrier
	s_nop 0
	ds_read_b128 v[16:19], v245
	ds_read_b128 v[24:27], v245 offset:1024
	ds_read_b128 v[32:35], v245 offset:2048
	ds_read_b128 v[40:43], v245 offset:3072
	ds_read_b128 v[96:99], v247 offset:32768
	ds_read_b128 v[192:195], v247 offset:33792
	ds_read_b128 v[80:83], v248 offset:32768
	ds_read_b128 v[88:91], v248 offset:33792
	ds_read_b128 v[64:67], v249 offset:32768
	ds_read_b128 v[72:75], v249 offset:33792
	ds_read_b128 v[48:51], v250 offset:32768
	ds_read_b128 v[56:59], v250 offset:33792
	s_waitcnt vmcnt(2)
	s_and_b64 vcc, exec, s[10:11]
	s_mul_i32 s25, s48, 0x160000
	s_mul_i32 s24, s41, 0x160000
	s_barrier
	s_cbranch_vccz .LBB0_816
	s_lshl_b32 s26, s48, 8
	s_mul_hi_i32 s13, s26, 0x1600
	s_add_u32 s12, s22, s25
	s_addc_u32 s13, s23, s13
	s_mov_b32 m0, s89
	s_lshl_b32 s27, s41, 8
	v_lshl_add_u64 v[104:105], s[12:13], 0, v[226:227]
	global_load_lds_dwordx4 v[104:105], off
	v_lshl_add_u64 v[104:105], s[12:13], 0, v[228:229]
	s_mul_hi_i32 s13, s27, 0x1600
	s_add_u32 s12, s20, s24
	s_mov_b32 m0, s63
	s_addc_u32 s13, s21, s13
	global_load_lds_dwordx4 v[104:105], off
	s_mov_b32 m0, s56
	v_lshl_add_u64 v[104:105], s[12:13], 0, v[226:227]
	global_load_lds_dwordx4 v[104:105], off
	v_lshl_add_u64 v[104:105], s[12:13], 0, v[228:229]
	s_or_b32 s12, s26, 0x80
	s_mul_hi_i32 s13, s12, 0x1600
	s_mulk_i32 s12, 0x1600
	s_add_u32 s12, s22, s12
	s_mov_b32 m0, s44
	s_addc_u32 s13, s23, s13
	global_load_lds_dwordx4 v[104:105], off
	s_mov_b32 m0, s45
	v_lshl_add_u64 v[104:105], s[12:13], 0, v[226:227]
	global_load_lds_dwordx4 v[104:105], off
	v_lshl_add_u64 v[104:105], s[12:13], 0, v[228:229]
	s_or_b32 s12, s27, 0x80
	s_mul_hi_i32 s13, s12, 0x1600
	s_mulk_i32 s12, 0x1600
	s_add_u32 s12, s20, s12
	s_mov_b32 m0, s38
	s_addc_u32 s13, s21, s13
	global_load_lds_dwordx4 v[104:105], off
	s_mov_b32 m0, s39
	v_lshl_add_u64 v[104:105], s[12:13], 0, v[226:227]
	global_load_lds_dwordx4 v[104:105], off
	v_lshl_add_u64 v[104:105], s[12:13], 0, v[228:229]
	s_mov_b32 m0, s46
	s_nop 0
	global_load_lds_dwordx4 v[104:105], off

; #define LDA(dst, b, h) for (int m = 0; m < 4; ++m) for (int k = 0; k < 2; ++k) \
;     dst[m][k] = *reinterpret_cast<const bf16x8*>((char*)SA(b, h) + lds_byte(wr * 64 + m * 16 + fr, k * 32 + fq * 8))
; #define LDB(dst, b, h) for (int n = 0; n < 2; ++n) for (int k = 0; k < 2; ++k) \
;     dst[n][k] = *reinterpret_cast<const bf16x8*>((char*)SB(b, h) + lds_byte(wc * 32 + n * 16 + fr, k * 32 + fq * 8))
; #define WAIT_V(n) asm volatile("s_waitcnt vmcnt(" #n ")" ::: "memory")
; #define WAIT_L(n) asm volatile("s_waitcnt lgkmcnt(" #n ")" ::: "memory")
; #define BAR __builtin_amdgcn_s_barrier()
; #define SCHED __builtin_amdgcn_sched_barrier(0)
; template <class Epi>
; DEVI void gemm_phase(const Params& p, const u16* __restrict__ A, const u16* __restrict__ Bt, const int M, const int N, const int K, const int Msplit, const Epi& epi) {
;     ...
;     f32x4 acc[2][2][4][2] = {};
;     bf16x8 At[4][2], B0[2][2], B1[2][2];
;     if (it == 0) { WAIT_V(0); } else { if constexpr (Epi::NST == 16) WAIT_V(16); else if constexpr (Epi::NST == 32) WAIT_V(32); else WAIT_V(0); }
;     if (wr == 1) BAR;
;     BAR;
;     BAR;
;     for (int t = 0; t < nt - 2; t += 2) {
;       LDB(B0, 0, 0); SCHED; LDA(At, 0, 0); STAGE(SA(1, 1), A, brow + HALF, t + 1);
;       WAIT_L(8); BAR; WAIT_L(0); MMA(0, 0, At, B0); BAR; SCHED;
.LBB0_1103:
	s_or_b64 exec, exec, s[14:15]
	s_lshl_b32 s36, s16, 8
	s_or_b32 s14, s36, 0x80
	s_ashr_i32 s15, s14, 31
	s_lshl_b32 s40, s17, 8
	s_lshl_b64 s[14:15], s[14:15], 11
	s_add_u32 s17, s68, s14
	s_addc_u32 s18, s69, s15
	s_ashr_i32 s41, s40, 31
	s_lshl_b64 s[14:15], s[40:41], 11
	s_add_u32 s19, s2, s14
	s_addc_u32 s20, s76, s15
	s_ashr_i32 s37, s36, 31
	s_lshl_b64 s[14:15], s[36:37], 11
	s_add_u32 s21, s68, s14
	s_addc_u32 s22, s69, s15
	s_or_b32 s24, s40, 0x80
	s_ashr_i32 s25, s24, 31
	s_lshl_b64 s[24:25], s[24:25], 11
	s_add_u32 s23, s2, s24
	s_addc_u32 s24, s76, s25
	s_add_u32 s25, s17, 0x100
	s_addc_u32 s26, s18, 0
	v_readlane_b32 s27, v254, 50
	s_add_u32 s27, s27, s14
	v_readlane_b32 s14, v254, 51
	v_mov_b32_e32 v0, 0
	s_addc_u32 s41, s14, s15
	s_mov_b64 s[14:15], 0
	s_mov_b32 s42, -2
	v_mov_b32_e32 v1, v0
	v_mov_b32_e32 v2, v0
	v_mov_b32_e32 v3, v0
	v_mov_b32_e32 v4, v0
	v_mov_b32_e32 v5, v0
	v_mov_b32_e32 v6, v0
	v_mov_b32_e32 v7, v0
	v_mov_b32_e32 v8, v0
	v_mov_b32_e32 v9, v0
	v_mov_b32_e32 v10, v0
	v_mov_b32_e32 v11, v0
	v_mov_b32_e32 v12, v0
	v_mov_b32_e32 v13, v0
	v_mov_b32_e32 v14, v0
	v_mov_b32_e32 v15, v0
	v_mov_b32_e32 v16, v0
	v_mov_b32_e32 v17, v0
	v_mov_b32_e32 v18, v0
	v_mov_b32_e32 v19, v0
	v_mov_b32_e32 v20, v0
	v_mov_b32_e32 v21, v0
	v_mov_b32_e32 v22, v0
	v_mov_b32_e32 v23, v0
	v_mov_b32_e32 v24, v0
	v_mov_b32_e32 v25, v0
	v_mov_b32_e32 v26, v0
	v_mov_b32_e32 v27, v0
	v_mov_b32_e32 v28, v0
	v_mov_b32_e32 v29, v0
	v_mov_b32_e32 v30, v0
	v_mov_b32_e32 v31, v0
	v_mov_b32_e32 v32, v0
	v_mov_b32_e32 v33, v0
	v_mov_b32_e32 v34, v0
	v_mov_b32_e32 v35, v0
	v_mov_b32_e32 v36, v0
	v_mov_b32_e32 v37, v0
	v_mov_b32_e32 v38, v0
	v_mov_b32_e32 v39, v0
	v_mov_b32_e32 v40, v0
	v_mov_b32_e32 v41, v0
	v_mov_b32_e32 v42, v0
	v_mov_b32_e32 v43, v0
	v_mov_b32_e32 v44, v0
	v_mov_b32_e32 v45, v0
	v_mov_b32_e32 v46, v0
	v_mov_b32_e32 v47, v0
	v_mov_b32_e32 v48, v0
	v_mov_b32_e32 v49, v0
	v_mov_b32_e32 v50, v0
	v_mov_b32_e32 v51, v0
	v_mov_b32_e32 v52, v0
	v_mov_b32_e32 v53, v0
	v_mov_b32_e32 v54, v0
	v_mov_b32_e32 v55, v0
	v_mov_b32_e32 v56, v0
	v_mov_b32_e32 v57, v0
	v_mov_b32_e32 v58, v0
	v_mov_b32_e32 v59, v0
	v_mov_b32_e32 v60, v0
	v_mov_b32_e32 v61, v0
	v_mov_b32_e32 v62, v0
	v_mov_b32_e32 v63, v0
	v_mov_b32_e32 v64, v0
	v_mov_b32_e32 v65, v0
	v_mov_b32_e32 v66, v0
	v_mov_b32_e32 v67, v0
	v_mov_b32_e32 v68, v0
	v_mov_b32_e32 v69, v0
	v_mov_b32_e32 v70, v0
	v_mov_b32_e32 v71, v0
	v_mov_b32_e32 v72, v0
	v_mov_b32_e32 v73, v0
	v_mov_b32_e32 v74, v0
	v_mov_b32_e32 v75, v0
	v_mov_b32_e32 v76, v0
	v_mov_b32_e32 v77, v0
	v_mov_b32_e32 v78, v0
	v_mov_b32_e32 v79, v0
	v_mov_b32_e32 v80, v0
	v_mov_b32_e32 v81, v0
	v_mov_b32_e32 v82, v0
	v_mov_b32_e32 v83, v0
	v_mov_b32_e32 v84, v0
	v_mov_b32_e32 v85, v0
	v_mov_b32_e32 v86, v0
	v_mov_b32_e32 v87, v0
	v_mov_b32_e32 v88, v0
	v_mov_b32_e32 v89, v0
	v_mov_b32_e32 v90, v0
	v_mov_b32_e32 v91, v0
	v_mov_b32_e32 v92, v0
	v_mov_b32_e32 v93, v0
	v_mov_b32_e32 v94, v0
	v_mov_b32_e32 v95, v0
	v_mov_b32_e32 v96, v0
	v_mov_b32_e32 v97, v0
	v_mov_b32_e32 v98, v0
	v_mov_b32_e32 v99, v0
	v_mov_b32_e32 v100, v0
	v_mov_b32_e32 v101, v0
	v_mov_b32_e32 v102, v0
	v_mov_b32_e32 v103, v0
	v_mov_b32_e32 v104, v0
	v_mov_b32_e32 v105, v0
	v_mov_b32_e32 v106, v0
	v_mov_b32_e32 v107, v0
	v_mov_b32_e32 v108, v0
	v_mov_b32_e32 v109, v0
	v_mov_b32_e32 v110, v0
	v_mov_b32_e32 v111, v0
	v_mov_b32_e32 v112, v0
	v_mov_b32_e32 v113, v0
	v_mov_b32_e32 v114, v0
	v_mov_b32_e32 v115, v0
	v_mov_b32_e32 v116, v0
	v_mov_b32_e32 v117, v0
	v_mov_b32_e32 v118, v0
	v_mov_b32_e32 v119, v0
	v_mov_b32_e32 v120, v0
	v_mov_b32_e32 v121, v0
	v_mov_b32_e32 v122, v0
	v_mov_b32_e32 v123, v0
	v_mov_b32_e32 v124, v0
	v_mov_b32_e32 v125, v0
	v_mov_b32_e32 v126, v0
	v_mov_b32_e32 v127, v0
	s_barrier
	s_barrier
	ds_read_b128 v[128:131], v200
	ds_read_b128 v[132:135], v200 offset:1024
	ds_read_b128 v[136:139], v200 offset:2048
	ds_read_b128 v[140:143], v200 offset:3072
.LBB0_1104:
	s_add_u32 s38, s27, s14
	s_addc_u32 s39, s41, s15
	s_add_u32 s38, s38, 0x80
	s_addc_u32 s39, s39, 0
	s_add_i32 s47, s88, 0xc000
	ds_read_b128 v[144:147], v201
	ds_read_b128 v[148:151], v201 offset:1024
	ds_read_b128 v[152:155], v202
	ds_read_b128 v[156:159], v202 offset:1024
	ds_read_b128 v[160:163], v203
	ds_read_b128 v[164:167], v203 offset:1024
	ds_read_b128 v[168:171], v204
	ds_read_b128 v[172:175], v204 offset:1024
	s_mov_b32 m0, s47
	v_lshl_add_u64 v[176:177], s[38:39], 0, v[196:197]
	s_add_i32 s46, s88, 0xe000
	global_load_lds_dwordx4 v[176:177], off
	v_lshl_add_u64 v[176:177], s[38:39], 0, v[198:199]
	s_mov_b32 m0, s46
	s_nop 0
	global_load_lds_dwordx4 v[176:177], off
	s_waitcnt lgkmcnt(8)
	s_barrier
	s_waitcnt lgkmcnt(0)
	s_setprio 1
	s_waitcnt lgkmcnt(0)
	v_mfma_f32_16x16x32_bf16 v[124:127], v[144:147], v[128:131], v[124:127]
	v_mfma_f32_16x16x32_bf16 v[120:123], v[144:147], v[136:139], v[120:123]
	v_mfma_f32_16x16x32_bf16 v[116:119], v[152:155], v[128:131], v[116:119]
	v_mfma_f32_16x16x32_bf16 v[112:115], v[152:155], v[136:139], v[112:115]
	v_mfma_f32_16x16x32_bf16 v[108:111], v[160:163], v[128:131], v[108:111]
	v_mfma_f32_16x16x32_bf16 v[104:107], v[160:163], v[136:139], v[104:107]
	v_mfma_f32_16x16x32_bf16 v[100:103], v[168:171], v[128:131], v[100:103]
	v_mfma_f32_16x16x32_bf16 v[96:99], v[168:171], v[136:139], v[96:99]
	v_mfma_f32_16x16x32_bf16 v[124:127], v[148:151], v[132:135], v[124:127]
	v_mfma_f32_16x16x32_bf16 v[120:123], v[148:151], v[140:143], v[120:123]
	v_mfma_f32_16x16x32_bf16 v[116:119], v[156:159], v[132:135], v[116:119]
	v_mfma_f32_16x16x32_bf16 v[112:115], v[156:159], v[140:143], v[112:115]
	v_mfma_f32_16x16x32_bf16 v[108:111], v[164:167], v[132:135], v[108:111]
	v_mfma_f32_16x16x32_bf16 v[104:107], v[164:167], v[140:143], v[104:107]
	v_mfma_f32_16x16x32_bf16 v[100:103], v[172:175], v[132:135], v[100:103]
	v_mfma_f32_16x16x32_bf16 v[96:99], v[172:175], v[140:143], v[96:99]
	s_setprio 0
	s_barrier
; #define LDA(dst, b, h) for (int m = 0; m < 4; ++m) for (int k = 0; k < 2; ++k) \
;     dst[m][k] = *reinterpret_cast<const bf16x8*>((char*)SA(b, h) + lds_byte(wr * 64 + m * 16 + fr, k * 32 + fq * 8))
; #define LDB(dst, b, h) for (int n = 0; n < 2; ++n) for (int k = 0; k < 2; ++k) \
;     dst[n][k] = *reinterpret_cast<const bf16x8*>((char*)SB(b, h) + lds_byte(wc * 32 + n * 16 + fr, k * 32 + fq * 8))
; #define WAIT_V(n) asm volatile("s_waitcnt vmcnt(" #n ")" ::: "memory")
; #define WAIT_L(n) asm volatile("s_waitcnt lgkmcnt(" #n ")" ::: "memory")
; #define BAR __builtin_amdgcn_s_barrier()
; #define SCHED __builtin_amdgcn_sched_barrier(0)
; template <class Epi>
; DEVI void gemm_phase(const Params& p, const u16* __restrict__ A, const u16* __restrict__ Bt, const int M, const int N, const int K, const int Msplit, const Epi& epi) {
;     ...
;       LDB(B1, 0, 1); STAGE(SB(0, 0), Bt, bcol, t + 2);
;       BAR; WAIT_L(0); MMA(0, 1, At, B1); BAR;
;       LDA(At, 0, 1); STAGE(SA(0, 0), A, brow, t + 2);
;       BAR; WAIT_L(0); MMA(1, 0, At, B0); BAR; SCHED;
;       STAGE(SB(0, 1), Bt, bcol + HALF, t + 2);
;       WAIT_V(6); BAR; MMA(1, 1, At, B1); BAR;
	s_add_u32 s43, s19, s14
	s_addc_u32 s44, s20, s15
	s_add_u32 s38, s43, 0x100
	s_addc_u32 s39, s44, 0
	s_add_i32 s45, s88, 0x10000
	ds_read_b128 v[176:179], v205
	ds_read_b128 v[180:183], v205 offset:1024
	ds_read_b128 v[184:187], v205 offset:2048
	ds_read_b128 v[188:191], v205 offset:3072
	s_mov_b32 m0, s45
	v_lshl_add_u64 v[192:193], s[38:39], 0, v[196:197]
	s_add_i32 s49, s88, 0x12000
	global_load_lds_dwordx4 v[192:193], off
	v_lshl_add_u64 v[192:193], s[38:39], 0, v[198:199]
	s_mov_b32 m0, s49
	s_nop 0
	global_load_lds_dwordx4 v[192:193], off
	s_barrier
	s_waitcnt lgkmcnt(0)
	s_setprio 1
	s_waitcnt lgkmcnt(0)
	v_mfma_f32_16x16x32_bf16 v[92:95], v[144:147], v[176:179], v[92:95]
	v_mfma_f32_16x16x32_bf16 v[88:91], v[144:147], v[184:187], v[88:91]
	v_mfma_f32_16x16x32_bf16 v[84:87], v[152:155], v[176:179], v[84:87]
	v_mfma_f32_16x16x32_bf16 v[80:83], v[152:155], v[184:187], v[80:83]
	v_mfma_f32_16x16x32_bf16 v[76:79], v[160:163], v[176:179], v[76:79]
	v_mfma_f32_16x16x32_bf16 v[72:75], v[160:163], v[184:187], v[72:75]
	v_mfma_f32_16x16x32_bf16 v[68:71], v[168:171], v[176:179], v[68:71]
	v_mfma_f32_16x16x32_bf16 v[64:67], v[168:171], v[184:187], v[64:67]
	v_mfma_f32_16x16x32_bf16 v[92:95], v[148:151], v[180:183], v[92:95]
	v_mfma_f32_16x16x32_bf16 v[88:91], v[148:151], v[188:191], v[88:91]
	v_mfma_f32_16x16x32_bf16 v[84:87], v[156:159], v[180:183], v[84:87]
	v_mfma_f32_16x16x32_bf16 v[80:83], v[156:159], v[188:191], v[80:83]
	v_mfma_f32_16x16x32_bf16 v[76:79], v[164:167], v[180:183], v[76:79]
	v_mfma_f32_16x16x32_bf16 v[72:75], v[164:167], v[188:191], v[72:75]
	v_mfma_f32_16x16x32_bf16 v[68:71], v[172:175], v[180:183], v[68:71]
	v_mfma_f32_16x16x32_bf16 v[64:67], v[172:175], v[188:191], v[64:67]
	s_setprio 0
	s_add_u32 s54, s21, s14
	s_addc_u32 s55, s22, s15
	s_add_u32 s38, s54, 0x100
	s_addc_u32 s39, s55, 0
	s_mov_b32 m0, s88
	s_barrier
	ds_read_b128 v[144:147], v201 offset:16384
	ds_read_b128 v[148:151], v201 offset:17408
	ds_read_b128 v[152:155], v202 offset:16384
	ds_read_b128 v[156:159], v202 offset:17408
	ds_read_b128 v[160:163], v203 offset:16384
	ds_read_b128 v[164:167], v203 offset:17408
	ds_read_b128 v[168:171], v204 offset:16384
	ds_read_b128 v[172:175], v204 offset:17408
	s_nop 0
	v_lshl_add_u64 v[192:193], s[38:39], 0, v[196:197]
	global_load_lds_dwordx4 v[192:193], off
	v_lshl_add_u64 v[192:193], s[38:39], 0, v[198:199]
	s_mov_b32 m0, s89
	s_nop 0
	global_load_lds_dwordx4 v[192:193], off
	s_waitcnt vmcnt(10)
	s_barrier
	s_waitcnt lgkmcnt(0)
	s_setprio 1
	s_waitcnt lgkmcnt(0)
	v_mfma_f32_16x16x32_bf16 v[60:63], v[144:147], v[128:131], v[60:63]
	v_mfma_f32_16x16x32_bf16 v[56:59], v[144:147], v[136:139], v[56:59]
	v_mfma_f32_16x16x32_bf16 v[52:55], v[152:155], v[128:131], v[52:55]
	v_mfma_f32_16x16x32_bf16 v[48:51], v[152:155], v[136:139], v[48:51]
	v_mfma_f32_16x16x32_bf16 v[44:47], v[160:163], v[128:131], v[44:47]
	v_mfma_f32_16x16x32_bf16 v[40:43], v[160:163], v[136:139], v[40:43]
	v_mfma_f32_16x16x32_bf16 v[36:39], v[168:171], v[128:131], v[36:39]
	v_mfma_f32_16x16x32_bf16 v[32:35], v[168:171], v[136:139], v[32:35]
	v_mfma_f32_16x16x32_bf16 v[60:63], v[148:151], v[132:135], v[60:63]
	v_mfma_f32_16x16x32_bf16 v[56:59], v[148:151], v[140:143], v[56:59]
	v_mfma_f32_16x16x32_bf16 v[52:55], v[156:159], v[132:135], v[52:55]
	v_mfma_f32_16x16x32_bf16 v[48:51], v[156:159], v[140:143], v[48:51]
	v_mfma_f32_16x16x32_bf16 v[44:47], v[164:167], v[132:135], v[44:47]
	v_mfma_f32_16x16x32_bf16 v[40:43], v[164:167], v[140:143], v[40:43]
	v_mfma_f32_16x16x32_bf16 v[36:39], v[172:175], v[132:135], v[36:39]
	v_mfma_f32_16x16x32_bf16 v[32:35], v[172:175], v[140:143], v[32:35]
	s_setprio 0
	s_barrier
	ds_read_b128 v[128:131], v206
	ds_read_b128 v[132:135], v206 offset:1024
	ds_read_b128 v[136:139], v206 offset:2048
	ds_read_b128 v[140:143], v206 offset:3072
	s_add_u32 s58, s23, s14
	s_addc_u32 s59, s24, s15
	s_add_u32 s52, s58, 0x100
	s_addc_u32 s53, s59, 0
	s_add_i32 s38, s88, 0x14000
	s_mov_b32 m0, s38
	v_lshl_add_u64 v[226:227], s[52:53], 0, v[196:197]
	s_add_i32 s39, s88, 0x16000
	global_load_lds_dwordx4 v[226:227], off
	v_lshl_add_u64 v[226:227], s[52:53], 0, v[198:199]
	s_mov_b32 m0, s39
	s_nop 0
	global_load_lds_dwordx4 v[226:227], off
	s_waitcnt vmcnt(6)
	s_barrier
	s_setprio 1
	v_mfma_f32_16x16x32_bf16 v[28:31], v[144:147], v[176:179], v[28:31]
	v_mfma_f32_16x16x32_bf16 v[24:27], v[144:147], v[184:187], v[24:27]
	v_mfma_f32_16x16x32_bf16 v[20:23], v[152:155], v[176:179], v[20:23]
	v_mfma_f32_16x16x32_bf16 v[16:19], v[152:155], v[184:187], v[16:19]
	v_mfma_f32_16x16x32_bf16 v[12:15], v[160:163], v[176:179], v[12:15]
	v_mfma_f32_16x16x32_bf16 v[8:11], v[160:163], v[184:187], v[8:11]
	v_mfma_f32_16x16x32_bf16 v[4:7], v[168:171], v[176:179], v[4:7]
	v_mfma_f32_16x16x32_bf16 v[0:3], v[168:171], v[184:187], v[0:3]
	v_mfma_f32_16x16x32_bf16 v[28:31], v[148:151], v[180:183], v[28:31]
	v_mfma_f32_16x16x32_bf16 v[24:27], v[148:151], v[188:191], v[24:27]
	v_mfma_f32_16x16x32_bf16 v[20:23], v[156:159], v[180:183], v[20:23]
	v_mfma_f32_16x16x32_bf16 v[16:19], v[156:159], v[188:191], v[16:19]
	v_mfma_f32_16x16x32_bf16 v[12:15], v[164:167], v[180:183], v[12:15]
	v_mfma_f32_16x16x32_bf16 v[8:11], v[164:167], v[188:191], v[8:11]
	v_mfma_f32_16x16x32_bf16 v[4:7], v[172:175], v[180:183], v[4:7]
	v_mfma_f32_16x16x32_bf16 v[0:3], v[172:175], v[188:191], v[0:3]
	s_setprio 0
	s_barrier
; #define LDA(dst, b, h) for (int m = 0; m < 4; ++m) for (int k = 0; k < 2; ++k) \
;     dst[m][k] = *reinterpret_cast<const bf16x8*>((char*)SA(b, h) + lds_byte(wr * 64 + m * 16 + fr, k * 32 + fq * 8))
; #define LDB(dst, b, h) for (int n = 0; n < 2; ++n) for (int k = 0; k < 2; ++k) \
;     dst[n][k] = *reinterpret_cast<const bf16x8*>((char*)SB(b, h) + lds_byte(wc * 32 + n * 16 + fr, k * 32 + fq * 8))
; #define WAIT_L(n) asm volatile("s_waitcnt lgkmcnt(" #n ")" ::: "memory")
; #define BAR __builtin_amdgcn_s_barrier()
; #define SCHED __builtin_amdgcn_sched_barrier(0)
; template <class Epi>
; DEVI void gemm_phase(const Params& p, const u16* __restrict__ A, const u16* __restrict__ Bt, const int M, const int N, const int K, const int Msplit, const Epi& epi) {
;     ...
;       LDB(B0, 1, 0); SCHED; LDA(At, 1, 0); STAGE(SA(0, 1), A, brow + HALF, t + 2);
;       WAIT_L(8); BAR; WAIT_L(0); MMA(0, 0, At, B0); BAR; SCHED;
;       LDB(B1, 1, 1); STAGE(SB(1, 0), Bt, bcol, t + 3);
;       BAR; WAIT_L(0); MMA(0, 1, At, B1); BAR;
;       LDA(At, 1, 1); STAGE(SA(1, 0), A, brow, t + 3);
;       BAR; WAIT_L(0); MMA(1, 0, At, B0); BAR; SCHED;
	s_add_u32 s52, s25, s14
	s_addc_u32 s53, s26, s15
	s_mov_b32 m0, s90
	ds_read_b128 v[144:147], v201 offset:32768
	ds_read_b128 v[148:151], v201 offset:33792
	ds_read_b128 v[152:155], v202 offset:32768
	ds_read_b128 v[156:159], v202 offset:33792
	ds_read_b128 v[160:163], v203 offset:32768
	ds_read_b128 v[164:167], v203 offset:33792
	ds_read_b128 v[168:171], v204 offset:32768
	ds_read_b128 v[172:175], v204 offset:33792
	s_nop 0
	v_lshl_add_u64 v[176:177], s[52:53], 0, v[196:197]
	global_load_lds_dwordx4 v[176:177], off
	v_lshl_add_u64 v[176:177], s[52:53], 0, v[198:199]
	s_mov_b32 m0, s77
	s_nop 0
	global_load_lds_dwordx4 v[176:177], off
	s_waitcnt lgkmcnt(8)
	s_barrier
	s_waitcnt lgkmcnt(0)
	s_setprio 1
	s_waitcnt lgkmcnt(0)
	v_mfma_f32_16x16x32_bf16 v[124:127], v[144:147], v[128:131], v[124:127]
	v_mfma_f32_16x16x32_bf16 v[120:123], v[144:147], v[136:139], v[120:123]
	v_mfma_f32_16x16x32_bf16 v[116:119], v[152:155], v[128:131], v[116:119]
	v_mfma_f32_16x16x32_bf16 v[112:115], v[152:155], v[136:139], v[112:115]
	v_mfma_f32_16x16x32_bf16 v[108:111], v[160:163], v[128:131], v[108:111]
	v_mfma_f32_16x16x32_bf16 v[104:107], v[160:163], v[136:139], v[104:107]
	v_mfma_f32_16x16x32_bf16 v[100:103], v[168:171], v[128:131], v[100:103]
	v_mfma_f32_16x16x32_bf16 v[96:99], v[168:171], v[136:139], v[96:99]
	v_mfma_f32_16x16x32_bf16 v[124:127], v[148:151], v[132:135], v[124:127]
	v_mfma_f32_16x16x32_bf16 v[120:123], v[148:151], v[140:143], v[120:123]
	v_mfma_f32_16x16x32_bf16 v[116:119], v[156:159], v[132:135], v[116:119]
	v_mfma_f32_16x16x32_bf16 v[112:115], v[156:159], v[140:143], v[112:115]
	v_mfma_f32_16x16x32_bf16 v[108:111], v[164:167], v[132:135], v[108:111]
	v_mfma_f32_16x16x32_bf16 v[104:107], v[164:167], v[140:143], v[104:107]
	v_mfma_f32_16x16x32_bf16 v[100:103], v[172:175], v[132:135], v[100:103]
	v_mfma_f32_16x16x32_bf16 v[96:99], v[172:175], v[140:143], v[96:99]
	s_setprio 0
	s_barrier
	s_add_u32 s52, s43, 0x180
	s_addc_u32 s53, s44, 0
	s_add_i32 s48, s88, 0x18000
	ds_read_b128 v[176:179], v207
	ds_read_b128 v[180:183], v207 offset:1024
	ds_read_b128 v[184:187], v207 offset:2048
	ds_read_b128 v[188:191], v207 offset:3072
	s_mov_b32 m0, s48
	v_lshl_add_u64 v[192:193], s[52:53], 0, v[196:197]
	s_add_i32 s43, s88, 0x1a000
	global_load_lds_dwordx4 v[192:193], off
	v_lshl_add_u64 v[192:193], s[52:53], 0, v[198:199]
	s_mov_b32 m0, s43
	s_nop 0
	global_load_lds_dwordx4 v[192:193], off
	s_barrier
	s_waitcnt lgkmcnt(0)
	s_setprio 1
	s_waitcnt lgkmcnt(0)
	v_mfma_f32_16x16x32_bf16 v[92:95], v[144:147], v[176:179], v[92:95]
	v_mfma_f32_16x16x32_bf16 v[88:91], v[144:147], v[184:187], v[88:91]
	v_mfma_f32_16x16x32_bf16 v[84:87], v[152:155], v[176:179], v[84:87]
	v_mfma_f32_16x16x32_bf16 v[80:83], v[152:155], v[184:187], v[80:83]
	v_mfma_f32_16x16x32_bf16 v[76:79], v[160:163], v[176:179], v[76:79]
	v_mfma_f32_16x16x32_bf16 v[72:75], v[160:163], v[184:187], v[72:75]
	v_mfma_f32_16x16x32_bf16 v[68:71], v[168:171], v[176:179], v[68:71]
	v_mfma_f32_16x16x32_bf16 v[64:67], v[168:171], v[184:187], v[64:67]
	v_mfma_f32_16x16x32_bf16 v[92:95], v[148:151], v[180:183], v[92:95]
	v_mfma_f32_16x16x32_bf16 v[88:91], v[148:151], v[188:191], v[88:91]
	v_mfma_f32_16x16x32_bf16 v[84:87], v[156:159], v[180:183], v[84:87]
	v_mfma_f32_16x16x32_bf16 v[80:83], v[156:159], v[188:191], v[80:83]
	v_mfma_f32_16x16x32_bf16 v[76:79], v[164:167], v[180:183], v[76:79]
	v_mfma_f32_16x16x32_bf16 v[72:75], v[164:167], v[188:191], v[72:75]
	v_mfma_f32_16x16x32_bf16 v[68:71], v[172:175], v[180:183], v[68:71]
	v_mfma_f32_16x16x32_bf16 v[64:67], v[172:175], v[188:191], v[64:67]
	s_setprio 0
	s_add_u32 s52, s54, 0x180
	s_addc_u32 s53, s55, 0
	s_mov_b32 m0, s0
	s_barrier
	ds_read_b128 v[144:147], v201 offset:49152
	ds_read_b128 v[148:151], v201 offset:50176
	ds_read_b128 v[152:155], v202 offset:49152
	ds_read_b128 v[156:159], v202 offset:50176
	ds_read_b128 v[160:163], v203 offset:49152
	ds_read_b128 v[164:167], v203 offset:50176
	ds_read_b128 v[168:171], v204 offset:49152
	ds_read_b128 v[172:175], v204 offset:50176
	s_nop 0
	v_lshl_add_u64 v[192:193], s[52:53], 0, v[196:197]
	global_load_lds_dwordx4 v[192:193], off
	v_lshl_add_u64 v[192:193], s[52:53], 0, v[198:199]
	s_mov_b32 m0, s1
	s_nop 0
	global_load_lds_dwordx4 v[192:193], off
	s_waitcnt vmcnt(10)
	s_barrier
	s_waitcnt lgkmcnt(0)
	s_setprio 1
	s_waitcnt lgkmcnt(0)
	v_mfma_f32_16x16x32_bf16 v[60:63], v[144:147], v[128:131], v[60:63]
	v_mfma_f32_16x16x32_bf16 v[56:59], v[144:147], v[136:139], v[56:59]
	v_mfma_f32_16x16x32_bf16 v[52:55], v[152:155], v[128:131], v[52:55]
	v_mfma_f32_16x16x32_bf16 v[48:51], v[152:155], v[136:139], v[48:51]
	v_mfma_f32_16x16x32_bf16 v[44:47], v[160:163], v[128:131], v[44:47]
	v_mfma_f32_16x16x32_bf16 v[40:43], v[160:163], v[136:139], v[40:43]
	v_mfma_f32_16x16x32_bf16 v[36:39], v[168:171], v[128:131], v[36:39]
	v_mfma_f32_16x16x32_bf16 v[32:35], v[168:171], v[136:139], v[32:35]
	v_mfma_f32_16x16x32_bf16 v[60:63], v[148:151], v[132:135], v[60:63]
	v_mfma_f32_16x16x32_bf16 v[56:59], v[148:151], v[140:143], v[56:59]
	v_mfma_f32_16x16x32_bf16 v[52:55], v[156:159], v[132:135], v[52:55]
	v_mfma_f32_16x16x32_bf16 v[48:51], v[156:159], v[140:143], v[48:51]
	v_mfma_f32_16x16x32_bf16 v[44:47], v[164:167], v[132:135], v[44:47]
	v_mfma_f32_16x16x32_bf16 v[40:43], v[164:167], v[140:143], v[40:43]
	v_mfma_f32_16x16x32_bf16 v[36:39], v[172:175], v[132:135], v[36:39]
	v_mfma_f32_16x16x32_bf16 v[32:35], v[172:175], v[140:143], v[32:35]
	s_setprio 0
	s_barrier
; #define LDA(dst, b, h) for (int m = 0; m < 4; ++m) for (int k = 0; k < 2; ++k) \
;     dst[m][k] = *reinterpret_cast<const bf16x8*>((char*)SA(b, h) + lds_byte(wr * 64 + m * 16 + fr, k * 32 + fq * 8))
; #define LDB(dst, b, h) for (int n = 0; n < 2; ++n) for (int k = 0; k < 2; ++k) \
;     dst[n][k] = *reinterpret_cast<const bf16x8*>((char*)SB(b, h) + lds_byte(wc * 32 + n * 16 + fr, k * 32 + fq * 8))
; #define WAIT_V(n) asm volatile("s_waitcnt vmcnt(" #n ")" ::: "memory")
; #define WAIT_L(n) asm volatile("s_waitcnt lgkmcnt(" #n ")" ::: "memory")
; #define BAR __builtin_amdgcn_s_barrier()
; template <class Epi>
; DEVI void gemm_phase(const Params& p, const u16* __restrict__ A, const u16* __restrict__ Bt, const int M, const int N, const int K, const int Msplit, const Epi& epi) {
;     ...
;       STAGE(SB(1, 1), Bt, bcol + HALF, t + 3);
;       WAIT_V(6); BAR; MMA(1, 1, At, B1); BAR;
;     }
;     { LDB(B0, 0, 0); LDA(At, 0, 0); STAGE(SA(1, 1), A, brow + HALF, nt - 1);
;       BAR; WAIT_L(0); MMA(0, 0, At, B0); BAR;
;       LDB(B1, 0, 1); BAR; WAIT_L(0); MMA(0, 1, At, B1); BAR;
;       LDA(At, 0, 1); WAIT_V(4); BAR; WAIT_L(0); MMA(1, 0, At, B0); MMA(1, 1, At, B1); BAR; }
	ds_read_b128 v[128:131], v200
	ds_read_b128 v[132:135], v200 offset:1024
	ds_read_b128 v[136:139], v200 offset:2048
	ds_read_b128 v[140:143], v200 offset:3072
	s_add_u32 s54, s58, 0x180
	s_addc_u32 s55, s59, 0
	s_add_i32 s52, s88, 0x1c000
	s_mov_b32 m0, s52
	v_lshl_add_u64 v[226:227], s[54:55], 0, v[196:197]
	s_add_i32 s44, s88, 0x1e000
	global_load_lds_dwordx4 v[226:227], off
	v_lshl_add_u64 v[226:227], s[54:55], 0, v[198:199]
	s_mov_b32 m0, s44
	s_nop 0
	global_load_lds_dwordx4 v[226:227], off
	s_waitcnt vmcnt(6)
	s_barrier
	s_setprio 1
	v_mfma_f32_16x16x32_bf16 v[28:31], v[144:147], v[176:179], v[28:31]
	v_mfma_f32_16x16x32_bf16 v[24:27], v[144:147], v[184:187], v[24:27]
	v_mfma_f32_16x16x32_bf16 v[20:23], v[152:155], v[176:179], v[20:23]
	v_mfma_f32_16x16x32_bf16 v[16:19], v[152:155], v[184:187], v[16:19]
	v_mfma_f32_16x16x32_bf16 v[12:15], v[160:163], v[176:179], v[12:15]
	v_mfma_f32_16x16x32_bf16 v[8:11], v[160:163], v[184:187], v[8:11]
	v_mfma_f32_16x16x32_bf16 v[4:7], v[168:171], v[176:179], v[4:7]
	v_mfma_f32_16x16x32_bf16 v[0:3], v[168:171], v[184:187], v[0:3]
	v_mfma_f32_16x16x32_bf16 v[28:31], v[148:151], v[180:183], v[28:31]
	v_mfma_f32_16x16x32_bf16 v[24:27], v[148:151], v[188:191], v[24:27]
	v_mfma_f32_16x16x32_bf16 v[20:23], v[156:159], v[180:183], v[20:23]
	v_mfma_f32_16x16x32_bf16 v[16:19], v[156:159], v[188:191], v[16:19]
	v_mfma_f32_16x16x32_bf16 v[12:15], v[164:167], v[180:183], v[12:15]
	v_mfma_f32_16x16x32_bf16 v[8:11], v[164:167], v[188:191], v[8:11]
	v_mfma_f32_16x16x32_bf16 v[4:7], v[172:175], v[180:183], v[4:7]
	v_mfma_f32_16x16x32_bf16 v[0:3], v[172:175], v[188:191], v[0:3]
	s_setprio 0
	s_add_u32 s14, s14, 0x100
	s_addc_u32 s15, s15, 0
	s_add_i32 s42, s42, 2
	s_cmp_lt_u32 s42, 12
	s_barrier
	s_cbranch_scc1 .LBB0_1104
	s_add_u32 s14, s17, 0x780
	s_addc_u32 s15, s18, 0
	s_mov_b32 m0, s47
	ds_read_b128 v[156:159], v200
	ds_read_b128 v[160:163], v200 offset:1024
	ds_read_b128 v[164:167], v200 offset:2048
	ds_read_b128 v[168:171], v200 offset:3072
	ds_read_b128 v[128:131], v201
	ds_read_b128 v[132:135], v201 offset:1024
	ds_read_b128 v[136:139], v202
	ds_read_b128 v[140:143], v202 offset:1024
	ds_read_b128 v[144:147], v203
	ds_read_b128 v[148:151], v203 offset:1024
	ds_read_b128 v[152:155], v204
	ds_read_b128 v[172:175], v204 offset:1024
	s_nop 0
	v_lshl_add_u64 v[176:177], s[14:15], 0, v[196:197]
	global_load_lds_dwordx4 v[176:177], off
	v_lshl_add_u64 v[176:177], s[14:15], 0, v[198:199]
	s_mov_b32 m0, s46
	s_nop 0
	global_load_lds_dwordx4 v[176:177], off
	s_barrier
	s_waitcnt lgkmcnt(0)
	s_setprio 1
	s_waitcnt lgkmcnt(0)
	v_mfma_f32_16x16x32_bf16 v[124:127], v[128:131], v[156:159], v[124:127]
	v_mfma_f32_16x16x32_bf16 v[120:123], v[128:131], v[164:167], v[120:123]
	v_mfma_f32_16x16x32_bf16 v[116:119], v[136:139], v[156:159], v[116:119]
	v_mfma_f32_16x16x32_bf16 v[112:115], v[136:139], v[164:167], v[112:115]
	v_mfma_f32_16x16x32_bf16 v[108:111], v[144:147], v[156:159], v[108:111]
	v_mfma_f32_16x16x32_bf16 v[104:107], v[144:147], v[164:167], v[104:107]
	v_mfma_f32_16x16x32_bf16 v[100:103], v[152:155], v[156:159], v[100:103]
	v_mfma_f32_16x16x32_bf16 v[96:99], v[152:155], v[164:167], v[96:99]
	v_mfma_f32_16x16x32_bf16 v[124:127], v[132:135], v[160:163], v[124:127]
	v_mfma_f32_16x16x32_bf16 v[176:179], v[132:135], v[168:171], v[120:123]
	v_mfma_f32_16x16x32_bf16 v[116:119], v[140:143], v[160:163], v[116:119]
	v_mfma_f32_16x16x32_bf16 v[180:183], v[140:143], v[168:171], v[112:115]
	v_mfma_f32_16x16x32_bf16 v[108:111], v[148:151], v[160:163], v[108:111]
	v_mfma_f32_16x16x32_bf16 v[184:187], v[148:151], v[168:171], v[104:107]
	v_mfma_f32_16x16x32_bf16 v[100:103], v[172:175], v[160:163], v[100:103]
	v_mfma_f32_16x16x32_bf16 v[188:191], v[172:175], v[168:171], v[96:99]
	s_setprio 0
	s_barrier
	s_nop 0
	ds_read_b128 v[96:99], v205
	ds_read_b128 v[104:107], v205 offset:1024
	ds_read_b128 v[112:115], v205 offset:2048
	ds_read_b128 v[120:123], v205 offset:3072
	s_barrier
	s_waitcnt lgkmcnt(0)
	s_setprio 1
	s_waitcnt lgkmcnt(0)
	v_mfma_f32_16x16x32_bf16 v[92:95], v[128:131], v[96:99], v[92:95]
	v_mfma_f32_16x16x32_bf16 v[88:91], v[128:131], v[112:115], v[88:91]
	v_mfma_f32_16x16x32_bf16 v[84:87], v[136:139], v[96:99], v[84:87]
	v_mfma_f32_16x16x32_bf16 v[80:83], v[136:139], v[112:115], v[80:83]
	v_mfma_f32_16x16x32_bf16 v[76:79], v[144:147], v[96:99], v[76:79]
	v_mfma_f32_16x16x32_bf16 v[72:75], v[144:147], v[112:115], v[72:75]
	v_mfma_f32_16x16x32_bf16 v[68:71], v[152:155], v[96:99], v[68:71]
	v_mfma_f32_16x16x32_bf16 v[64:67], v[152:155], v[112:115], v[64:67]
	v_mfma_f32_16x16x32_bf16 v[92:95], v[132:135], v[104:107], v[92:95]
	v_mfma_f32_16x16x32_bf16 v[128:131], v[132:135], v[120:123], v[88:91]
	v_mfma_f32_16x16x32_bf16 v[84:87], v[140:143], v[104:107], v[84:87]
	v_mfma_f32_16x16x32_bf16 v[132:135], v[140:143], v[120:123], v[80:83]
	v_mfma_f32_16x16x32_bf16 v[76:79], v[148:151], v[104:107], v[76:79]
	v_mfma_f32_16x16x32_bf16 v[136:139], v[148:151], v[120:123], v[72:75]
	v_mfma_f32_16x16x32_bf16 v[68:71], v[172:175], v[104:107], v[68:71]
	v_mfma_f32_16x16x32_bf16 v[140:143], v[172:175], v[120:123], v[64:67]
	s_setprio 0
	s_barrier
; #define LDA(dst, b, h) for (int m = 0; m < 4; ++m) for (int k = 0; k < 2; ++k) \
;     dst[m][k] = *reinterpret_cast<const bf16x8*>((char*)SA(b, h) + lds_byte(wr * 64 + m * 16 + fr, k * 32 + fq * 8))
; #define LDB(dst, b, h) for (int n = 0; n < 2; ++n) for (int k = 0; k < 2; ++k) \
;     dst[n][k] = *reinterpret_cast<const bf16x8*>((char*)SB(b, h) + lds_byte(wc * 32 + n * 16 + fr, k * 32 + fq * 8))
; #define WAIT_V(n) asm volatile("s_waitcnt vmcnt(" #n ")" ::: "memory")
; #define WAIT_L(n) asm volatile("s_waitcnt lgkmcnt(" #n ")" ::: "memory")
; #define BAR __builtin_amdgcn_s_barrier()
; #define PRO_K0(brow_, bcol_) do { STAGE(SB(0, 0), Bt, bcol_, 0); STAGE(SA(0, 0), A, brow_, 0); STAGE(SB(0, 1), Bt, (bcol_) + HALF, 0); STAGE(SA(0, 1), A, (brow_) + HALF, 0); } while (0)
; template <class Epi>
; DEVI void gemm_phase(const Params& p, const u16* __restrict__ A, const u16* __restrict__ Bt, const int M, const int N, const int K, const int Msplit, const Epi& epi) {
;     ...
;       LDA(At, 0, 1); WAIT_V(4); BAR; WAIT_L(0); MMA(1, 0, At, B0); MMA(1, 1, At, B1); BAR; }
;     { LDB(B0, 1, 0); LDA(At, 1, 0); WAIT_V(2); BAR;
;       if (have2) { const u16* Asv = A; const u16* Bsv = Bt; A = An; Bt = Bn; PRO_K0(pm * BM, pn * BM); A = Asv; Bt = Bsv; }
	s_nop 0
	ds_read_b128 v[64:67], v201 offset:16384
	ds_read_b128 v[72:75], v201 offset:17408
	ds_read_b128 v[80:83], v202 offset:16384
	ds_read_b128 v[88:91], v202 offset:17408
	ds_read_b128 v[172:175], v203 offset:16384
	ds_read_b128 v[192:195], v203 offset:17408
	ds_read_b128 v[208:211], v204 offset:16384
	ds_read_b128 v[214:217], v204 offset:17408
	s_waitcnt vmcnt(4)
	s_barrier
	s_waitcnt lgkmcnt(0)
	s_setprio 1
	s_waitcnt lgkmcnt(0)
	v_mfma_f32_16x16x32_bf16 v[60:63], v[64:67], v[156:159], v[60:63]
	v_mfma_f32_16x16x32_bf16 v[56:59], v[64:67], v[164:167], v[56:59]
	v_mfma_f32_16x16x32_bf16 v[52:55], v[80:83], v[156:159], v[52:55]
	v_mfma_f32_16x16x32_bf16 v[48:51], v[80:83], v[164:167], v[48:51]
	v_mfma_f32_16x16x32_bf16 v[44:47], v[172:175], v[156:159], v[44:47]
	v_mfma_f32_16x16x32_bf16 v[40:43], v[172:175], v[164:167], v[40:43]
	v_mfma_f32_16x16x32_bf16 v[36:39], v[208:211], v[156:159], v[36:39]
	v_mfma_f32_16x16x32_bf16 v[32:35], v[208:211], v[164:167], v[32:35]
	v_mfma_f32_16x16x32_bf16 v[60:63], v[72:75], v[160:163], v[60:63]
	v_mfma_f32_16x16x32_bf16 v[144:147], v[72:75], v[168:171], v[56:59]
	v_mfma_f32_16x16x32_bf16 v[52:55], v[88:91], v[160:163], v[52:55]
	v_mfma_f32_16x16x32_bf16 v[148:151], v[88:91], v[168:171], v[48:51]
	v_mfma_f32_16x16x32_bf16 v[44:47], v[192:195], v[160:163], v[44:47]
	v_mfma_f32_16x16x32_bf16 v[152:155], v[192:195], v[168:171], v[40:43]
	v_mfma_f32_16x16x32_bf16 v[36:39], v[214:217], v[160:163], v[36:39]
	v_mfma_f32_16x16x32_bf16 v[156:159], v[214:217], v[168:171], v[32:35]
	s_setprio 0
	s_setprio 1
	v_mfma_f32_16x16x32_bf16 v[28:31], v[64:67], v[96:99], v[28:31]
	v_mfma_f32_16x16x32_bf16 v[24:27], v[64:67], v[112:115], v[24:27]
	v_mfma_f32_16x16x32_bf16 v[20:23], v[80:83], v[96:99], v[20:23]
	v_mfma_f32_16x16x32_bf16 v[16:19], v[80:83], v[112:115], v[16:19]
	v_mfma_f32_16x16x32_bf16 v[12:15], v[172:175], v[96:99], v[12:15]
	v_mfma_f32_16x16x32_bf16 v[8:11], v[172:175], v[112:115], v[8:11]
	v_mfma_f32_16x16x32_bf16 v[4:7], v[208:211], v[96:99], v[4:7]
	v_mfma_f32_16x16x32_bf16 v[0:3], v[208:211], v[112:115], v[0:3]
	v_mfma_f32_16x16x32_bf16 v[28:31], v[72:75], v[104:107], v[28:31]
	v_mfma_f32_16x16x32_bf16 v[160:163], v[72:75], v[120:123], v[24:27]
	v_mfma_f32_16x16x32_bf16 v[20:23], v[88:91], v[104:107], v[20:23]
	v_mfma_f32_16x16x32_bf16 v[164:167], v[88:91], v[120:123], v[16:19]
	v_mfma_f32_16x16x32_bf16 v[12:15], v[192:195], v[104:107], v[12:15]
	v_mfma_f32_16x16x32_bf16 v[168:171], v[192:195], v[120:123], v[8:11]
	v_mfma_f32_16x16x32_bf16 v[4:7], v[214:217], v[104:107], v[4:7]
	v_mfma_f32_16x16x32_bf16 v[172:175], v[214:217], v[120:123], v[0:3]
	s_setprio 0
	s_barrier
	s_nop 0
	ds_read_b128 v[0:3], v206
	ds_read_b128 v[8:11], v206 offset:1024
	ds_read_b128 v[16:19], v206 offset:2048
	ds_read_b128 v[24:27], v206 offset:3072
	ds_read_b128 v[80:83], v201 offset:32768
	ds_read_b128 v[192:195], v201 offset:33792
	ds_read_b128 v[64:67], v202 offset:32768
	ds_read_b128 v[72:75], v202 offset:33792
	ds_read_b128 v[48:51], v203 offset:32768
	ds_read_b128 v[56:59], v203 offset:33792
	ds_read_b128 v[32:35], v204 offset:32768
	ds_read_b128 v[40:43], v204 offset:33792
	s_waitcnt vmcnt(2)
	v_cndmask_b32_e64 v88, 0, 1, s[12:13]
	v_cmp_ne_u32_e64 s[14:15], 1, v88
	s_andn2_b64 vcc, exec, s[12:13]
	s_barrier
	s_cbranch_vccnz .LBB0_1107
	s_lshl_b32 s12, s57, 8
	s_ashr_i32 s13, s12, 31
	s_lshl_b64 s[18:19], s[12:13], 11
	s_add_u32 s18, s2, s18
	s_addc_u32 s19, s76, s19
	s_mov_b32 m0, s45
	s_nop 0
	v_lshl_add_u64 v[88:89], s[18:19], 0, v[196:197]
	global_load_lds_dwordx4 v[88:89], off
	v_lshl_add_u64 v[88:89], s[18:19], 0, v[198:199]
	s_lshl_b32 s18, s62, 8
	s_ashr_i32 s19, s18, 31
	s_lshl_b64 s[20:21], s[18:19], 11
	s_add_u32 s20, s68, s20
	s_addc_u32 s21, s69, s21
	s_bitset1_b32 s12, 7
	s_ashr_i32 s13, s12, 31
	s_mov_b32 m0, s49
	s_lshl_b64 s[12:13], s[12:13], 11
	global_load_lds_dwordx4 v[88:89], off
	s_mov_b32 m0, s88
	v_lshl_add_u64 v[88:89], s[20:21], 0, v[196:197]
	s_add_u32 s12, s2, s12
	global_load_lds_dwordx4 v[88:89], off
	v_lshl_add_u64 v[88:89], s[20:21], 0, v[198:199]
	s_mov_b32 m0, s89
	s_addc_u32 s13, s76, s13
	global_load_lds_dwordx4 v[88:89], off
	s_mov_b32 m0, s38
	v_lshl_add_u64 v[88:89], s[12:13], 0, v[196:197]
	global_load_lds_dwordx4 v[88:89], off
	v_lshl_add_u64 v[88:89], s[12:13], 0, v[198:199]
	s_or_b32 s12, s18, 0x80
	s_ashr_i32 s13, s12, 31
	s_lshl_b64 s[12:13], s[12:13], 11
	s_add_u32 s12, s68, s12
	s_mov_b32 m0, s39
	s_addc_u32 s13, s69, s13
	global_load_lds_dwordx4 v[88:89], off
	s_mov_b32 m0, s90
	v_lshl_add_u64 v[88:89], s[12:13], 0, v[196:197]
	global_load_lds_dwordx4 v[88:89], off
	v_lshl_add_u64 v[88:89], s[12:13], 0, v[198:199]
	s_mov_b32 m0, s77
	s_nop 0
	global_load_lds_dwordx4 v[88:89], off

; #define WAIT_V(n) asm volatile("s_waitcnt vmcnt(" #n ")" ::: "memory")
; #define BAR __builtin_amdgcn_s_barrier()
; template <class Epi>
; DEVI void gemm_phase(const Params& p, const u16* __restrict__ A, const u16* __restrict__ Bt, const int M, const int N, const int K, const int Msplit, const Epi& epi) {
;     ...
;     const int brow = pm * BM, bcol = pn * BM;
;     const int slcur = brow < M ? -1 : kt0 / ((ntT / 7) & ~1);
;     int kt0n = 0, ntn = 2;
;     const bool have2 = unit_next(it + 1, pm, pn, kt0n, ntn);
;     const u16* An = A0 + (long)kt0n * BK; const u16* Bn = B0p + (long)kt0n * BK;
;     f32x4 acc[2][2][4][2] = {};
;     bf16x8 At[4][2], B0[2][2], B1[2][2];
;     if (it == 0) { WAIT_V(0); } else { if constexpr (Epi::NST == 16) WAIT_V(16); else if constexpr (Epi::NST == 32) WAIT_V(32); else WAIT_V(0); }
;     if (wr == 1) BAR;
;     BAR;
;     BAR;
;     for (int t = 0; t < nt - 2; t += 2) {
.LBB0_1715:
	s_or_b64 exec, exec, s[10:11]
	s_lshl_b32 s10, s1, 8
	s_or_b32 s16, s10, 0x80
	s_ashr_i32 s17, s16, 31
	s_lshl_b32 s24, s15, 8
	s_lshl_b64 s[36:37], s[16:17], 10
	v_mov_b32_e32 v135, 0
	s_cmp_lt_u32 s40, 3
	v_mov_b32_e32 v134, v135
	v_mov_b32_e32 v133, v135
	v_mov_b32_e32 v132, v135
	v_mov_b32_e32 v131, v135
	v_mov_b32_e32 v130, v135
	v_mov_b32_e32 v129, v135
	v_mov_b32_e32 v128, v135
	v_mov_b32_e32 v127, v135
	v_mov_b32_e32 v126, v135
	v_mov_b32_e32 v125, v135
	v_mov_b32_e32 v124, v135
	v_mov_b32_e32 v123, v135
	v_mov_b32_e32 v122, v135
	v_mov_b32_e32 v121, v135
	v_mov_b32_e32 v120, v135
	s_waitcnt vmcnt(0)
	v_mov_b32_e32 v119, v135
	v_mov_b32_e32 v118, v135
	v_mov_b32_e32 v117, v135
	v_mov_b32_e32 v116, v135
	v_mov_b32_e32 v115, v135
	v_mov_b32_e32 v114, v135
	v_mov_b32_e32 v113, v135
	v_mov_b32_e32 v112, v135
	v_mov_b32_e32 v111, v135
	v_mov_b32_e32 v110, v135
	v_mov_b32_e32 v109, v135
	v_mov_b32_e32 v108, v135
	v_mov_b32_e32 v107, v135
	v_mov_b32_e32 v106, v135
	v_mov_b32_e32 v105, v135
	v_mov_b32_e32 v104, v135
	v_mov_b32_e32 v103, v135
	v_mov_b32_e32 v102, v135
	v_mov_b32_e32 v101, v135
	v_mov_b32_e32 v100, v135
	v_mov_b32_e32 v99, v135
	v_mov_b32_e32 v98, v135
	v_mov_b32_e32 v97, v135
	v_mov_b32_e32 v96, v135
	v_mov_b32_e32 v95, v135
	s_waitcnt vmcnt(0)
	v_mov_b32_e32 v94, v135
	v_mov_b32_e32 v93, v135
	v_mov_b32_e32 v92, v135
	v_mov_b32_e32 v91, v135
	v_mov_b32_e32 v90, v135
	v_mov_b32_e32 v89, v135
	v_mov_b32_e32 v88, v135
	v_mov_b32_e32 v87, v135
	v_mov_b32_e32 v86, v135
	v_mov_b32_e32 v85, v135
	v_mov_b32_e32 v84, v135
	v_mov_b32_e32 v83, v135
	v_mov_b32_e32 v82, v135
	v_mov_b32_e32 v81, v135
	v_mov_b32_e32 v80, v135
	v_mov_b32_e32 v79, v135
	v_mov_b32_e32 v78, v135
	v_mov_b32_e32 v77, v135
	v_mov_b32_e32 v76, v135
	v_mov_b32_e32 v75, v135
	v_mov_b32_e32 v74, v135
	v_mov_b32_e32 v73, v135
	v_mov_b32_e32 v72, v135
	v_mov_b32_e32 v71, v135
	v_mov_b32_e32 v70, v135
	v_mov_b32_e32 v69, v135
	v_mov_b32_e32 v68, v135
	v_mov_b32_e32 v67, v135
	v_mov_b32_e32 v66, v135
	v_mov_b32_e32 v65, v135
	v_mov_b32_e32 v64, v135
	v_mov_b32_e32 v63, v135
	v_mov_b32_e32 v62, v135
	v_mov_b32_e32 v61, v135
	v_mov_b32_e32 v60, v135
	v_mov_b32_e32 v59, v135
	v_mov_b32_e32 v58, v135
	v_mov_b32_e32 v57, v135
	v_mov_b32_e32 v56, v135
	v_mov_b32_e32 v55, v135
	v_mov_b32_e32 v54, v135
	v_mov_b32_e32 v53, v135
	v_mov_b32_e32 v52, v135
	v_mov_b32_e32 v51, v135
	v_mov_b32_e32 v50, v135
	v_mov_b32_e32 v49, v135
	v_mov_b32_e32 v48, v135
	v_mov_b32_e32 v47, v135
	v_mov_b32_e32 v46, v135
	v_mov_b32_e32 v45, v135
	v_mov_b32_e32 v44, v135
	v_mov_b32_e32 v43, v135
	v_mov_b32_e32 v42, v135
	v_mov_b32_e32 v41, v135
	v_mov_b32_e32 v40, v135
	v_mov_b32_e32 v39, v135
	v_mov_b32_e32 v38, v135
	v_mov_b32_e32 v37, v135
	v_mov_b32_e32 v36, v135
	v_mov_b32_e32 v35, v135
	v_mov_b32_e32 v34, v135
	v_mov_b32_e32 v33, v135
	v_mov_b32_e32 v32, v135
	v_mov_b32_e32 v31, v135
	v_mov_b32_e32 v30, v135
	v_mov_b32_e32 v29, v135
	v_mov_b32_e32 v28, v135
	v_mov_b32_e32 v27, v135
	v_mov_b32_e32 v26, v135
	v_mov_b32_e32 v25, v135
	v_mov_b32_e32 v24, v135
	v_mov_b32_e32 v23, v135
	v_mov_b32_e32 v22, v135
	v_mov_b32_e32 v21, v135
	v_mov_b32_e32 v20, v135
	v_mov_b32_e32 v19, v135
	v_mov_b32_e32 v18, v135
	v_mov_b32_e32 v17, v135
	v_mov_b32_e32 v16, v135
	v_mov_b32_e32 v15, v135
	v_mov_b32_e32 v14, v135
	v_mov_b32_e32 v13, v135
	v_mov_b32_e32 v12, v135
	v_mov_b32_e32 v11, v135
	v_mov_b32_e32 v10, v135
	v_mov_b32_e32 v9, v135
	v_mov_b32_e32 v8, v135
	s_barrier
	s_barrier
	s_cbranch_scc1 .LBB0_1718
	s_add_i32 s15, s40, -2
	s_lshl_b64 s[16:17], s[36:37], 1
	s_add_u32 s20, s26, s16
	s_addc_u32 s21, s27, s17
	s_ashr_i32 s25, s24, 31
	s_lshl_b64 s[16:17], s[24:25], 11
	s_add_u32 s22, s18, s16
	s_addc_u32 s23, s19, s17
	s_ashr_i32 s11, s10, 31
	s_lshl_b64 s[16:17], s[10:11], 11
	s_add_u32 s11, s26, s16
	s_addc_u32 s25, s27, s17
	s_or_b32 s16, s24, 0x80
	s_ashr_i32 s17, s16, 31
	s_lshl_b64 s[16:17], s[16:17], 11
	s_add_u32 s41, s18, s16
	v_mov_b32_e32 v8, 0
	s_addc_u32 s52, s19, s17
	s_mov_b32 s53, 0
	s_mov_b64 s[18:19], 0
	v_mov_b32_e32 v9, v8
	v_mov_b32_e32 v10, v8
	v_mov_b32_e32 v11, v8
	v_mov_b32_e32 v12, v8
	v_mov_b32_e32 v13, v8
	v_mov_b32_e32 v14, v8
	v_mov_b32_e32 v15, v8
	v_mov_b32_e32 v16, v8
	v_mov_b32_e32 v17, v8
	v_mov_b32_e32 v18, v8
	v_mov_b32_e32 v19, v8
	v_mov_b32_e32 v20, v8
	v_mov_b32_e32 v21, v8
	v_mov_b32_e32 v22, v8
	v_mov_b32_e32 v23, v8
	v_mov_b32_e32 v24, v8
	v_mov_b32_e32 v25, v8
	v_mov_b32_e32 v26, v8
	v_mov_b32_e32 v27, v8
	v_mov_b32_e32 v28, v8
	v_mov_b32_e32 v29, v8
	v_mov_b32_e32 v30, v8
	v_mov_b32_e32 v31, v8
	v_mov_b32_e32 v32, v8
	v_mov_b32_e32 v33, v8
	v_mov_b32_e32 v34, v8
	v_mov_b32_e32 v35, v8
	v_mov_b32_e32 v36, v8
	v_mov_b32_e32 v37, v8
	v_mov_b32_e32 v38, v8
	v_mov_b32_e32 v39, v8
	v_mov_b32_e32 v40, v8
	v_mov_b32_e32 v41, v8
	v_mov_b32_e32 v42, v8
	v_mov_b32_e32 v43, v8
	v_mov_b32_e32 v44, v8
	v_mov_b32_e32 v45, v8
	v_mov_b32_e32 v46, v8
	v_mov_b32_e32 v47, v8
	v_mov_b32_e32 v48, v8
	v_mov_b32_e32 v49, v8
	v_mov_b32_e32 v50, v8
	v_mov_b32_e32 v51, v8
	v_mov_b32_e32 v52, v8
	v_mov_b32_e32 v53, v8
	v_mov_b32_e32 v54, v8
	v_mov_b32_e32 v55, v8
	v_mov_b32_e32 v56, v8
	v_mov_b32_e32 v57, v8
	v_mov_b32_e32 v58, v8
	v_mov_b32_e32 v59, v8
	v_mov_b32_e32 v60, v8
	v_mov_b32_e32 v61, v8
	v_mov_b32_e32 v62, v8
	v_mov_b32_e32 v63, v8
	v_mov_b32_e32 v64, v8
	v_mov_b32_e32 v65, v8
	v_mov_b32_e32 v66, v8
	v_mov_b32_e32 v67, v8
	v_mov_b32_e32 v68, v8
	v_mov_b32_e32 v69, v8
	v_mov_b32_e32 v70, v8
	v_mov_b32_e32 v71, v8
	v_mov_b32_e32 v72, v8
	v_mov_b32_e32 v73, v8
	v_mov_b32_e32 v74, v8
	v_mov_b32_e32 v75, v8
	v_mov_b32_e32 v76, v8
	v_mov_b32_e32 v77, v8
; #define LDA(dst, b, h) for (int m = 0; m < 4; ++m) for (int k = 0; k < 2; ++k) \
;     dst[m][k] = *reinterpret_cast<const bf16x8*>((char*)SA(b, h) + lds_byte(wr * 64 + m * 16 + fr, k * 32 + fq * 8))
; #define LDB(dst, b, h) for (int n = 0; n < 2; ++n) for (int k = 0; k < 2; ++k) \
;     dst[n][k] = *reinterpret_cast<const bf16x8*>((char*)SB(b, h) + lds_byte(wc * 32 + n * 16 + fr, k * 32 + fq * 8))
; #define WAIT_V(n) asm volatile("s_waitcnt vmcnt(" #n ")" ::: "memory")
; #define WAIT_L(n) asm volatile("s_waitcnt lgkmcnt(" #n ")" ::: "memory")
; #define BAR __builtin_amdgcn_s_barrier()
; #define SCHED __builtin_amdgcn_sched_barrier(0)
; template <class Epi>
; DEVI void gemm_phase(const Params& p, const u16* __restrict__ A, const u16* __restrict__ Bt, const int M, const int N, const int K, const int Msplit, const Epi& epi) {
;     ...
;     f32x4 acc[2][2][4][2] = {};
;     bf16x8 At[4][2], B0[2][2], B1[2][2];
;     if (it == 0) { WAIT_V(0); } else { if constexpr (Epi::NST == 16) WAIT_V(16); else if constexpr (Epi::NST == 32) WAIT_V(32); else WAIT_V(0); }
;     if (wr == 1) BAR;
;     BAR;
;     BAR;
;     for (int t = 0; t < nt - 2; t += 2) {
;       LDB(B0, 0, 0); SCHED; LDA(At, 0, 0); STAGE(SA(1, 1), A, brow + HALF, t + 1);
;       WAIT_L(8); BAR; WAIT_L(0); MMA(0, 0, At, B0); BAR; SCHED;
;       LDB(B1, 0, 1); STAGE(SB(0, 0), Bt, bcol, t + 2);
;       BAR; WAIT_L(0); MMA(0, 1, At, B1); BAR;
	v_mov_b32_e32 v78, v8
	v_mov_b32_e32 v79, v8
	v_mov_b32_e32 v80, v8
	v_mov_b32_e32 v81, v8
	v_mov_b32_e32 v82, v8
	v_mov_b32_e32 v83, v8
	v_mov_b32_e32 v84, v8
	v_mov_b32_e32 v85, v8
	v_mov_b32_e32 v86, v8
	v_mov_b32_e32 v87, v8
	v_mov_b32_e32 v88, v8
	v_mov_b32_e32 v89, v8
	v_mov_b32_e32 v90, v8
	v_mov_b32_e32 v91, v8
	v_mov_b32_e32 v92, v8
	v_mov_b32_e32 v93, v8
	v_mov_b32_e32 v94, v8
	v_mov_b32_e32 v95, v8
	v_mov_b32_e32 v96, v8
	v_mov_b32_e32 v97, v8
	v_mov_b32_e32 v98, v8
	v_mov_b32_e32 v99, v8
	v_mov_b32_e32 v100, v8
	v_mov_b32_e32 v101, v8
	v_mov_b32_e32 v102, v8
	v_mov_b32_e32 v103, v8
	v_mov_b32_e32 v104, v8
	v_mov_b32_e32 v105, v8
	v_mov_b32_e32 v106, v8
	v_mov_b32_e32 v107, v8
	v_mov_b32_e32 v108, v8
	v_mov_b32_e32 v109, v8
	v_mov_b32_e32 v110, v8
	v_mov_b32_e32 v111, v8
	v_mov_b32_e32 v112, v8
	v_mov_b32_e32 v113, v8
	v_mov_b32_e32 v114, v8
	v_mov_b32_e32 v115, v8
	v_mov_b32_e32 v116, v8
	v_mov_b32_e32 v117, v8
	v_mov_b32_e32 v118, v8
	v_mov_b32_e32 v119, v8
	v_mov_b32_e32 v120, v8
	v_mov_b32_e32 v121, v8
	v_mov_b32_e32 v122, v8
	v_mov_b32_e32 v123, v8
	v_mov_b32_e32 v124, v8
	v_mov_b32_e32 v125, v8
	v_mov_b32_e32 v126, v8
	v_mov_b32_e32 v127, v8
	v_mov_b32_e32 v128, v8
	v_mov_b32_e32 v129, v8
	v_mov_b32_e32 v130, v8
	v_mov_b32_e32 v131, v8
	v_mov_b32_e32 v132, v8
	v_mov_b32_e32 v133, v8
	v_mov_b32_e32 v134, v8
	v_mov_b32_e32 v135, v8
	v_add_u32_e32 v148, v226, v232
	ds_read_b128 v[136:139], v148
	ds_read_b128 v[140:143], v148 offset:1024
	ds_read_b128 v[144:147], v148 offset:2048
	ds_read_b128 v[148:151], v148 offset:3072
.LBB0_1717:
	s_add_u32 s17, s20, s18
	s_addc_u32 s44, s21, s19
	s_add_u32 s38, s17, 0x80
	v_add_u32_e32 v202, v249, v245
	v_add_u32_e32 v203, v250, v246
	v_add_u32_e32 v204, v250, v247
	v_add_u32_e32 v205, v250, v248
	s_addc_u32 s39, s44, 0
	s_add_i32 s16, s78, 0
	ds_read_b128 v[152:155], v202
	ds_read_b128 v[156:159], v202 offset:1024
	ds_read_b128 v[160:163], v203
	ds_read_b128 v[164:167], v203 offset:1024
	ds_read_b128 v[168:171], v204
	ds_read_b128 v[172:175], v204 offset:1024
	ds_read_b128 v[176:179], v205
	ds_read_b128 v[180:183], v205 offset:1024
	s_add_i32 m0, s16, 0xc000
	v_lshl_add_u64 v[184:185], s[38:39], 0, v[208:209]
	global_load_lds_dwordx4 v[184:185], off
	v_lshl_add_u64 v[184:185], s[38:39], 0, v[210:211]
	s_add_i32 m0, s16, 0xe000
	s_nop 0
	global_load_lds_dwordx4 v[184:185], off
	s_waitcnt lgkmcnt(8)
	s_barrier
	s_waitcnt lgkmcnt(0)
	s_setprio 1
	s_waitcnt lgkmcnt(0)
	v_mfma_f32_16x16x32_bf16 v[132:135], v[136:139], v[152:155], v[132:135]
	v_mfma_f32_16x16x32_bf16 v[128:131], v[144:147], v[152:155], v[128:131]
	v_mfma_f32_16x16x32_bf16 v[124:127], v[136:139], v[160:163], v[124:127]
	v_mfma_f32_16x16x32_bf16 v[120:123], v[144:147], v[160:163], v[120:123]
	v_mfma_f32_16x16x32_bf16 v[116:119], v[136:139], v[168:171], v[116:119]
	v_mfma_f32_16x16x32_bf16 v[112:115], v[144:147], v[168:171], v[112:115]
	v_mfma_f32_16x16x32_bf16 v[108:111], v[136:139], v[176:179], v[108:111]
	v_mfma_f32_16x16x32_bf16 v[104:107], v[144:147], v[176:179], v[104:107]
	v_mfma_f32_16x16x32_bf16 v[132:135], v[140:143], v[156:159], v[132:135]
	v_mfma_f32_16x16x32_bf16 v[128:131], v[148:151], v[156:159], v[128:131]
	v_mfma_f32_16x16x32_bf16 v[124:127], v[140:143], v[164:167], v[124:127]
	v_mfma_f32_16x16x32_bf16 v[120:123], v[148:151], v[164:167], v[120:123]
	v_mfma_f32_16x16x32_bf16 v[116:119], v[140:143], v[172:175], v[116:119]
	v_mfma_f32_16x16x32_bf16 v[112:115], v[148:151], v[172:175], v[112:115]
	v_mfma_f32_16x16x32_bf16 v[108:111], v[140:143], v[180:183], v[108:111]
	v_mfma_f32_16x16x32_bf16 v[104:107], v[148:151], v[180:183], v[104:107]
	s_setprio 0
	s_barrier
	s_add_i32 s53, s53, 2
	s_add_u32 s45, s22, s18
	s_addc_u32 s46, s23, s19
	s_add_u32 s38, s45, 0x100
	v_add_u32_e32 v196, v227, v232
	s_addc_u32 s39, s46, 0
	ds_read_b128 v[184:187], v196
	ds_read_b128 v[188:191], v196 offset:1024
	ds_read_b128 v[192:195], v196 offset:2048
	ds_read_b128 v[196:199], v196 offset:3072
	s_add_i32 m0, s16, 0x10000
	v_lshl_add_u64 v[200:201], s[38:39], 0, v[208:209]
	global_load_lds_dwordx4 v[200:201], off
	v_lshl_add_u64 v[200:201], s[38:39], 0, v[210:211]
	s_add_i32 m0, s16, 0x12000
	s_nop 0
	global_load_lds_dwordx4 v[200:201], off
	s_barrier
	s_waitcnt lgkmcnt(0)
	s_setprio 1
	s_waitcnt lgkmcnt(0)
	v_mfma_f32_16x16x32_bf16 v[100:103], v[184:187], v[152:155], v[100:103]
	v_mfma_f32_16x16x32_bf16 v[96:99], v[192:195], v[152:155], v[96:99]
	v_mfma_f32_16x16x32_bf16 v[92:95], v[184:187], v[160:163], v[92:95]
	v_mfma_f32_16x16x32_bf16 v[88:91], v[192:195], v[160:163], v[88:91]
	v_mfma_f32_16x16x32_bf16 v[84:87], v[184:187], v[168:171], v[84:87]
	v_mfma_f32_16x16x32_bf16 v[80:83], v[192:195], v[168:171], v[80:83]
	v_mfma_f32_16x16x32_bf16 v[76:79], v[184:187], v[176:179], v[76:79]
	v_mfma_f32_16x16x32_bf16 v[72:75], v[192:195], v[176:179], v[72:75]
	v_mfma_f32_16x16x32_bf16 v[100:103], v[188:191], v[156:159], v[100:103]
	v_mfma_f32_16x16x32_bf16 v[96:99], v[196:199], v[156:159], v[96:99]
	v_mfma_f32_16x16x32_bf16 v[92:95], v[188:191], v[164:167], v[92:95]
	v_mfma_f32_16x16x32_bf16 v[88:91], v[196:199], v[164:167], v[88:91]
	v_mfma_f32_16x16x32_bf16 v[84:87], v[188:191], v[172:175], v[84:87]
	v_mfma_f32_16x16x32_bf16 v[80:83], v[196:199], v[172:175], v[80:83]
	v_mfma_f32_16x16x32_bf16 v[76:79], v[188:191], v[180:183], v[76:79]
	v_mfma_f32_16x16x32_bf16 v[72:75], v[196:199], v[180:183], v[72:75]
	s_setprio 0
	s_add_u32 s47, s11, s18
	s_addc_u32 s54, s25, s19
	s_add_u32 s38, s47, 0x100
	s_addc_u32 s39, s54, 0
	s_mov_b32 m0, s16
	s_barrier
; #define LDA(dst, b, h) for (int m = 0; m < 4; ++m) for (int k = 0; k < 2; ++k) \
;     dst[m][k] = *reinterpret_cast<const bf16x8*>((char*)SA(b, h) + lds_byte(wr * 64 + m * 16 + fr, k * 32 + fq * 8))
; #define LDB(dst, b, h) for (int n = 0; n < 2; ++n) for (int k = 0; k < 2; ++k) \
;     dst[n][k] = *reinterpret_cast<const bf16x8*>((char*)SB(b, h) + lds_byte(wc * 32 + n * 16 + fr, k * 32 + fq * 8))
; #define WAIT_V(n) asm volatile("s_waitcnt vmcnt(" #n ")" ::: "memory")
; #define WAIT_L(n) asm volatile("s_waitcnt lgkmcnt(" #n ")" ::: "memory")
; #define BAR __builtin_amdgcn_s_barrier()
; #define SCHED __builtin_amdgcn_sched_barrier(0)
; template <class Epi>
; DEVI void gemm_phase(const Params& p, const u16* __restrict__ A, const u16* __restrict__ Bt, const int M, const int N, const int K, const int Msplit, const Epi& epi) {
;     ...
;       LDA(At, 0, 1); STAGE(SA(0, 0), A, brow, t + 2);
;       BAR; WAIT_L(0); MMA(1, 0, At, B0); BAR; SCHED;
;       STAGE(SB(0, 1), Bt, bcol + HALF, t + 2);
;       WAIT_V(6); BAR; MMA(1, 1, At, B1); BAR;
;       LDB(B0, 1, 0); SCHED; LDA(At, 1, 0); STAGE(SA(0, 1), A, brow + HALF, t + 2);
;       WAIT_L(8); BAR; WAIT_L(0); MMA(0, 0, At, B0); BAR; SCHED;
	ds_read_b128 v[152:155], v202 offset:16384
	ds_read_b128 v[156:159], v202 offset:17408
	ds_read_b128 v[160:163], v203 offset:16384
	ds_read_b128 v[164:167], v203 offset:17408
	ds_read_b128 v[168:171], v204 offset:16384
	ds_read_b128 v[172:175], v204 offset:17408
	ds_read_b128 v[176:179], v205 offset:16384
	ds_read_b128 v[180:183], v205 offset:17408
	s_nop 0
	v_lshl_add_u64 v[200:201], s[38:39], 0, v[208:209]
	global_load_lds_dwordx4 v[200:201], off
	v_lshl_add_u64 v[200:201], s[38:39], 0, v[210:211]
	s_add_i32 m0, s16, 0x2000
	s_nop 0
	global_load_lds_dwordx4 v[200:201], off
	s_waitcnt vmcnt(10)
	s_barrier
	s_waitcnt lgkmcnt(0)
	s_setprio 1
	s_waitcnt lgkmcnt(0)
	v_mfma_f32_16x16x32_bf16 v[68:71], v[136:139], v[152:155], v[68:71]
	v_mfma_f32_16x16x32_bf16 v[64:67], v[144:147], v[152:155], v[64:67]
	v_mfma_f32_16x16x32_bf16 v[60:63], v[136:139], v[160:163], v[60:63]
	v_mfma_f32_16x16x32_bf16 v[56:59], v[144:147], v[160:163], v[56:59]
	v_mfma_f32_16x16x32_bf16 v[52:55], v[136:139], v[168:171], v[52:55]
	v_mfma_f32_16x16x32_bf16 v[48:51], v[144:147], v[168:171], v[48:51]
	v_mfma_f32_16x16x32_bf16 v[44:47], v[136:139], v[176:179], v[44:47]
	v_mfma_f32_16x16x32_bf16 v[40:43], v[144:147], v[176:179], v[40:43]
	v_mfma_f32_16x16x32_bf16 v[68:71], v[140:143], v[156:159], v[68:71]
	v_mfma_f32_16x16x32_bf16 v[64:67], v[148:151], v[156:159], v[64:67]
	v_mfma_f32_16x16x32_bf16 v[60:63], v[140:143], v[164:167], v[60:63]
	v_mfma_f32_16x16x32_bf16 v[56:59], v[148:151], v[164:167], v[56:59]
	v_mfma_f32_16x16x32_bf16 v[52:55], v[140:143], v[172:175], v[52:55]
	v_mfma_f32_16x16x32_bf16 v[48:51], v[148:151], v[172:175], v[48:51]
	v_mfma_f32_16x16x32_bf16 v[44:47], v[140:143], v[180:183], v[44:47]
	v_mfma_f32_16x16x32_bf16 v[40:43], v[148:151], v[180:183], v[40:43]
	s_setprio 0
	s_barrier
	v_add_u32_e32 v148, v228, v232
	ds_read_b128 v[136:139], v148
	ds_read_b128 v[140:143], v148 offset:1024
	ds_read_b128 v[144:147], v148 offset:2048
	ds_read_b128 v[148:151], v148 offset:3072
	s_add_u32 s55, s41, s18
	s_addc_u32 s56, s52, s19
	s_add_u32 s38, s55, 0x100
	s_addc_u32 s39, s56, 0
	s_add_i32 m0, s16, 0x14000
	v_lshl_add_u64 v[214:215], s[38:39], 0, v[208:209]
	global_load_lds_dwordx4 v[214:215], off
	v_lshl_add_u64 v[214:215], s[38:39], 0, v[210:211]
	s_add_i32 m0, s16, 0x16000
	s_nop 0
	global_load_lds_dwordx4 v[214:215], off
	s_waitcnt vmcnt(6)
	s_barrier
	s_setprio 1
	v_mfma_f32_16x16x32_bf16 v[36:39], v[184:187], v[152:155], v[36:39]
	v_mfma_f32_16x16x32_bf16 v[32:35], v[192:195], v[152:155], v[32:35]
	v_mfma_f32_16x16x32_bf16 v[28:31], v[184:187], v[160:163], v[28:31]
	v_mfma_f32_16x16x32_bf16 v[24:27], v[192:195], v[160:163], v[24:27]
	v_mfma_f32_16x16x32_bf16 v[20:23], v[184:187], v[168:171], v[20:23]
	v_mfma_f32_16x16x32_bf16 v[16:19], v[192:195], v[168:171], v[16:19]
	v_mfma_f32_16x16x32_bf16 v[12:15], v[184:187], v[176:179], v[12:15]
	v_mfma_f32_16x16x32_bf16 v[8:11], v[192:195], v[176:179], v[8:11]
	v_mfma_f32_16x16x32_bf16 v[36:39], v[188:191], v[156:159], v[36:39]
	v_mfma_f32_16x16x32_bf16 v[32:35], v[196:199], v[156:159], v[32:35]
	v_mfma_f32_16x16x32_bf16 v[28:31], v[188:191], v[164:167], v[28:31]
	v_mfma_f32_16x16x32_bf16 v[24:27], v[196:199], v[164:167], v[24:27]
	v_mfma_f32_16x16x32_bf16 v[20:23], v[188:191], v[172:175], v[20:23]
	v_mfma_f32_16x16x32_bf16 v[16:19], v[196:199], v[172:175], v[16:19]
	v_mfma_f32_16x16x32_bf16 v[12:15], v[188:191], v[180:183], v[12:15]
	v_mfma_f32_16x16x32_bf16 v[8:11], v[196:199], v[180:183], v[8:11]
	s_setprio 0
	s_barrier
	s_add_u32 s38, s17, 0x100
	s_addc_u32 s39, s44, 0
	ds_read_b128 v[152:155], v202 offset:32768
	ds_read_b128 v[156:159], v202 offset:33792
	ds_read_b128 v[160:163], v203 offset:32768
	ds_read_b128 v[164:167], v203 offset:33792
	ds_read_b128 v[168:171], v204 offset:32768
	ds_read_b128 v[172:175], v204 offset:33792
	ds_read_b128 v[176:179], v205 offset:32768
	ds_read_b128 v[180:183], v205 offset:33792
	s_add_i32 m0, s16, 0x4000
	v_lshl_add_u64 v[184:185], s[38:39], 0, v[208:209]
	global_load_lds_dwordx4 v[184:185], off
	v_lshl_add_u64 v[184:185], s[38:39], 0, v[210:211]
	s_add_i32 m0, s16, 0x6000
	s_nop 0
	global_load_lds_dwordx4 v[184:185], off
	s_waitcnt lgkmcnt(8)
	s_barrier
	s_waitcnt lgkmcnt(0)
	s_setprio 1
	s_waitcnt lgkmcnt(0)
	v_mfma_f32_16x16x32_bf16 v[132:135], v[136:139], v[152:155], v[132:135]
	v_mfma_f32_16x16x32_bf16 v[128:131], v[144:147], v[152:155], v[128:131]
	v_mfma_f32_16x16x32_bf16 v[124:127], v[136:139], v[160:163], v[124:127]
	v_mfma_f32_16x16x32_bf16 v[120:123], v[144:147], v[160:163], v[120:123]
	v_mfma_f32_16x16x32_bf16 v[116:119], v[136:139], v[168:171], v[116:119]
	v_mfma_f32_16x16x32_bf16 v[112:115], v[144:147], v[168:171], v[112:115]
	v_mfma_f32_16x16x32_bf16 v[108:111], v[136:139], v[176:179], v[108:111]
	v_mfma_f32_16x16x32_bf16 v[104:107], v[144:147], v[176:179], v[104:107]
	v_mfma_f32_16x16x32_bf16 v[132:135], v[140:143], v[156:159], v[132:135]
	v_mfma_f32_16x16x32_bf16 v[128:131], v[148:151], v[156:159], v[128:131]
	v_mfma_f32_16x16x32_bf16 v[124:127], v[140:143], v[164:167], v[124:127]
	v_mfma_f32_16x16x32_bf16 v[120:123], v[148:151], v[164:167], v[120:123]
	v_mfma_f32_16x16x32_bf16 v[116:119], v[140:143], v[172:175], v[116:119]
	v_mfma_f32_16x16x32_bf16 v[112:115], v[148:151], v[172:175], v[112:115]
	v_mfma_f32_16x16x32_bf16 v[108:111], v[140:143], v[180:183], v[108:111]
	v_mfma_f32_16x16x32_bf16 v[104:107], v[148:151], v[180:183], v[104:107]
	s_setprio 0
	s_barrier
; #define LDA(dst, b, h) for (int m = 0; m < 4; ++m) for (int k = 0; k < 2; ++k) \
;     dst[m][k] = *reinterpret_cast<const bf16x8*>((char*)SA(b, h) + lds_byte(wr * 64 + m * 16 + fr, k * 32 + fq * 8))
; #define LDB(dst, b, h) for (int n = 0; n < 2; ++n) for (int k = 0; k < 2; ++k) \
;     dst[n][k] = *reinterpret_cast<const bf16x8*>((char*)SB(b, h) + lds_byte(wc * 32 + n * 16 + fr, k * 32 + fq * 8))
; #define WAIT_V(n) asm volatile("s_waitcnt vmcnt(" #n ")" ::: "memory")
; #define WAIT_L(n) asm volatile("s_waitcnt lgkmcnt(" #n ")" ::: "memory")
; #define BAR __builtin_amdgcn_s_barrier()
; #define SCHED __builtin_amdgcn_sched_barrier(0)
; template <class Epi>
; DEVI void gemm_phase(const Params& p, const u16* __restrict__ A, const u16* __restrict__ Bt, const int M, const int N, const int K, const int Msplit, const Epi& epi) {
;     ...
;       LDB(B1, 1, 1); STAGE(SB(1, 0), Bt, bcol, t + 3);
;       BAR; WAIT_L(0); MMA(0, 1, At, B1); BAR;
;       LDA(At, 1, 1); STAGE(SA(1, 0), A, brow, t + 3);
;       BAR; WAIT_L(0); MMA(1, 0, At, B0); BAR; SCHED;
;       STAGE(SB(1, 1), Bt, bcol + HALF, t + 3);
;       WAIT_V(6); BAR; MMA(1, 1, At, B1); BAR;
;     }
	s_add_u32 s38, s45, 0x180
	v_add_u32_e32 v196, v229, v232
	s_addc_u32 s39, s46, 0
	ds_read_b128 v[184:187], v196
	ds_read_b128 v[188:191], v196 offset:1024
	ds_read_b128 v[192:195], v196 offset:2048
	ds_read_b128 v[196:199], v196 offset:3072
	s_add_i32 m0, s16, 0x18000
	v_lshl_add_u64 v[200:201], s[38:39], 0, v[208:209]
	global_load_lds_dwordx4 v[200:201], off
	v_lshl_add_u64 v[200:201], s[38:39], 0, v[210:211]
	s_add_i32 m0, s16, 0x1a000
	s_nop 0
	global_load_lds_dwordx4 v[200:201], off
	s_barrier
	s_waitcnt lgkmcnt(0)
	s_setprio 1
	s_waitcnt lgkmcnt(0)
	v_mfma_f32_16x16x32_bf16 v[100:103], v[184:187], v[152:155], v[100:103]
	v_mfma_f32_16x16x32_bf16 v[96:99], v[192:195], v[152:155], v[96:99]
	v_mfma_f32_16x16x32_bf16 v[92:95], v[184:187], v[160:163], v[92:95]
	v_mfma_f32_16x16x32_bf16 v[88:91], v[192:195], v[160:163], v[88:91]
	v_mfma_f32_16x16x32_bf16 v[84:87], v[184:187], v[168:171], v[84:87]
	v_mfma_f32_16x16x32_bf16 v[80:83], v[192:195], v[168:171], v[80:83]
	v_mfma_f32_16x16x32_bf16 v[76:79], v[184:187], v[176:179], v[76:79]
	v_mfma_f32_16x16x32_bf16 v[72:75], v[192:195], v[176:179], v[72:75]
	v_mfma_f32_16x16x32_bf16 v[100:103], v[188:191], v[156:159], v[100:103]
	v_mfma_f32_16x16x32_bf16 v[96:99], v[196:199], v[156:159], v[96:99]
	v_mfma_f32_16x16x32_bf16 v[92:95], v[188:191], v[164:167], v[92:95]
	v_mfma_f32_16x16x32_bf16 v[88:91], v[196:199], v[164:167], v[88:91]
	v_mfma_f32_16x16x32_bf16 v[84:87], v[188:191], v[172:175], v[84:87]
	v_mfma_f32_16x16x32_bf16 v[80:83], v[196:199], v[172:175], v[80:83]
	v_mfma_f32_16x16x32_bf16 v[76:79], v[188:191], v[180:183], v[76:79]
	v_mfma_f32_16x16x32_bf16 v[72:75], v[196:199], v[180:183], v[72:75]
	s_setprio 0
	s_add_u32 s38, s47, 0x180
	s_addc_u32 s39, s54, 0
	s_barrier
	ds_read_b128 v[152:155], v202 offset:49152
	ds_read_b128 v[156:159], v202 offset:50176
	ds_read_b128 v[160:163], v203 offset:49152
	ds_read_b128 v[164:167], v203 offset:50176
	ds_read_b128 v[168:171], v204 offset:49152
	ds_read_b128 v[172:175], v204 offset:50176
	ds_read_b128 v[176:179], v205 offset:49152
	ds_read_b128 v[180:183], v205 offset:50176
	s_add_i32 m0, s16, 0x8000
	v_lshl_add_u64 v[200:201], s[38:39], 0, v[208:209]
	global_load_lds_dwordx4 v[200:201], off
	v_lshl_add_u64 v[200:201], s[38:39], 0, v[210:211]
	s_add_i32 m0, s16, 0xa000
	s_nop 0
	global_load_lds_dwordx4 v[200:201], off
	s_waitcnt vmcnt(10)
	s_barrier
	s_waitcnt lgkmcnt(0)
	s_setprio 1
	s_waitcnt lgkmcnt(0)
	v_mfma_f32_16x16x32_bf16 v[68:71], v[136:139], v[152:155], v[68:71]
	v_mfma_f32_16x16x32_bf16 v[64:67], v[144:147], v[152:155], v[64:67]
	v_mfma_f32_16x16x32_bf16 v[60:63], v[136:139], v[160:163], v[60:63]
	v_mfma_f32_16x16x32_bf16 v[56:59], v[144:147], v[160:163], v[56:59]
	v_mfma_f32_16x16x32_bf16 v[52:55], v[136:139], v[168:171], v[52:55]
	v_mfma_f32_16x16x32_bf16 v[48:51], v[144:147], v[168:171], v[48:51]
	v_mfma_f32_16x16x32_bf16 v[44:47], v[136:139], v[176:179], v[44:47]
	v_mfma_f32_16x16x32_bf16 v[40:43], v[144:147], v[176:179], v[40:43]
	v_mfma_f32_16x16x32_bf16 v[68:71], v[140:143], v[156:159], v[68:71]
	v_mfma_f32_16x16x32_bf16 v[64:67], v[148:151], v[156:159], v[64:67]
	v_mfma_f32_16x16x32_bf16 v[60:63], v[140:143], v[164:167], v[60:63]
	v_mfma_f32_16x16x32_bf16 v[56:59], v[148:151], v[164:167], v[56:59]
	v_mfma_f32_16x16x32_bf16 v[52:55], v[140:143], v[172:175], v[52:55]
	v_mfma_f32_16x16x32_bf16 v[48:51], v[148:151], v[172:175], v[48:51]
	v_mfma_f32_16x16x32_bf16 v[44:47], v[140:143], v[180:183], v[44:47]
	v_mfma_f32_16x16x32_bf16 v[40:43], v[148:151], v[180:183], v[40:43]
	s_setprio 0
	s_barrier
	v_add_u32_e32 v148, v226, v232
	ds_read_b128 v[136:139], v148
	ds_read_b128 v[140:143], v148 offset:1024
	ds_read_b128 v[144:147], v148 offset:2048
	ds_read_b128 v[148:151], v148 offset:3072
	s_add_u32 s38, s55, 0x180
	s_addc_u32 s39, s56, 0
	s_add_i32 m0, s16, 0x1c000
	v_lshl_add_u64 v[214:215], s[38:39], 0, v[208:209]
	global_load_lds_dwordx4 v[214:215], off
	v_lshl_add_u64 v[214:215], s[38:39], 0, v[210:211]
	s_add_i32 m0, s16, 0x1e000
	s_nop 0
	global_load_lds_dwordx4 v[214:215], off
	s_waitcnt vmcnt(6)
	s_barrier
	s_setprio 1
	v_mfma_f32_16x16x32_bf16 v[36:39], v[184:187], v[152:155], v[36:39]
	v_mfma_f32_16x16x32_bf16 v[32:35], v[192:195], v[152:155], v[32:35]
	v_mfma_f32_16x16x32_bf16 v[28:31], v[184:187], v[160:163], v[28:31]
	v_mfma_f32_16x16x32_bf16 v[24:27], v[192:195], v[160:163], v[24:27]
	v_mfma_f32_16x16x32_bf16 v[20:23], v[184:187], v[168:171], v[20:23]
	v_mfma_f32_16x16x32_bf16 v[16:19], v[192:195], v[168:171], v[16:19]
	v_mfma_f32_16x16x32_bf16 v[12:15], v[184:187], v[176:179], v[12:15]
	v_mfma_f32_16x16x32_bf16 v[8:11], v[192:195], v[176:179], v[8:11]
	v_mfma_f32_16x16x32_bf16 v[36:39], v[188:191], v[156:159], v[36:39]
	v_mfma_f32_16x16x32_bf16 v[32:35], v[196:199], v[156:159], v[32:35]
	v_mfma_f32_16x16x32_bf16 v[28:31], v[188:191], v[164:167], v[28:31]
	v_mfma_f32_16x16x32_bf16 v[24:27], v[196:199], v[164:167], v[24:27]
	v_mfma_f32_16x16x32_bf16 v[20:23], v[188:191], v[172:175], v[20:23]
	v_mfma_f32_16x16x32_bf16 v[16:19], v[196:199], v[172:175], v[16:19]
	v_mfma_f32_16x16x32_bf16 v[12:15], v[188:191], v[180:183], v[12:15]
	v_mfma_f32_16x16x32_bf16 v[8:11], v[196:199], v[180:183], v[8:11]
	s_setprio 0
	s_add_u32 s18, s18, 0x100
	s_addc_u32 s19, s19, 0
	s_cmp_ge_i32 s53, s15
	s_barrier
	s_cbranch_scc0 .LBB0_1717

; #define LDA(dst, b, h) for (int m = 0; m < 4; ++m) for (int k = 0; k < 2; ++k) \
;     dst[m][k] = *reinterpret_cast<const bf16x8*>((char*)SA(b, h) + lds_byte(wr * 64 + m * 16 + fr, k * 32 + fq * 8))
; #define LDB(dst, b, h) for (int n = 0; n < 2; ++n) for (int k = 0; k < 2; ++k) \
;     dst[n][k] = *reinterpret_cast<const bf16x8*>((char*)SB(b, h) + lds_byte(wc * 32 + n * 16 + fr, k * 32 + fq * 8))
; #define WAIT_V(n) asm volatile("s_waitcnt vmcnt(" #n ")" ::: "memory")
; #define WAIT_L(n) asm volatile("s_waitcnt lgkmcnt(" #n ")" ::: "memory")
; #define BAR __builtin_amdgcn_s_barrier()
; #define SCHED __builtin_amdgcn_sched_barrier(0)
; template <class Epi>
; DEVI void gemm_phase(const Params& p, const u16* __restrict__ A, const u16* __restrict__ Bt, const int M, const int N, const int K, const int Msplit, const Epi& epi) {
;     ...
;     f32x4 acc[2][2][4][2] = {};
;     bf16x8 At[4][2], B0[2][2], B1[2][2];
;     if (it == 0) { WAIT_V(0); } else { if constexpr (Epi::NST == 16) WAIT_V(16); else if constexpr (Epi::NST == 32) WAIT_V(32); else WAIT_V(0); }
;     if (wr == 1) BAR;
;     BAR;
;     BAR;
;     for (int t = 0; t < nt - 2; t += 2) {
;       LDB(B0, 0, 0); SCHED; LDA(At, 0, 0); STAGE(SA(1, 1), A, brow + HALF, t + 1);
;       WAIT_L(8); BAR; WAIT_L(0); MMA(0, 0, At, B0); BAR; SCHED;
.LBB0_1993:
	s_or_b64 exec, exec, s[14:15]
	s_lshl_b32 s20, s20, 8
	s_or_b32 s90, s20, 0x80
	s_lshl_b32 s22, s16, 8
	s_lshl_b64 s[14:15], s[90:91], 11
	s_add_u32 s42, s68, s14
	s_addc_u32 s43, s69, s15
	s_ashr_i32 s23, s22, 31
	s_lshl_b64 s[14:15], s[22:23], 11
	s_add_u32 s23, s1, s14
	s_mov_b32 s21, s91
	s_addc_u32 s48, s2, s15
	s_lshl_b64 s[14:15], s[20:21], 11
	s_add_u32 s21, s68, s14
	s_addc_u32 s49, s69, s15
	s_or_b32 s38, s22, 0x80
	s_ashr_i32 s39, s38, 31
	s_lshl_b64 s[38:39], s[38:39], 11
	s_add_u32 s52, s1, s38
	s_addc_u32 s53, s2, s39
	s_add_u32 s56, s42, 0x100
	s_addc_u32 s57, s43, 0
	v_readlane_b32 s16, v254, 50
	s_add_u32 s62, s16, s14
	v_readlane_b32 s14, v254, 51
	v_mov_b32_e32 v0, 0
	s_addc_u32 s63, s14, s15
	s_mov_b64 s[14:15], 0
	s_mov_b32 s76, -2
	v_mov_b32_e32 v1, v0
	v_mov_b32_e32 v2, v0
	v_mov_b32_e32 v3, v0
	v_mov_b32_e32 v4, v0
	v_mov_b32_e32 v5, v0
	v_mov_b32_e32 v6, v0
	v_mov_b32_e32 v7, v0
	v_mov_b32_e32 v8, v0
	v_mov_b32_e32 v9, v0
	v_mov_b32_e32 v10, v0
	v_mov_b32_e32 v11, v0
	v_mov_b32_e32 v12, v0
	v_mov_b32_e32 v13, v0
	v_mov_b32_e32 v14, v0
	v_mov_b32_e32 v15, v0
	v_mov_b32_e32 v16, v0
	v_mov_b32_e32 v17, v0
	v_mov_b32_e32 v18, v0
	v_mov_b32_e32 v19, v0
	v_mov_b32_e32 v20, v0
	v_mov_b32_e32 v21, v0
	v_mov_b32_e32 v22, v0
	v_mov_b32_e32 v23, v0
	v_mov_b32_e32 v24, v0
	v_mov_b32_e32 v25, v0
	v_mov_b32_e32 v26, v0
	v_mov_b32_e32 v27, v0
	v_mov_b32_e32 v28, v0
	v_mov_b32_e32 v29, v0
	v_mov_b32_e32 v30, v0
	v_mov_b32_e32 v31, v0
	v_mov_b32_e32 v32, v0
	v_mov_b32_e32 v33, v0
	v_mov_b32_e32 v34, v0
	v_mov_b32_e32 v35, v0
	v_mov_b32_e32 v36, v0
	v_mov_b32_e32 v37, v0
	v_mov_b32_e32 v38, v0
	v_mov_b32_e32 v39, v0
	v_mov_b32_e32 v40, v0
	v_mov_b32_e32 v41, v0
	v_mov_b32_e32 v42, v0
	v_mov_b32_e32 v43, v0
	v_mov_b32_e32 v44, v0
	v_mov_b32_e32 v45, v0
	v_mov_b32_e32 v46, v0
	v_mov_b32_e32 v47, v0
	v_mov_b32_e32 v48, v0
	v_mov_b32_e32 v49, v0
	v_mov_b32_e32 v50, v0
	v_mov_b32_e32 v51, v0
	v_mov_b32_e32 v52, v0
	v_mov_b32_e32 v53, v0
	v_mov_b32_e32 v54, v0
	v_mov_b32_e32 v55, v0
	v_mov_b32_e32 v56, v0
	v_mov_b32_e32 v57, v0
	v_mov_b32_e32 v58, v0
	v_mov_b32_e32 v59, v0
	v_mov_b32_e32 v60, v0
	v_mov_b32_e32 v61, v0
	v_mov_b32_e32 v62, v0
	v_mov_b32_e32 v63, v0
	v_mov_b32_e32 v64, v0
	v_mov_b32_e32 v65, v0
	v_mov_b32_e32 v66, v0
	v_mov_b32_e32 v67, v0
	v_mov_b32_e32 v68, v0
	v_mov_b32_e32 v69, v0
	v_mov_b32_e32 v70, v0
	v_mov_b32_e32 v71, v0
	v_mov_b32_e32 v72, v0
	v_mov_b32_e32 v73, v0
	v_mov_b32_e32 v74, v0
	v_mov_b32_e32 v75, v0
	v_mov_b32_e32 v76, v0
	v_mov_b32_e32 v77, v0
	v_mov_b32_e32 v78, v0
	v_mov_b32_e32 v79, v0
	v_mov_b32_e32 v80, v0
	v_mov_b32_e32 v81, v0
	v_mov_b32_e32 v82, v0
	v_mov_b32_e32 v83, v0
	v_mov_b32_e32 v84, v0
	v_mov_b32_e32 v85, v0
	v_mov_b32_e32 v86, v0
	v_mov_b32_e32 v87, v0
	v_mov_b32_e32 v88, v0
	v_mov_b32_e32 v89, v0
	v_mov_b32_e32 v90, v0
	v_mov_b32_e32 v91, v0
	v_mov_b32_e32 v92, v0
	v_mov_b32_e32 v93, v0
	v_mov_b32_e32 v94, v0
	v_mov_b32_e32 v95, v0
	v_mov_b32_e32 v96, v0
	v_mov_b32_e32 v97, v0
	v_mov_b32_e32 v98, v0
	v_mov_b32_e32 v99, v0
	v_mov_b32_e32 v100, v0
	v_mov_b32_e32 v101, v0
	v_mov_b32_e32 v102, v0
	v_mov_b32_e32 v103, v0
	v_mov_b32_e32 v104, v0
	v_mov_b32_e32 v105, v0
	v_mov_b32_e32 v106, v0
	v_mov_b32_e32 v107, v0
	v_mov_b32_e32 v108, v0
	v_mov_b32_e32 v109, v0
	v_mov_b32_e32 v110, v0
	v_mov_b32_e32 v111, v0
	v_mov_b32_e32 v112, v0
	v_mov_b32_e32 v113, v0
	v_mov_b32_e32 v114, v0
	v_mov_b32_e32 v115, v0
	v_mov_b32_e32 v116, v0
	v_mov_b32_e32 v117, v0
	v_mov_b32_e32 v118, v0
	v_mov_b32_e32 v119, v0
	v_mov_b32_e32 v120, v0
	v_mov_b32_e32 v121, v0
	v_mov_b32_e32 v122, v0
	v_mov_b32_e32 v123, v0
	v_mov_b32_e32 v124, v0
	v_mov_b32_e32 v125, v0
	v_mov_b32_e32 v126, v0
	v_mov_b32_e32 v127, v0
	s_barrier
	s_barrier
	ds_read_b128 v[128:131], v198
	ds_read_b128 v[132:135], v198 offset:1024
	ds_read_b128 v[136:139], v198 offset:2048
	ds_read_b128 v[140:143], v198 offset:3072
.LBB0_1994:
	s_add_u32 s16, s62, s14
	s_addc_u32 s39, s63, s15
	s_add_u32 s38, s16, 0x80
	s_addc_u32 s39, s39, 0
	s_add_i32 s47, s19, 0xc000
	ds_read_b128 v[144:147], v199
	ds_read_b128 v[148:151], v199 offset:1024
	ds_read_b128 v[152:155], v200
	ds_read_b128 v[156:159], v200 offset:1024
	ds_read_b128 v[160:163], v201
	ds_read_b128 v[164:167], v201 offset:1024
	ds_read_b128 v[168:171], v202
	ds_read_b128 v[172:175], v202 offset:1024
	s_mov_b32 m0, s47
	v_lshl_add_u64 v[176:177], s[38:39], 0, v[212:213]
	s_add_i32 s46, s19, 0xe000
	global_load_lds_dwordx4 v[176:177], off
	v_lshl_add_u64 v[176:177], s[38:39], 0, v[196:197]
	s_mov_b32 m0, s46
	s_nop 0
	global_load_lds_dwordx4 v[176:177], off
	s_waitcnt lgkmcnt(8)
	s_barrier
	s_waitcnt lgkmcnt(0)
	s_setprio 1
	s_waitcnt lgkmcnt(0)
	v_mfma_f32_16x16x32_bf16 v[124:127], v[128:131], v[144:147], v[124:127]
	v_mfma_f32_16x16x32_bf16 v[120:123], v[136:139], v[144:147], v[120:123]
	v_mfma_f32_16x16x32_bf16 v[116:119], v[128:131], v[152:155], v[116:119]
	v_mfma_f32_16x16x32_bf16 v[112:115], v[136:139], v[152:155], v[112:115]
	v_mfma_f32_16x16x32_bf16 v[108:111], v[128:131], v[160:163], v[108:111]
	v_mfma_f32_16x16x32_bf16 v[104:107], v[136:139], v[160:163], v[104:107]
	v_mfma_f32_16x16x32_bf16 v[100:103], v[128:131], v[168:171], v[100:103]
	v_mfma_f32_16x16x32_bf16 v[96:99], v[136:139], v[168:171], v[96:99]
	v_mfma_f32_16x16x32_bf16 v[124:127], v[132:135], v[148:151], v[124:127]
	v_mfma_f32_16x16x32_bf16 v[120:123], v[140:143], v[148:151], v[120:123]
	v_mfma_f32_16x16x32_bf16 v[116:119], v[132:135], v[156:159], v[116:119]
	v_mfma_f32_16x16x32_bf16 v[112:115], v[140:143], v[156:159], v[112:115]
	v_mfma_f32_16x16x32_bf16 v[108:111], v[132:135], v[164:167], v[108:111]
	v_mfma_f32_16x16x32_bf16 v[104:107], v[140:143], v[164:167], v[104:107]
	v_mfma_f32_16x16x32_bf16 v[100:103], v[132:135], v[172:175], v[100:103]
	v_mfma_f32_16x16x32_bf16 v[96:99], v[140:143], v[172:175], v[96:99]
	s_setprio 0
	s_barrier
; #define LDA(dst, b, h) for (int m = 0; m < 4; ++m) for (int k = 0; k < 2; ++k) \
;     dst[m][k] = *reinterpret_cast<const bf16x8*>((char*)SA(b, h) + lds_byte(wr * 64 + m * 16 + fr, k * 32 + fq * 8))
; #define LDB(dst, b, h) for (int n = 0; n < 2; ++n) for (int k = 0; k < 2; ++k) \
;     dst[n][k] = *reinterpret_cast<const bf16x8*>((char*)SB(b, h) + lds_byte(wc * 32 + n * 16 + fr, k * 32 + fq * 8))
; #define WAIT_V(n) asm volatile("s_waitcnt vmcnt(" #n ")" ::: "memory")
; #define WAIT_L(n) asm volatile("s_waitcnt lgkmcnt(" #n ")" ::: "memory")
; #define BAR __builtin_amdgcn_s_barrier()
; #define SCHED __builtin_amdgcn_sched_barrier(0)
; template <class Epi>
; DEVI void gemm_phase(const Params& p, const u16* __restrict__ A, const u16* __restrict__ Bt, const int M, const int N, const int K, const int Msplit, const Epi& epi) {
;     ...
;       LDB(B1, 0, 1); STAGE(SB(0, 0), Bt, bcol, t + 2);
;       BAR; WAIT_L(0); MMA(0, 1, At, B1); BAR;
;       LDA(At, 0, 1); STAGE(SA(0, 0), A, brow, t + 2);
;       BAR; WAIT_L(0); MMA(1, 0, At, B0); BAR; SCHED;
;       STAGE(SB(0, 1), Bt, bcol + HALF, t + 2);
;       WAIT_V(6); BAR; MMA(1, 1, At, B1); BAR;
;       LDB(B0, 1, 0); SCHED; LDA(At, 1, 0); STAGE(SA(0, 1), A, brow + HALF, t + 2);
	s_add_u32 s54, s23, s14
	s_addc_u32 s55, s48, s15
	s_add_u32 s38, s54, 0x100
	s_addc_u32 s39, s55, 0
	s_add_i32 s16, s19, 0x10000
	ds_read_b128 v[176:179], v203
	ds_read_b128 v[180:183], v203 offset:1024
	ds_read_b128 v[184:187], v203 offset:2048
	ds_read_b128 v[188:191], v203 offset:3072
	s_mov_b32 m0, s16
	v_lshl_add_u64 v[192:193], s[38:39], 0, v[212:213]
	s_add_i32 s89, s19, 0x12000
	global_load_lds_dwordx4 v[192:193], off
	v_lshl_add_u64 v[192:193], s[38:39], 0, v[196:197]
	s_mov_b32 m0, s89
	s_nop 0
	global_load_lds_dwordx4 v[192:193], off
	s_barrier
	s_waitcnt lgkmcnt(0)
	s_setprio 1
	s_waitcnt lgkmcnt(0)
	v_mfma_f32_16x16x32_bf16 v[92:95], v[176:179], v[144:147], v[92:95]
	v_mfma_f32_16x16x32_bf16 v[88:91], v[184:187], v[144:147], v[88:91]
	v_mfma_f32_16x16x32_bf16 v[84:87], v[176:179], v[152:155], v[84:87]
	v_mfma_f32_16x16x32_bf16 v[80:83], v[184:187], v[152:155], v[80:83]
	v_mfma_f32_16x16x32_bf16 v[76:79], v[176:179], v[160:163], v[76:79]
	v_mfma_f32_16x16x32_bf16 v[72:75], v[184:187], v[160:163], v[72:75]
	v_mfma_f32_16x16x32_bf16 v[68:71], v[176:179], v[168:171], v[68:71]
	v_mfma_f32_16x16x32_bf16 v[64:67], v[184:187], v[168:171], v[64:67]
	v_mfma_f32_16x16x32_bf16 v[92:95], v[180:183], v[148:151], v[92:95]
	v_mfma_f32_16x16x32_bf16 v[88:91], v[188:191], v[148:151], v[88:91]
	v_mfma_f32_16x16x32_bf16 v[84:87], v[180:183], v[156:159], v[84:87]
	v_mfma_f32_16x16x32_bf16 v[80:83], v[188:191], v[156:159], v[80:83]
	v_mfma_f32_16x16x32_bf16 v[76:79], v[180:183], v[164:167], v[76:79]
	v_mfma_f32_16x16x32_bf16 v[72:75], v[188:191], v[164:167], v[72:75]
	v_mfma_f32_16x16x32_bf16 v[68:71], v[180:183], v[172:175], v[68:71]
	v_mfma_f32_16x16x32_bf16 v[64:67], v[188:191], v[172:175], v[64:67]
	s_setprio 0
	s_add_u32 s58, s21, s14
	s_addc_u32 s59, s49, s15
	s_add_u32 s38, s58, 0x100
	s_addc_u32 s39, s59, 0
	s_mov_b32 m0, s19
	s_barrier
	ds_read_b128 v[144:147], v199 offset:16384
	ds_read_b128 v[148:151], v199 offset:17408
	ds_read_b128 v[152:155], v200 offset:16384
	ds_read_b128 v[156:159], v200 offset:17408
	ds_read_b128 v[160:163], v201 offset:16384
	ds_read_b128 v[164:167], v201 offset:17408
	ds_read_b128 v[168:171], v202 offset:16384
	ds_read_b128 v[172:175], v202 offset:17408
	s_nop 0
	v_lshl_add_u64 v[192:193], s[38:39], 0, v[212:213]
	global_load_lds_dwordx4 v[192:193], off
	v_lshl_add_u64 v[192:193], s[38:39], 0, v[196:197]
	s_mov_b32 m0, s24
	s_nop 0
	global_load_lds_dwordx4 v[192:193], off
	s_waitcnt vmcnt(10)
	s_barrier
	s_waitcnt lgkmcnt(0)
	s_setprio 1
	s_waitcnt lgkmcnt(0)
	v_mfma_f32_16x16x32_bf16 v[60:63], v[128:131], v[144:147], v[60:63]
	v_mfma_f32_16x16x32_bf16 v[56:59], v[136:139], v[144:147], v[56:59]
	v_mfma_f32_16x16x32_bf16 v[52:55], v[128:131], v[152:155], v[52:55]
	v_mfma_f32_16x16x32_bf16 v[48:51], v[136:139], v[152:155], v[48:51]
	v_mfma_f32_16x16x32_bf16 v[44:47], v[128:131], v[160:163], v[44:47]
	v_mfma_f32_16x16x32_bf16 v[40:43], v[136:139], v[160:163], v[40:43]
	v_mfma_f32_16x16x32_bf16 v[36:39], v[128:131], v[168:171], v[36:39]
	v_mfma_f32_16x16x32_bf16 v[32:35], v[136:139], v[168:171], v[32:35]
	v_mfma_f32_16x16x32_bf16 v[60:63], v[132:135], v[148:151], v[60:63]
	v_mfma_f32_16x16x32_bf16 v[56:59], v[140:143], v[148:151], v[56:59]
	v_mfma_f32_16x16x32_bf16 v[52:55], v[132:135], v[156:159], v[52:55]
	v_mfma_f32_16x16x32_bf16 v[48:51], v[140:143], v[156:159], v[48:51]
	v_mfma_f32_16x16x32_bf16 v[44:47], v[132:135], v[164:167], v[44:47]
	v_mfma_f32_16x16x32_bf16 v[40:43], v[140:143], v[164:167], v[40:43]
	v_mfma_f32_16x16x32_bf16 v[36:39], v[132:135], v[172:175], v[36:39]
	v_mfma_f32_16x16x32_bf16 v[32:35], v[140:143], v[172:175], v[32:35]
	s_setprio 0
	s_barrier
	ds_read_b128 v[128:131], v204
	ds_read_b128 v[132:135], v204 offset:1024
	ds_read_b128 v[136:139], v204 offset:2048
	ds_read_b128 v[140:143], v204 offset:3072
	s_add_u32 s90, s52, s14
	s_addc_u32 vcc_lo, s53, s15
	s_add_u32 s44, s90, 0x100
	s_addc_u32 s45, vcc_lo, 0
	s_add_i32 s38, s19, 0x14000
	s_mov_b32 m0, s38
	v_lshl_add_u64 v[226:227], s[44:45], 0, v[212:213]
	s_add_i32 s39, s19, 0x16000
	global_load_lds_dwordx4 v[226:227], off
	v_lshl_add_u64 v[226:227], s[44:45], 0, v[196:197]
	s_mov_b32 m0, s39
	s_nop 0
	global_load_lds_dwordx4 v[226:227], off
	s_waitcnt vmcnt(6)
	s_barrier
	s_setprio 1
	v_mfma_f32_16x16x32_bf16 v[28:31], v[176:179], v[144:147], v[28:31]
	v_mfma_f32_16x16x32_bf16 v[24:27], v[184:187], v[144:147], v[24:27]
	v_mfma_f32_16x16x32_bf16 v[20:23], v[176:179], v[152:155], v[20:23]
	v_mfma_f32_16x16x32_bf16 v[16:19], v[184:187], v[152:155], v[16:19]
	v_mfma_f32_16x16x32_bf16 v[12:15], v[176:179], v[160:163], v[12:15]
	v_mfma_f32_16x16x32_bf16 v[8:11], v[184:187], v[160:163], v[8:11]
	v_mfma_f32_16x16x32_bf16 v[4:7], v[176:179], v[168:171], v[4:7]
	v_mfma_f32_16x16x32_bf16 v[0:3], v[184:187], v[168:171], v[0:3]
	v_mfma_f32_16x16x32_bf16 v[28:31], v[180:183], v[148:151], v[28:31]
	v_mfma_f32_16x16x32_bf16 v[24:27], v[188:191], v[148:151], v[24:27]
	v_mfma_f32_16x16x32_bf16 v[20:23], v[180:183], v[156:159], v[20:23]
	v_mfma_f32_16x16x32_bf16 v[16:19], v[188:191], v[156:159], v[16:19]
	v_mfma_f32_16x16x32_bf16 v[12:15], v[180:183], v[164:167], v[12:15]
	v_mfma_f32_16x16x32_bf16 v[8:11], v[188:191], v[164:167], v[8:11]
	v_mfma_f32_16x16x32_bf16 v[4:7], v[180:183], v[172:175], v[4:7]
	v_mfma_f32_16x16x32_bf16 v[0:3], v[188:191], v[172:175], v[0:3]
	s_setprio 0
	s_barrier
; #define LDA(dst, b, h) for (int m = 0; m < 4; ++m) for (int k = 0; k < 2; ++k) \
;     dst[m][k] = *reinterpret_cast<const bf16x8*>((char*)SA(b, h) + lds_byte(wr * 64 + m * 16 + fr, k * 32 + fq * 8))
; #define LDB(dst, b, h) for (int n = 0; n < 2; ++n) for (int k = 0; k < 2; ++k) \
;     dst[n][k] = *reinterpret_cast<const bf16x8*>((char*)SB(b, h) + lds_byte(wc * 32 + n * 16 + fr, k * 32 + fq * 8))
; #define WAIT_L(n) asm volatile("s_waitcnt lgkmcnt(" #n ")" ::: "memory")
; #define BAR __builtin_amdgcn_s_barrier()
; #define SCHED __builtin_amdgcn_sched_barrier(0)
; template <class Epi>
; DEVI void gemm_phase(const Params& p, const u16* __restrict__ A, const u16* __restrict__ Bt, const int M, const int N, const int K, const int Msplit, const Epi& epi) {
;     ...
;       LDB(B0, 1, 0); SCHED; LDA(At, 1, 0); STAGE(SA(0, 1), A, brow + HALF, t + 2);
;       WAIT_L(8); BAR; WAIT_L(0); MMA(0, 0, At, B0); BAR; SCHED;
;       LDB(B1, 1, 1); STAGE(SB(1, 0), Bt, bcol, t + 3);
;       BAR; WAIT_L(0); MMA(0, 1, At, B1); BAR;
;       LDA(At, 1, 1); STAGE(SA(1, 0), A, brow, t + 3);
;       BAR; WAIT_L(0); MMA(1, 0, At, B0); BAR; SCHED;
	s_add_u32 s44, s56, s14
	s_addc_u32 s45, s57, s15
	s_mov_b32 m0, s25
	ds_read_b128 v[144:147], v199 offset:32768
	ds_read_b128 v[148:151], v199 offset:33792
	ds_read_b128 v[152:155], v200 offset:32768
	ds_read_b128 v[156:159], v200 offset:33792
	ds_read_b128 v[160:163], v201 offset:32768
	ds_read_b128 v[164:167], v201 offset:33792
	ds_read_b128 v[168:171], v202 offset:32768
	ds_read_b128 v[172:175], v202 offset:33792
	s_nop 0
	v_lshl_add_u64 v[176:177], s[44:45], 0, v[212:213]
	global_load_lds_dwordx4 v[176:177], off
	v_lshl_add_u64 v[176:177], s[44:45], 0, v[196:197]
	s_mov_b32 m0, s26
	s_nop 0
	global_load_lds_dwordx4 v[176:177], off
	s_waitcnt lgkmcnt(8)
	s_barrier
	s_waitcnt lgkmcnt(0)
	s_setprio 1
	s_waitcnt lgkmcnt(0)
	v_mfma_f32_16x16x32_bf16 v[124:127], v[128:131], v[144:147], v[124:127]
	v_mfma_f32_16x16x32_bf16 v[120:123], v[136:139], v[144:147], v[120:123]
	v_mfma_f32_16x16x32_bf16 v[116:119], v[128:131], v[152:155], v[116:119]
	v_mfma_f32_16x16x32_bf16 v[112:115], v[136:139], v[152:155], v[112:115]
	v_mfma_f32_16x16x32_bf16 v[108:111], v[128:131], v[160:163], v[108:111]
	v_mfma_f32_16x16x32_bf16 v[104:107], v[136:139], v[160:163], v[104:107]
	v_mfma_f32_16x16x32_bf16 v[100:103], v[128:131], v[168:171], v[100:103]
	v_mfma_f32_16x16x32_bf16 v[96:99], v[136:139], v[168:171], v[96:99]
	v_mfma_f32_16x16x32_bf16 v[124:127], v[132:135], v[148:151], v[124:127]
	v_mfma_f32_16x16x32_bf16 v[120:123], v[140:143], v[148:151], v[120:123]
	v_mfma_f32_16x16x32_bf16 v[116:119], v[132:135], v[156:159], v[116:119]
	v_mfma_f32_16x16x32_bf16 v[112:115], v[140:143], v[156:159], v[112:115]
	v_mfma_f32_16x16x32_bf16 v[108:111], v[132:135], v[164:167], v[108:111]
	v_mfma_f32_16x16x32_bf16 v[104:107], v[140:143], v[164:167], v[104:107]
	v_mfma_f32_16x16x32_bf16 v[100:103], v[132:135], v[172:175], v[100:103]
	v_mfma_f32_16x16x32_bf16 v[96:99], v[140:143], v[172:175], v[96:99]
	s_setprio 0
	s_barrier
	s_add_u32 s44, s54, 0x180
	s_addc_u32 s45, s55, 0
	s_add_i32 s88, s19, 0x18000
	ds_read_b128 v[176:179], v205
	ds_read_b128 v[180:183], v205 offset:1024
	ds_read_b128 v[184:187], v205 offset:2048
	ds_read_b128 v[188:191], v205 offset:3072
	s_mov_b32 m0, s88
	v_lshl_add_u64 v[192:193], s[44:45], 0, v[212:213]
	s_add_i32 s77, s19, 0x1a000
	global_load_lds_dwordx4 v[192:193], off
	v_lshl_add_u64 v[192:193], s[44:45], 0, v[196:197]
	s_mov_b32 m0, s77
	s_nop 0
	global_load_lds_dwordx4 v[192:193], off
	s_barrier
	s_waitcnt lgkmcnt(0)
	s_setprio 1
	s_waitcnt lgkmcnt(0)
	v_mfma_f32_16x16x32_bf16 v[92:95], v[176:179], v[144:147], v[92:95]
	v_mfma_f32_16x16x32_bf16 v[88:91], v[184:187], v[144:147], v[88:91]
	v_mfma_f32_16x16x32_bf16 v[84:87], v[176:179], v[152:155], v[84:87]
	v_mfma_f32_16x16x32_bf16 v[80:83], v[184:187], v[152:155], v[80:83]
	v_mfma_f32_16x16x32_bf16 v[76:79], v[176:179], v[160:163], v[76:79]
	v_mfma_f32_16x16x32_bf16 v[72:75], v[184:187], v[160:163], v[72:75]
	v_mfma_f32_16x16x32_bf16 v[68:71], v[176:179], v[168:171], v[68:71]
	v_mfma_f32_16x16x32_bf16 v[64:67], v[184:187], v[168:171], v[64:67]
	v_mfma_f32_16x16x32_bf16 v[92:95], v[180:183], v[148:151], v[92:95]
	v_mfma_f32_16x16x32_bf16 v[88:91], v[188:191], v[148:151], v[88:91]
	v_mfma_f32_16x16x32_bf16 v[84:87], v[180:183], v[156:159], v[84:87]
	v_mfma_f32_16x16x32_bf16 v[80:83], v[188:191], v[156:159], v[80:83]
	v_mfma_f32_16x16x32_bf16 v[76:79], v[180:183], v[164:167], v[76:79]
	v_mfma_f32_16x16x32_bf16 v[72:75], v[188:191], v[164:167], v[72:75]
	v_mfma_f32_16x16x32_bf16 v[68:71], v[180:183], v[172:175], v[68:71]
	v_mfma_f32_16x16x32_bf16 v[64:67], v[188:191], v[172:175], v[64:67]
	s_setprio 0
	s_add_u32 s44, s58, 0x180
	s_addc_u32 s45, s59, 0
	s_mov_b32 m0, s27
	s_barrier
	ds_read_b128 v[144:147], v199 offset:49152
	ds_read_b128 v[148:151], v199 offset:50176
	ds_read_b128 v[152:155], v200 offset:49152
	ds_read_b128 v[156:159], v200 offset:50176
	ds_read_b128 v[160:163], v201 offset:49152
	ds_read_b128 v[164:167], v201 offset:50176
	ds_read_b128 v[168:171], v202 offset:49152
	ds_read_b128 v[172:175], v202 offset:50176
	s_nop 0
	v_lshl_add_u64 v[192:193], s[44:45], 0, v[212:213]
	global_load_lds_dwordx4 v[192:193], off
	v_lshl_add_u64 v[192:193], s[44:45], 0, v[196:197]
	s_mov_b32 m0, s36
	s_nop 0
	global_load_lds_dwordx4 v[192:193], off
	s_waitcnt vmcnt(10)
	s_barrier
	s_waitcnt lgkmcnt(0)
	s_setprio 1
	s_waitcnt lgkmcnt(0)
	v_mfma_f32_16x16x32_bf16 v[60:63], v[128:131], v[144:147], v[60:63]
	v_mfma_f32_16x16x32_bf16 v[56:59], v[136:139], v[144:147], v[56:59]
	v_mfma_f32_16x16x32_bf16 v[52:55], v[128:131], v[152:155], v[52:55]
	v_mfma_f32_16x16x32_bf16 v[48:51], v[136:139], v[152:155], v[48:51]
	v_mfma_f32_16x16x32_bf16 v[44:47], v[128:131], v[160:163], v[44:47]
	v_mfma_f32_16x16x32_bf16 v[40:43], v[136:139], v[160:163], v[40:43]
	v_mfma_f32_16x16x32_bf16 v[36:39], v[128:131], v[168:171], v[36:39]
	v_mfma_f32_16x16x32_bf16 v[32:35], v[136:139], v[168:171], v[32:35]
	v_mfma_f32_16x16x32_bf16 v[60:63], v[132:135], v[148:151], v[60:63]
	v_mfma_f32_16x16x32_bf16 v[56:59], v[140:143], v[148:151], v[56:59]
	v_mfma_f32_16x16x32_bf16 v[52:55], v[132:135], v[156:159], v[52:55]
	v_mfma_f32_16x16x32_bf16 v[48:51], v[140:143], v[156:159], v[48:51]
	v_mfma_f32_16x16x32_bf16 v[44:47], v[132:135], v[164:167], v[44:47]
	v_mfma_f32_16x16x32_bf16 v[40:43], v[140:143], v[164:167], v[40:43]
	v_mfma_f32_16x16x32_bf16 v[36:39], v[132:135], v[172:175], v[36:39]
	v_mfma_f32_16x16x32_bf16 v[32:35], v[140:143], v[172:175], v[32:35]
	s_setprio 0
	s_barrier
; #define LDA(dst, b, h) for (int m = 0; m < 4; ++m) for (int k = 0; k < 2; ++k) \
;     dst[m][k] = *reinterpret_cast<const bf16x8*>((char*)SA(b, h) + lds_byte(wr * 64 + m * 16 + fr, k * 32 + fq * 8))
; #define LDB(dst, b, h) for (int n = 0; n < 2; ++n) for (int k = 0; k < 2; ++k) \
;     dst[n][k] = *reinterpret_cast<const bf16x8*>((char*)SB(b, h) + lds_byte(wc * 32 + n * 16 + fr, k * 32 + fq * 8))
; #define WAIT_V(n) asm volatile("s_waitcnt vmcnt(" #n ")" ::: "memory")
; #define WAIT_L(n) asm volatile("s_waitcnt lgkmcnt(" #n ")" ::: "memory")
; #define BAR __builtin_amdgcn_s_barrier()
; template <class Epi>
; DEVI void gemm_phase(const Params& p, const u16* __restrict__ A, const u16* __restrict__ Bt, const int M, const int N, const int K, const int Msplit, const Epi& epi) {
;     ...
;       STAGE(SB(1, 1), Bt, bcol + HALF, t + 3);
;       WAIT_V(6); BAR; MMA(1, 1, At, B1); BAR;
;     }
;     { LDB(B0, 0, 0); LDA(At, 0, 0); STAGE(SA(1, 1), A, brow + HALF, nt - 1);
;       BAR; WAIT_L(0); MMA(0, 0, At, B0); BAR;
;       LDB(B1, 0, 1); BAR; WAIT_L(0); MMA(0, 1, At, B1); BAR;
;       LDA(At, 0, 1); WAIT_V(4); BAR; WAIT_L(0); MMA(1, 0, At, B0); MMA(1, 1, At, B1); BAR; }
	ds_read_b128 v[128:131], v198
	ds_read_b128 v[132:135], v198 offset:1024
	ds_read_b128 v[136:139], v198 offset:2048
	ds_read_b128 v[140:143], v198 offset:3072
	s_add_u32 s54, s90, 0x180
	s_addc_u32 s55, vcc_lo, 0
	s_add_i32 s44, s19, 0x1c000
	s_mov_b32 m0, s44
	v_lshl_add_u64 v[226:227], s[54:55], 0, v[212:213]
	s_add_i32 s45, s19, 0x1e000
	global_load_lds_dwordx4 v[226:227], off
	v_lshl_add_u64 v[226:227], s[54:55], 0, v[196:197]
	s_mov_b32 m0, s45
	s_nop 0
	global_load_lds_dwordx4 v[226:227], off
	s_waitcnt vmcnt(6)
	s_barrier
	s_setprio 1
	v_mfma_f32_16x16x32_bf16 v[28:31], v[176:179], v[144:147], v[28:31]
	v_mfma_f32_16x16x32_bf16 v[24:27], v[184:187], v[144:147], v[24:27]
	v_mfma_f32_16x16x32_bf16 v[20:23], v[176:179], v[152:155], v[20:23]
	v_mfma_f32_16x16x32_bf16 v[16:19], v[184:187], v[152:155], v[16:19]
	v_mfma_f32_16x16x32_bf16 v[12:15], v[176:179], v[160:163], v[12:15]
	v_mfma_f32_16x16x32_bf16 v[8:11], v[184:187], v[160:163], v[8:11]
	v_mfma_f32_16x16x32_bf16 v[4:7], v[176:179], v[168:171], v[4:7]
	v_mfma_f32_16x16x32_bf16 v[0:3], v[184:187], v[168:171], v[0:3]
	v_mfma_f32_16x16x32_bf16 v[28:31], v[180:183], v[148:151], v[28:31]
	v_mfma_f32_16x16x32_bf16 v[24:27], v[188:191], v[148:151], v[24:27]
	v_mfma_f32_16x16x32_bf16 v[20:23], v[180:183], v[156:159], v[20:23]
	v_mfma_f32_16x16x32_bf16 v[16:19], v[188:191], v[156:159], v[16:19]
	v_mfma_f32_16x16x32_bf16 v[12:15], v[180:183], v[164:167], v[12:15]
	v_mfma_f32_16x16x32_bf16 v[8:11], v[188:191], v[164:167], v[8:11]
	v_mfma_f32_16x16x32_bf16 v[4:7], v[180:183], v[172:175], v[4:7]
	v_mfma_f32_16x16x32_bf16 v[0:3], v[188:191], v[172:175], v[0:3]
	s_setprio 0
	s_add_u32 s14, s14, 0x100
	s_addc_u32 s15, s15, 0
	s_add_i32 s76, s76, 2
	s_cmp_lt_u32 s76, 12
	s_barrier
	s_cbranch_scc1 .LBB0_1994
	s_add_u32 s14, s42, 0x780
	s_addc_u32 s15, s43, 0
	s_mov_b32 m0, s47
	ds_read_b128 v[156:159], v198
	ds_read_b128 v[160:163], v198 offset:1024
	ds_read_b128 v[164:167], v198 offset:2048
	ds_read_b128 v[168:171], v198 offset:3072
	ds_read_b128 v[128:131], v199
	ds_read_b128 v[132:135], v199 offset:1024
	ds_read_b128 v[136:139], v200
	ds_read_b128 v[140:143], v200 offset:1024
	ds_read_b128 v[144:147], v201
	ds_read_b128 v[148:151], v201 offset:1024
	ds_read_b128 v[152:155], v202
	ds_read_b128 v[172:175], v202 offset:1024
	s_nop 0
	v_lshl_add_u64 v[176:177], s[14:15], 0, v[212:213]
	global_load_lds_dwordx4 v[176:177], off
	v_lshl_add_u64 v[176:177], s[14:15], 0, v[196:197]
	s_mov_b32 m0, s46
	s_nop 0
	global_load_lds_dwordx4 v[176:177], off
	s_barrier
	s_waitcnt lgkmcnt(0)
	s_setprio 1
	s_waitcnt lgkmcnt(0)
	v_mfma_f32_16x16x32_bf16 v[124:127], v[156:159], v[128:131], v[124:127]
	v_mfma_f32_16x16x32_bf16 v[120:123], v[164:167], v[128:131], v[120:123]
	v_mfma_f32_16x16x32_bf16 v[116:119], v[156:159], v[136:139], v[116:119]
	v_mfma_f32_16x16x32_bf16 v[112:115], v[164:167], v[136:139], v[112:115]
	v_mfma_f32_16x16x32_bf16 v[108:111], v[156:159], v[144:147], v[108:111]
	v_mfma_f32_16x16x32_bf16 v[104:107], v[164:167], v[144:147], v[104:107]
	v_mfma_f32_16x16x32_bf16 v[100:103], v[156:159], v[152:155], v[100:103]
	v_mfma_f32_16x16x32_bf16 v[96:99], v[164:167], v[152:155], v[96:99]
	v_mfma_f32_16x16x32_bf16 v[124:127], v[160:163], v[132:135], v[124:127]
	v_mfma_f32_16x16x32_bf16 v[176:179], v[168:171], v[132:135], v[120:123]
	v_mfma_f32_16x16x32_bf16 v[116:119], v[160:163], v[140:143], v[116:119]
	v_mfma_f32_16x16x32_bf16 v[180:183], v[168:171], v[140:143], v[112:115]
	v_mfma_f32_16x16x32_bf16 v[108:111], v[160:163], v[148:151], v[108:111]
	v_mfma_f32_16x16x32_bf16 v[184:187], v[168:171], v[148:151], v[104:107]
	v_mfma_f32_16x16x32_bf16 v[100:103], v[160:163], v[172:175], v[100:103]
	v_mfma_f32_16x16x32_bf16 v[188:191], v[168:171], v[172:175], v[96:99]
	s_setprio 0
	s_barrier
	s_nop 0
	ds_read_b128 v[96:99], v203
	ds_read_b128 v[104:107], v203 offset:1024
	ds_read_b128 v[112:115], v203 offset:2048
	ds_read_b128 v[120:123], v203 offset:3072
	s_barrier
	s_waitcnt lgkmcnt(0)
	s_setprio 1
	s_waitcnt lgkmcnt(0)
	v_mfma_f32_16x16x32_bf16 v[92:95], v[96:99], v[128:131], v[92:95]
	v_mfma_f32_16x16x32_bf16 v[88:91], v[112:115], v[128:131], v[88:91]
	v_mfma_f32_16x16x32_bf16 v[84:87], v[96:99], v[136:139], v[84:87]
	v_mfma_f32_16x16x32_bf16 v[80:83], v[112:115], v[136:139], v[80:83]
	v_mfma_f32_16x16x32_bf16 v[76:79], v[96:99], v[144:147], v[76:79]
	v_mfma_f32_16x16x32_bf16 v[72:75], v[112:115], v[144:147], v[72:75]
	v_mfma_f32_16x16x32_bf16 v[68:71], v[96:99], v[152:155], v[68:71]
	v_mfma_f32_16x16x32_bf16 v[64:67], v[112:115], v[152:155], v[64:67]
	v_mfma_f32_16x16x32_bf16 v[92:95], v[104:107], v[132:135], v[92:95]
	v_mfma_f32_16x16x32_bf16 v[128:131], v[120:123], v[132:135], v[88:91]
	v_mfma_f32_16x16x32_bf16 v[84:87], v[104:107], v[140:143], v[84:87]
	v_mfma_f32_16x16x32_bf16 v[132:135], v[120:123], v[140:143], v[80:83]
	v_mfma_f32_16x16x32_bf16 v[76:79], v[104:107], v[148:151], v[76:79]
	v_mfma_f32_16x16x32_bf16 v[136:139], v[120:123], v[148:151], v[72:75]
	v_mfma_f32_16x16x32_bf16 v[68:71], v[104:107], v[172:175], v[68:71]
	v_mfma_f32_16x16x32_bf16 v[140:143], v[120:123], v[172:175], v[64:67]
	s_setprio 0
	s_barrier
; #define LDA(dst, b, h) for (int m = 0; m < 4; ++m) for (int k = 0; k < 2; ++k) \
;     dst[m][k] = *reinterpret_cast<const bf16x8*>((char*)SA(b, h) + lds_byte(wr * 64 + m * 16 + fr, k * 32 + fq * 8))
; #define LDB(dst, b, h) for (int n = 0; n < 2; ++n) for (int k = 0; k < 2; ++k) \
;     dst[n][k] = *reinterpret_cast<const bf16x8*>((char*)SB(b, h) + lds_byte(wc * 32 + n * 16 + fr, k * 32 + fq * 8))
; #define WAIT_V(n) asm volatile("s_waitcnt vmcnt(" #n ")" ::: "memory")
; #define WAIT_L(n) asm volatile("s_waitcnt lgkmcnt(" #n ")" ::: "memory")
; #define BAR __builtin_amdgcn_s_barrier()
; #define PRO_K0(brow_, bcol_) do { STAGE(SB(0, 0), Bt, bcol_, 0); STAGE(SA(0, 0), A, brow_, 0); STAGE(SB(0, 1), Bt, (bcol_) + HALF, 0); STAGE(SA(0, 1), A, (brow_) + HALF, 0); } while (0)
; template <class Epi>
; DEVI void gemm_phase(const Params& p, const u16* __restrict__ A, const u16* __restrict__ Bt, const int M, const int N, const int K, const int Msplit, const Epi& epi) {
;     ...
;       LDA(At, 0, 1); WAIT_V(4); BAR; WAIT_L(0); MMA(1, 0, At, B0); MMA(1, 1, At, B1); BAR; }
;     { LDB(B0, 1, 0); LDA(At, 1, 0); WAIT_V(2); BAR;
;       if (have2) { const u16* Asv = A; const u16* Bsv = Bt; A = An; Bt = Bn; PRO_K0(pm * BM, pn * BM); A = Asv; Bt = Bsv; }
;       WAIT_L(0); MMA(0, 0, At, B0); BAR;
;       LDB(B1, 1, 1); if (have2) { WAIT_V(8); } else { WAIT_V(0); } BAR; WAIT_L(0); MMA(0, 1, At, B1); BAR;
;       LDA(At, 1, 1); BAR; WAIT_L(0); MMA(1, 0, At, B0); MMA(1, 1, At, B1); BAR; }
	s_nop 0
	ds_read_b128 v[64:67], v199 offset:16384
	ds_read_b128 v[72:75], v199 offset:17408
	ds_read_b128 v[80:83], v200 offset:16384
	ds_read_b128 v[88:91], v200 offset:17408
	ds_read_b128 v[172:175], v201 offset:16384
	ds_read_b128 v[192:195], v201 offset:17408
	ds_read_b128 v[206:209], v202 offset:16384
	ds_read_b128 v[214:217], v202 offset:17408
	s_waitcnt vmcnt(4)
	s_barrier
	s_waitcnt lgkmcnt(0)
	s_setprio 1
	s_waitcnt lgkmcnt(0)
	v_mfma_f32_16x16x32_bf16 v[60:63], v[156:159], v[64:67], v[60:63]
	v_mfma_f32_16x16x32_bf16 v[56:59], v[164:167], v[64:67], v[56:59]
	v_mfma_f32_16x16x32_bf16 v[52:55], v[156:159], v[80:83], v[52:55]
	v_mfma_f32_16x16x32_bf16 v[48:51], v[164:167], v[80:83], v[48:51]
	v_mfma_f32_16x16x32_bf16 v[44:47], v[156:159], v[172:175], v[44:47]
	v_mfma_f32_16x16x32_bf16 v[40:43], v[164:167], v[172:175], v[40:43]
	v_mfma_f32_16x16x32_bf16 v[36:39], v[156:159], v[206:209], v[36:39]
	v_mfma_f32_16x16x32_bf16 v[32:35], v[164:167], v[206:209], v[32:35]
	v_mfma_f32_16x16x32_bf16 v[60:63], v[160:163], v[72:75], v[60:63]
	v_mfma_f32_16x16x32_bf16 v[144:147], v[168:171], v[72:75], v[56:59]
	v_mfma_f32_16x16x32_bf16 v[52:55], v[160:163], v[88:91], v[52:55]
	v_mfma_f32_16x16x32_bf16 v[148:151], v[168:171], v[88:91], v[48:51]
	v_mfma_f32_16x16x32_bf16 v[44:47], v[160:163], v[192:195], v[44:47]
	v_mfma_f32_16x16x32_bf16 v[152:155], v[168:171], v[192:195], v[40:43]
	v_mfma_f32_16x16x32_bf16 v[36:39], v[160:163], v[214:217], v[36:39]
	v_mfma_f32_16x16x32_bf16 v[156:159], v[168:171], v[214:217], v[32:35]
	s_setprio 0
	s_setprio 1
	v_mfma_f32_16x16x32_bf16 v[28:31], v[96:99], v[64:67], v[28:31]
	v_mfma_f32_16x16x32_bf16 v[24:27], v[112:115], v[64:67], v[24:27]
	v_mfma_f32_16x16x32_bf16 v[20:23], v[96:99], v[80:83], v[20:23]
	v_mfma_f32_16x16x32_bf16 v[16:19], v[112:115], v[80:83], v[16:19]
	v_mfma_f32_16x16x32_bf16 v[12:15], v[96:99], v[172:175], v[12:15]
	v_mfma_f32_16x16x32_bf16 v[8:11], v[112:115], v[172:175], v[8:11]
	v_mfma_f32_16x16x32_bf16 v[4:7], v[96:99], v[206:209], v[4:7]
	v_mfma_f32_16x16x32_bf16 v[0:3], v[112:115], v[206:209], v[0:3]
	v_mfma_f32_16x16x32_bf16 v[28:31], v[104:107], v[72:75], v[28:31]
	v_mfma_f32_16x16x32_bf16 v[160:163], v[120:123], v[72:75], v[24:27]
	v_mfma_f32_16x16x32_bf16 v[20:23], v[104:107], v[88:91], v[20:23]
	v_mfma_f32_16x16x32_bf16 v[164:167], v[120:123], v[88:91], v[16:19]
	v_mfma_f32_16x16x32_bf16 v[12:15], v[104:107], v[192:195], v[12:15]
	v_mfma_f32_16x16x32_bf16 v[168:171], v[120:123], v[192:195], v[8:11]
	v_mfma_f32_16x16x32_bf16 v[4:7], v[104:107], v[214:217], v[4:7]
	v_mfma_f32_16x16x32_bf16 v[172:175], v[120:123], v[214:217], v[0:3]
	s_setprio 0
	s_barrier
	s_nop 0
	ds_read_b128 v[0:3], v204
	ds_read_b128 v[8:11], v204 offset:1024
	ds_read_b128 v[16:19], v204 offset:2048
	ds_read_b128 v[24:27], v204 offset:3072
	ds_read_b128 v[80:83], v199 offset:32768
	ds_read_b128 v[192:195], v199 offset:33792
	ds_read_b128 v[64:67], v200 offset:32768
	ds_read_b128 v[72:75], v200 offset:33792
	ds_read_b128 v[48:51], v201 offset:32768
	ds_read_b128 v[56:59], v201 offset:33792
	ds_read_b128 v[32:35], v202 offset:32768
	ds_read_b128 v[40:43], v202 offset:33792
	s_waitcnt vmcnt(2)
	v_cndmask_b32_e64 v88, 0, 1, s[12:13]
	v_cmp_ne_u32_e64 s[14:15], 1, v88
	s_andn2_b64 vcc, exec, s[12:13]
	s_barrier
	s_cbranch_vccnz .LBB0_1997
	s_lshl_b32 s12, s40, 8
	s_ashr_i32 s13, s12, 31
	s_lshl_b64 s[42:43], s[12:13], 11
	s_add_u32 s42, s1, s42
	s_addc_u32 s43, s2, s43
	s_mov_b32 m0, s16
	s_lshl_b32 s90, s41, 8
	v_lshl_add_u64 v[88:89], s[42:43], 0, v[212:213]
	global_load_lds_dwordx4 v[88:89], off
	v_lshl_add_u64 v[88:89], s[42:43], 0, v[196:197]
	s_lshl_b64 s[42:43], s[90:91], 11
	s_add_u32 s42, s68, s42
	s_addc_u32 s43, s69, s43
	s_bitset1_b32 s12, 7
	s_ashr_i32 s13, s12, 31
	s_mov_b32 m0, s89
	s_lshl_b64 s[12:13], s[12:13], 11
	global_load_lds_dwordx4 v[88:89], off
	s_mov_b32 m0, s19
	v_lshl_add_u64 v[88:89], s[42:43], 0, v[212:213]
	s_add_u32 s12, s1, s12
	global_load_lds_dwordx4 v[88:89], off
	v_lshl_add_u64 v[88:89], s[42:43], 0, v[196:197]
	s_mov_b32 m0, s24
	s_addc_u32 s13, s2, s13
	global_load_lds_dwordx4 v[88:89], off
	s_mov_b32 m0, s38
	v_lshl_add_u64 v[88:89], s[12:13], 0, v[212:213]
	s_bitset1_b32 s90, 7
	global_load_lds_dwordx4 v[88:89], off
	v_lshl_add_u64 v[88:89], s[12:13], 0, v[196:197]
	s_lshl_b64 s[12:13], s[90:91], 11
	s_add_u32 s12, s68, s12
	s_mov_b32 m0, s39
	s_addc_u32 s13, s69, s13
	global_load_lds_dwordx4 v[88:89], off
	s_mov_b32 m0, s25
	v_lshl_add_u64 v[88:89], s[12:13], 0, v[212:213]
	global_load_lds_dwordx4 v[88:89], off
	v_lshl_add_u64 v[88:89], s[12:13], 0, v[196:197]
	s_mov_b32 m0, s26
	s_nop 0
	global_load_lds_dwordx4 v[88:89], off

; #define LDA(dst, b, h) for (int m = 0; m < 4; ++m) for (int k = 0; k < 2; ++k) \
;     dst[m][k] = *reinterpret_cast<const bf16x8*>((char*)SA(b, h) + lds_byte(wr * 64 + m * 16 + fr, k * 32 + fq * 8))
; #define LDB(dst, b, h) for (int n = 0; n < 2; ++n) for (int k = 0; k < 2; ++k) \
;     dst[n][k] = *reinterpret_cast<const bf16x8*>((char*)SB(b, h) + lds_byte(wc * 32 + n * 16 + fr, k * 32 + fq * 8))
; #define WAIT_V(n) asm volatile("s_waitcnt vmcnt(" #n ")" ::: "memory")
; #define WAIT_L(n) asm volatile("s_waitcnt lgkmcnt(" #n ")" ::: "memory")
; #define BAR __builtin_amdgcn_s_barrier()
; #define SCHED __builtin_amdgcn_sched_barrier(0)
; template <class Epi>
; DEVI void gemm_phase(const Params& p, const u16* __restrict__ A, const u16* __restrict__ Bt, const int M, const int N, const int K, const int Msplit, const Epi& epi) {
;     ...
;     f32x4 acc[2][2][4][2] = {};
;     bf16x8 At[4][2], B0[2][2], B1[2][2];
;     if (it == 0) { WAIT_V(0); } else { if constexpr (Epi::NST == 16) WAIT_V(16); else if constexpr (Epi::NST == 32) WAIT_V(32); else WAIT_V(0); }
;     if (wr == 1) BAR;
;     BAR;
;     BAR;
;     for (int t = 0; t < nt - 2; t += 2) {
;       LDB(B0, 0, 0); SCHED; LDA(At, 0, 0); STAGE(SA(1, 1), A, brow + HALF, t + 1);
;       WAIT_L(8); BAR; WAIT_L(0); MMA(0, 0, At, B0); BAR; SCHED;
.LBB0_2079:
	s_or_b64 exec, exec, s[10:11]
	s_lshl_b32 s22, s1, 8
	s_or_b32 s10, s22, 0x80
	s_xor_b64 s[20:21], s[8:9], -1
	s_lshl_b32 s37, s2, 8
	s_add_i32 s42, s36, -2
	s_mul_hi_i32 s11, s10, 0x1600
	s_mulk_i32 s10, 0x1600
	s_add_u32 s40, s24, s10
	s_addc_u32 s41, s25, s11
	s_mul_i32 s10, s2, 0x160000
	s_mul_hi_i32 s11, s37, 0x1600
	s_add_u32 s43, s26, s10
	s_addc_u32 s52, s27, s11
	s_ashr_i32 s23, s22, 31
	s_mul_i32 s10, s1, 0x160000
	s_mul_hi_i32 s11, s22, 0x1600
	s_add_u32 s24, s24, s10
	s_addc_u32 s25, s25, s11
	s_or_b32 s10, s37, 0x80
	s_mul_hi_i32 s11, s10, 0x1600
	s_mulk_i32 s10, 0x1600
	s_add_u32 s26, s26, s10
	s_waitcnt lgkmcnt(0)
	v_mov_b32_e32 v16, 0
	s_addc_u32 s27, s27, s11
	s_mov_b32 s53, 0
	s_mov_b64 s[10:11], 0
	v_mov_b32_e32 v17, v16
	v_mov_b32_e32 v18, v16
	v_mov_b32_e32 v19, v16
	v_mov_b32_e32 v20, v16
	v_mov_b32_e32 v21, v16
	v_mov_b32_e32 v22, v16
	v_mov_b32_e32 v23, v16
	v_mov_b32_e32 v24, v16
	v_mov_b32_e32 v25, v16
	v_mov_b32_e32 v26, v16
	v_mov_b32_e32 v27, v16
	v_mov_b32_e32 v28, v16
	v_mov_b32_e32 v29, v16
	v_mov_b32_e32 v30, v16
	v_mov_b32_e32 v31, v16
	v_mov_b32_e32 v32, v16
	v_mov_b32_e32 v33, v16
	v_mov_b32_e32 v34, v16
	v_mov_b32_e32 v35, v16
	v_mov_b32_e32 v36, v16
	v_mov_b32_e32 v37, v16
	v_mov_b32_e32 v38, v16
	v_mov_b32_e32 v39, v16
	v_mov_b32_e32 v40, v16
	v_mov_b32_e32 v41, v16
	v_mov_b32_e32 v42, v16
	v_mov_b32_e32 v43, v16
	v_mov_b32_e32 v44, v16
	v_mov_b32_e32 v45, v16
	v_mov_b32_e32 v46, v16
	v_mov_b32_e32 v47, v16
	v_mov_b32_e32 v48, v16
	v_mov_b32_e32 v49, v16
	v_mov_b32_e32 v50, v16
	v_mov_b32_e32 v51, v16
	v_mov_b32_e32 v52, v16
	v_mov_b32_e32 v53, v16
	v_mov_b32_e32 v54, v16
	v_mov_b32_e32 v55, v16
	v_mov_b32_e32 v56, v16
	v_mov_b32_e32 v57, v16
	v_mov_b32_e32 v58, v16
	v_mov_b32_e32 v59, v16
	v_mov_b32_e32 v60, v16
	v_mov_b32_e32 v61, v16
	v_mov_b32_e32 v62, v16
	v_mov_b32_e32 v63, v16
	v_mov_b32_e32 v64, v16
	v_mov_b32_e32 v65, v16
	v_mov_b32_e32 v66, v16
	v_mov_b32_e32 v67, v16
	v_mov_b32_e32 v68, v16
	v_mov_b32_e32 v69, v16
	v_mov_b32_e32 v70, v16
	v_mov_b32_e32 v71, v16
	v_mov_b32_e32 v72, v16
	v_mov_b32_e32 v73, v16
	v_mov_b32_e32 v74, v16
	v_mov_b32_e32 v75, v16
	v_mov_b32_e32 v76, v16
	v_mov_b32_e32 v77, v16
	v_mov_b32_e32 v78, v16
	v_mov_b32_e32 v79, v16
	v_mov_b32_e32 v80, v16
	v_mov_b32_e32 v81, v16
	v_mov_b32_e32 v82, v16
	v_mov_b32_e32 v83, v16
	v_mov_b32_e32 v84, v16
	v_mov_b32_e32 v85, v16
	v_mov_b32_e32 v86, v16
	v_mov_b32_e32 v87, v16
	v_mov_b32_e32 v88, v16
	v_mov_b32_e32 v89, v16
	v_mov_b32_e32 v90, v16
	v_mov_b32_e32 v91, v16
	v_mov_b32_e32 v92, v16
	v_mov_b32_e32 v93, v16
	v_mov_b32_e32 v94, v16
	v_mov_b32_e32 v95, v16
	v_mov_b32_e32 v96, v16
	v_mov_b32_e32 v97, v16
	v_mov_b32_e32 v98, v16
	v_mov_b32_e32 v99, v16
	v_mov_b32_e32 v100, v16
	v_mov_b32_e32 v101, v16
	v_mov_b32_e32 v102, v16
	v_mov_b32_e32 v103, v16
	v_mov_b32_e32 v104, v16
	v_mov_b32_e32 v105, v16
	v_mov_b32_e32 v106, v16
	v_mov_b32_e32 v107, v16
	v_mov_b32_e32 v108, v16
	v_mov_b32_e32 v109, v16
	v_mov_b32_e32 v110, v16
	v_mov_b32_e32 v111, v16
	v_mov_b32_e32 v112, v16
	v_mov_b32_e32 v113, v16
	v_mov_b32_e32 v114, v16
	v_mov_b32_e32 v115, v16
	v_mov_b32_e32 v116, v16
	v_mov_b32_e32 v117, v16
	v_mov_b32_e32 v118, v16
	v_mov_b32_e32 v119, v16
	v_mov_b32_e32 v120, v16
	v_mov_b32_e32 v121, v16
	v_mov_b32_e32 v122, v16
	v_mov_b32_e32 v123, v16
	v_mov_b32_e32 v124, v16
	v_mov_b32_e32 v125, v16
	v_mov_b32_e32 v126, v16
	v_mov_b32_e32 v127, v16
	v_mov_b32_e32 v128, v16
	v_mov_b32_e32 v129, v16
	v_mov_b32_e32 v130, v16
	v_mov_b32_e32 v131, v16
	v_mov_b32_e32 v132, v16
	v_mov_b32_e32 v133, v16
	v_mov_b32_e32 v134, v16
	v_mov_b32_e32 v135, v16
	v_mov_b32_e32 v136, v16
	v_mov_b32_e32 v137, v16
	v_mov_b32_e32 v138, v16
	v_mov_b32_e32 v139, v16
	v_mov_b32_e32 v140, v16
	v_mov_b32_e32 v141, v16
	v_mov_b32_e32 v142, v16
	v_mov_b32_e32 v143, v16
	s_barrier
	s_barrier
	ds_read_b128 v[144:147], v226
	ds_read_b128 v[148:151], v226 offset:1024
	ds_read_b128 v[152:155], v226 offset:2048
	ds_read_b128 v[156:159], v226 offset:3072
.LBB0_2080:
	s_add_u32 s54, s40, s10
	s_addc_u32 s55, s41, s11
	s_add_u32 s16, s54, 0x80
	s_addc_u32 s17, s55, 0
	s_add_i32 s56, s78, 0
	s_add_i32 s47, s56, 0xc000
	ds_read_b128 v[160:163], v227
	ds_read_b128 v[164:167], v227 offset:1024
	ds_read_b128 v[168:171], v228
	ds_read_b128 v[172:175], v228 offset:1024
	ds_read_b128 v[176:179], v229
	ds_read_b128 v[180:183], v229 offset:1024
	ds_read_b128 v[184:187], v232
	ds_read_b128 v[188:191], v232 offset:1024
	s_mov_b32 m0, s47
	v_lshl_add_u64 v[192:193], s[16:17], 0, v[208:209]
	s_add_i32 s46, s56, 0xe000
	global_load_lds_dwordx4 v[192:193], off
	v_lshl_add_u64 v[192:193], s[16:17], 0, v[210:211]
	s_mov_b32 m0, s46
	s_nop 0
	global_load_lds_dwordx4 v[192:193], off
	s_waitcnt lgkmcnt(8)
	s_barrier
	s_waitcnt lgkmcnt(0)
	s_setprio 1
	s_waitcnt lgkmcnt(0)
	v_mfma_f32_16x16x32_bf16 v[140:143], v[144:147], v[160:163], v[140:143]
	v_mfma_f32_16x16x32_bf16 v[136:139], v[152:155], v[160:163], v[136:139]
	v_mfma_f32_16x16x32_bf16 v[132:135], v[144:147], v[168:171], v[132:135]
	v_mfma_f32_16x16x32_bf16 v[128:131], v[152:155], v[168:171], v[128:131]
	v_mfma_f32_16x16x32_bf16 v[124:127], v[144:147], v[176:179], v[124:127]
	v_mfma_f32_16x16x32_bf16 v[120:123], v[152:155], v[176:179], v[120:123]
	v_mfma_f32_16x16x32_bf16 v[116:119], v[144:147], v[184:187], v[116:119]
	v_mfma_f32_16x16x32_bf16 v[112:115], v[152:155], v[184:187], v[112:115]
	v_mfma_f32_16x16x32_bf16 v[140:143], v[148:151], v[164:167], v[140:143]
	v_mfma_f32_16x16x32_bf16 v[136:139], v[156:159], v[164:167], v[136:139]
	v_mfma_f32_16x16x32_bf16 v[132:135], v[148:151], v[172:175], v[132:135]
	v_mfma_f32_16x16x32_bf16 v[128:131], v[156:159], v[172:175], v[128:131]
	v_mfma_f32_16x16x32_bf16 v[124:127], v[148:151], v[180:183], v[124:127]
	v_mfma_f32_16x16x32_bf16 v[120:123], v[156:159], v[180:183], v[120:123]
	v_mfma_f32_16x16x32_bf16 v[116:119], v[148:151], v[188:191], v[116:119]
	v_mfma_f32_16x16x32_bf16 v[112:115], v[156:159], v[188:191], v[112:115]
	s_setprio 0
	s_barrier
; #define LDA(dst, b, h) for (int m = 0; m < 4; ++m) for (int k = 0; k < 2; ++k) \
;     dst[m][k] = *reinterpret_cast<const bf16x8*>((char*)SA(b, h) + lds_byte(wr * 64 + m * 16 + fr, k * 32 + fq * 8))
; #define LDB(dst, b, h) for (int n = 0; n < 2; ++n) for (int k = 0; k < 2; ++k) \
;     dst[n][k] = *reinterpret_cast<const bf16x8*>((char*)SB(b, h) + lds_byte(wc * 32 + n * 16 + fr, k * 32 + fq * 8))
; #define WAIT_V(n) asm volatile("s_waitcnt vmcnt(" #n ")" ::: "memory")
; #define WAIT_L(n) asm volatile("s_waitcnt lgkmcnt(" #n ")" ::: "memory")
; #define BAR __builtin_amdgcn_s_barrier()
; #define SCHED __builtin_amdgcn_sched_barrier(0)
; template <class Epi>
; DEVI void gemm_phase(const Params& p, const u16* __restrict__ A, const u16* __restrict__ Bt, const int M, const int N, const int K, const int Msplit, const Epi& epi) {
;     ...
;       LDB(B1, 0, 1); STAGE(SB(0, 0), Bt, bcol, t + 2);
;       BAR; WAIT_L(0); MMA(0, 1, At, B1); BAR;
;       LDA(At, 0, 1); STAGE(SA(0, 0), A, brow, t + 2);
;       BAR; WAIT_L(0); MMA(1, 0, At, B0); BAR; SCHED;
;       STAGE(SB(0, 1), Bt, bcol + HALF, t + 2);
;       WAIT_V(6); BAR; MMA(1, 1, At, B1); BAR;
;       LDB(B0, 1, 0); SCHED; LDA(At, 1, 0); STAGE(SA(0, 1), A, brow + HALF, t + 2);
	s_add_i32 s53, s53, 2
	s_add_u32 s57, s43, s10
	s_addc_u32 s58, s52, s11
	s_add_u32 s16, s57, 0x100
	s_addc_u32 s17, s58, 0
	s_add_i32 s88, s56, 0x10000
	ds_read_b128 v[192:195], v245
	ds_read_b128 v[196:199], v245 offset:1024
	ds_read_b128 v[200:203], v245 offset:2048
	ds_read_b128 v[204:207], v245 offset:3072
	s_mov_b32 m0, s88
	v_lshl_add_u64 v[214:215], s[16:17], 0, v[208:209]
	s_add_i32 s63, s56, 0x12000
	global_load_lds_dwordx4 v[214:215], off
	v_lshl_add_u64 v[214:215], s[16:17], 0, v[210:211]
	s_mov_b32 m0, s63
	s_nop 0
	global_load_lds_dwordx4 v[214:215], off
	s_barrier
	s_waitcnt lgkmcnt(0)
	s_setprio 1
	s_waitcnt lgkmcnt(0)
	v_mfma_f32_16x16x32_bf16 v[108:111], v[192:195], v[160:163], v[108:111]
	v_mfma_f32_16x16x32_bf16 v[104:107], v[200:203], v[160:163], v[104:107]
	v_mfma_f32_16x16x32_bf16 v[100:103], v[192:195], v[168:171], v[100:103]
	v_mfma_f32_16x16x32_bf16 v[96:99], v[200:203], v[168:171], v[96:99]
	v_mfma_f32_16x16x32_bf16 v[92:95], v[192:195], v[176:179], v[92:95]
	v_mfma_f32_16x16x32_bf16 v[88:91], v[200:203], v[176:179], v[88:91]
	v_mfma_f32_16x16x32_bf16 v[84:87], v[192:195], v[184:187], v[84:87]
	v_mfma_f32_16x16x32_bf16 v[80:83], v[200:203], v[184:187], v[80:83]
	v_mfma_f32_16x16x32_bf16 v[108:111], v[196:199], v[164:167], v[108:111]
	v_mfma_f32_16x16x32_bf16 v[104:107], v[204:207], v[164:167], v[104:107]
	v_mfma_f32_16x16x32_bf16 v[100:103], v[196:199], v[172:175], v[100:103]
	v_mfma_f32_16x16x32_bf16 v[96:99], v[204:207], v[172:175], v[96:99]
	v_mfma_f32_16x16x32_bf16 v[92:95], v[196:199], v[180:183], v[92:95]
	v_mfma_f32_16x16x32_bf16 v[88:91], v[204:207], v[180:183], v[88:91]
	v_mfma_f32_16x16x32_bf16 v[84:87], v[196:199], v[188:191], v[84:87]
	v_mfma_f32_16x16x32_bf16 v[80:83], v[204:207], v[188:191], v[80:83]
	s_setprio 0
	s_add_u32 s59, s24, s10
	s_addc_u32 s76, s25, s11
	s_add_u32 s16, s59, 0x100
	s_addc_u32 s17, s76, 0
	s_mov_b32 m0, s56
	s_barrier
	ds_read_b128 v[160:163], v227 offset:16384
	ds_read_b128 v[164:167], v227 offset:17408
	ds_read_b128 v[168:171], v228 offset:16384
	ds_read_b128 v[172:175], v228 offset:17408
	ds_read_b128 v[176:179], v229 offset:16384
	ds_read_b128 v[180:183], v229 offset:17408
	ds_read_b128 v[184:187], v232 offset:16384
	ds_read_b128 v[188:191], v232 offset:17408
	s_nop 0
	v_lshl_add_u64 v[214:215], s[16:17], 0, v[208:209]
	global_load_lds_dwordx4 v[214:215], off
	v_lshl_add_u64 v[214:215], s[16:17], 0, v[210:211]
	s_add_i32 s17, s56, 0x2000
	s_mov_b32 m0, s17
	s_nop 0
	global_load_lds_dwordx4 v[214:215], off
	s_waitcnt vmcnt(10)
	s_barrier
	s_waitcnt lgkmcnt(0)
	s_setprio 1
	s_waitcnt lgkmcnt(0)
	v_mfma_f32_16x16x32_bf16 v[76:79], v[144:147], v[160:163], v[76:79]
	v_mfma_f32_16x16x32_bf16 v[72:75], v[152:155], v[160:163], v[72:75]
	v_mfma_f32_16x16x32_bf16 v[68:71], v[144:147], v[168:171], v[68:71]
	v_mfma_f32_16x16x32_bf16 v[64:67], v[152:155], v[168:171], v[64:67]
	v_mfma_f32_16x16x32_bf16 v[60:63], v[144:147], v[176:179], v[60:63]
	v_mfma_f32_16x16x32_bf16 v[56:59], v[152:155], v[176:179], v[56:59]
	v_mfma_f32_16x16x32_bf16 v[52:55], v[144:147], v[184:187], v[52:55]
	v_mfma_f32_16x16x32_bf16 v[48:51], v[152:155], v[184:187], v[48:51]
	v_mfma_f32_16x16x32_bf16 v[76:79], v[148:151], v[164:167], v[76:79]
	v_mfma_f32_16x16x32_bf16 v[72:75], v[156:159], v[164:167], v[72:75]
	v_mfma_f32_16x16x32_bf16 v[68:71], v[148:151], v[172:175], v[68:71]
	v_mfma_f32_16x16x32_bf16 v[64:67], v[156:159], v[172:175], v[64:67]
	v_mfma_f32_16x16x32_bf16 v[60:63], v[148:151], v[180:183], v[60:63]
	v_mfma_f32_16x16x32_bf16 v[56:59], v[156:159], v[180:183], v[56:59]
	v_mfma_f32_16x16x32_bf16 v[52:55], v[148:151], v[188:191], v[52:55]
	v_mfma_f32_16x16x32_bf16 v[48:51], v[156:159], v[188:191], v[48:51]
	s_setprio 0
	s_barrier
	ds_read_b128 v[144:147], v246
	ds_read_b128 v[148:151], v246 offset:1024
	ds_read_b128 v[152:155], v246 offset:2048
	ds_read_b128 v[156:159], v246 offset:3072
	s_add_u32 s16, s26, s10
	s_addc_u32 s89, s27, s11
	s_add_u32 s38, s16, 0x100
	s_addc_u32 s39, s89, 0
	s_add_i32 s44, s56, 0x14000
	s_mov_b32 m0, s44
	v_lshl_add_u64 v[216:217], s[38:39], 0, v[208:209]
	s_add_i32 s45, s56, 0x16000
	global_load_lds_dwordx4 v[216:217], off
	v_lshl_add_u64 v[216:217], s[38:39], 0, v[210:211]
	s_mov_b32 m0, s45
	s_nop 0
	global_load_lds_dwordx4 v[216:217], off
	s_waitcnt vmcnt(6)
	s_barrier
	s_setprio 1
	v_mfma_f32_16x16x32_bf16 v[44:47], v[192:195], v[160:163], v[44:47]
	v_mfma_f32_16x16x32_bf16 v[40:43], v[200:203], v[160:163], v[40:43]
	v_mfma_f32_16x16x32_bf16 v[36:39], v[192:195], v[168:171], v[36:39]
	v_mfma_f32_16x16x32_bf16 v[32:35], v[200:203], v[168:171], v[32:35]
	v_mfma_f32_16x16x32_bf16 v[28:31], v[192:195], v[176:179], v[28:31]
	v_mfma_f32_16x16x32_bf16 v[24:27], v[200:203], v[176:179], v[24:27]
	v_mfma_f32_16x16x32_bf16 v[20:23], v[192:195], v[184:187], v[20:23]
	v_mfma_f32_16x16x32_bf16 v[16:19], v[200:203], v[184:187], v[16:19]
	v_mfma_f32_16x16x32_bf16 v[44:47], v[196:199], v[164:167], v[44:47]
	v_mfma_f32_16x16x32_bf16 v[40:43], v[204:207], v[164:167], v[40:43]
	v_mfma_f32_16x16x32_bf16 v[36:39], v[196:199], v[172:175], v[36:39]
	v_mfma_f32_16x16x32_bf16 v[32:35], v[204:207], v[172:175], v[32:35]
	v_mfma_f32_16x16x32_bf16 v[28:31], v[196:199], v[180:183], v[28:31]
	v_mfma_f32_16x16x32_bf16 v[24:27], v[204:207], v[180:183], v[24:27]
	v_mfma_f32_16x16x32_bf16 v[20:23], v[196:199], v[188:191], v[20:23]
	v_mfma_f32_16x16x32_bf16 v[16:19], v[204:207], v[188:191], v[16:19]
	s_setprio 0
	s_barrier
; #define LDA(dst, b, h) for (int m = 0; m < 4; ++m) for (int k = 0; k < 2; ++k) \
;     dst[m][k] = *reinterpret_cast<const bf16x8*>((char*)SA(b, h) + lds_byte(wr * 64 + m * 16 + fr, k * 32 + fq * 8))
; #define LDB(dst, b, h) for (int n = 0; n < 2; ++n) for (int k = 0; k < 2; ++k) \
;     dst[n][k] = *reinterpret_cast<const bf16x8*>((char*)SB(b, h) + lds_byte(wc * 32 + n * 16 + fr, k * 32 + fq * 8))
; #define WAIT_L(n) asm volatile("s_waitcnt lgkmcnt(" #n ")" ::: "memory")
; #define BAR __builtin_amdgcn_s_barrier()
; #define SCHED __builtin_amdgcn_sched_barrier(0)
; template <class Epi>
; DEVI void gemm_phase(const Params& p, const u16* __restrict__ A, const u16* __restrict__ Bt, const int M, const int N, const int K, const int Msplit, const Epi& epi) {
;     ...
;       LDB(B0, 1, 0); SCHED; LDA(At, 1, 0); STAGE(SA(0, 1), A, brow + HALF, t + 2);
;       WAIT_L(8); BAR; WAIT_L(0); MMA(0, 0, At, B0); BAR; SCHED;
;       LDB(B1, 1, 1); STAGE(SB(1, 0), Bt, bcol, t + 3);
;       BAR; WAIT_L(0); MMA(0, 1, At, B1); BAR;
;       LDA(At, 1, 1); STAGE(SA(1, 0), A, brow, t + 3);
;       BAR; WAIT_L(0); MMA(1, 0, At, B0); BAR; SCHED;
	s_add_u32 s54, s54, 0x100
	s_addc_u32 s55, s55, 0
	s_add_i32 s38, s56, 0x4000
	ds_read_b128 v[160:163], v227 offset:32768
	ds_read_b128 v[164:167], v227 offset:33792
	ds_read_b128 v[168:171], v228 offset:32768
	ds_read_b128 v[172:175], v228 offset:33792
	ds_read_b128 v[176:179], v229 offset:32768
	ds_read_b128 v[180:183], v229 offset:33792
	ds_read_b128 v[184:187], v232 offset:32768
	ds_read_b128 v[188:191], v232 offset:33792
	s_mov_b32 m0, s38
	v_lshl_add_u64 v[192:193], s[54:55], 0, v[208:209]
	s_add_i32 s39, s56, 0x6000
	global_load_lds_dwordx4 v[192:193], off
	v_lshl_add_u64 v[192:193], s[54:55], 0, v[210:211]
	s_mov_b32 m0, s39
	s_nop 0
	global_load_lds_dwordx4 v[192:193], off
	s_waitcnt lgkmcnt(8)
	s_barrier
	s_waitcnt lgkmcnt(0)
	s_setprio 1
	s_waitcnt lgkmcnt(0)
	v_mfma_f32_16x16x32_bf16 v[140:143], v[144:147], v[160:163], v[140:143]
	v_mfma_f32_16x16x32_bf16 v[136:139], v[152:155], v[160:163], v[136:139]
	v_mfma_f32_16x16x32_bf16 v[132:135], v[144:147], v[168:171], v[132:135]
	v_mfma_f32_16x16x32_bf16 v[128:131], v[152:155], v[168:171], v[128:131]
	v_mfma_f32_16x16x32_bf16 v[124:127], v[144:147], v[176:179], v[124:127]
	v_mfma_f32_16x16x32_bf16 v[120:123], v[152:155], v[176:179], v[120:123]
	v_mfma_f32_16x16x32_bf16 v[116:119], v[144:147], v[184:187], v[116:119]
	v_mfma_f32_16x16x32_bf16 v[112:115], v[152:155], v[184:187], v[112:115]
	v_mfma_f32_16x16x32_bf16 v[140:143], v[148:151], v[164:167], v[140:143]
	v_mfma_f32_16x16x32_bf16 v[136:139], v[156:159], v[164:167], v[136:139]
	v_mfma_f32_16x16x32_bf16 v[132:135], v[148:151], v[172:175], v[132:135]
	v_mfma_f32_16x16x32_bf16 v[128:131], v[156:159], v[172:175], v[128:131]
	v_mfma_f32_16x16x32_bf16 v[124:127], v[148:151], v[180:183], v[124:127]
	v_mfma_f32_16x16x32_bf16 v[120:123], v[156:159], v[180:183], v[120:123]
	v_mfma_f32_16x16x32_bf16 v[116:119], v[148:151], v[188:191], v[116:119]
	v_mfma_f32_16x16x32_bf16 v[112:115], v[156:159], v[188:191], v[112:115]
	s_setprio 0
	s_barrier
	s_add_u32 s54, s57, 0x180
	s_addc_u32 s55, s58, 0
	s_add_i32 s62, s56, 0x18000
	ds_read_b128 v[192:195], v247
	ds_read_b128 v[196:199], v247 offset:1024
	ds_read_b128 v[200:203], v247 offset:2048
	ds_read_b128 v[204:207], v247 offset:3072
	s_mov_b32 m0, s62
	v_lshl_add_u64 v[214:215], s[54:55], 0, v[208:209]
	s_add_i32 s57, s56, 0x1a000
	global_load_lds_dwordx4 v[214:215], off
	v_lshl_add_u64 v[214:215], s[54:55], 0, v[210:211]
	s_mov_b32 m0, s57
	s_nop 0
	global_load_lds_dwordx4 v[214:215], off
	s_barrier
	s_waitcnt lgkmcnt(0)
	s_setprio 1
	s_waitcnt lgkmcnt(0)
	v_mfma_f32_16x16x32_bf16 v[108:111], v[192:195], v[160:163], v[108:111]
	v_mfma_f32_16x16x32_bf16 v[104:107], v[200:203], v[160:163], v[104:107]
	v_mfma_f32_16x16x32_bf16 v[100:103], v[192:195], v[168:171], v[100:103]
	v_mfma_f32_16x16x32_bf16 v[96:99], v[200:203], v[168:171], v[96:99]
	v_mfma_f32_16x16x32_bf16 v[92:95], v[192:195], v[176:179], v[92:95]
	v_mfma_f32_16x16x32_bf16 v[88:91], v[200:203], v[176:179], v[88:91]
	v_mfma_f32_16x16x32_bf16 v[84:87], v[192:195], v[184:187], v[84:87]
	v_mfma_f32_16x16x32_bf16 v[80:83], v[200:203], v[184:187], v[80:83]
	v_mfma_f32_16x16x32_bf16 v[108:111], v[196:199], v[164:167], v[108:111]
	v_mfma_f32_16x16x32_bf16 v[104:107], v[204:207], v[164:167], v[104:107]
	v_mfma_f32_16x16x32_bf16 v[100:103], v[196:199], v[172:175], v[100:103]
	v_mfma_f32_16x16x32_bf16 v[96:99], v[204:207], v[172:175], v[96:99]
	v_mfma_f32_16x16x32_bf16 v[92:95], v[196:199], v[180:183], v[92:95]
	v_mfma_f32_16x16x32_bf16 v[88:91], v[204:207], v[180:183], v[88:91]
	v_mfma_f32_16x16x32_bf16 v[84:87], v[196:199], v[188:191], v[84:87]
	v_mfma_f32_16x16x32_bf16 v[80:83], v[204:207], v[188:191], v[80:83]
	s_setprio 0
	s_add_u32 s54, s59, 0x180
	s_addc_u32 s55, s76, 0
	s_add_i32 s76, s56, 0x8000
	s_barrier
	ds_read_b128 v[160:163], v227 offset:49152
	ds_read_b128 v[164:167], v227 offset:50176
	ds_read_b128 v[168:171], v228 offset:49152
	ds_read_b128 v[172:175], v228 offset:50176
	ds_read_b128 v[176:179], v229 offset:49152
	ds_read_b128 v[180:183], v229 offset:50176
	ds_read_b128 v[184:187], v232 offset:49152
	ds_read_b128 v[188:191], v232 offset:50176
	s_mov_b32 m0, s76
	v_lshl_add_u64 v[214:215], s[54:55], 0, v[208:209]
	s_add_i32 s77, s56, 0xa000
	global_load_lds_dwordx4 v[214:215], off
	v_lshl_add_u64 v[214:215], s[54:55], 0, v[210:211]
	s_mov_b32 m0, s77
	s_nop 0
	global_load_lds_dwordx4 v[214:215], off
	s_waitcnt vmcnt(10)
	s_barrier
	s_waitcnt lgkmcnt(0)
	s_setprio 1
	s_waitcnt lgkmcnt(0)
	v_mfma_f32_16x16x32_bf16 v[76:79], v[144:147], v[160:163], v[76:79]
	v_mfma_f32_16x16x32_bf16 v[72:75], v[152:155], v[160:163], v[72:75]
	v_mfma_f32_16x16x32_bf16 v[68:71], v[144:147], v[168:171], v[68:71]
	v_mfma_f32_16x16x32_bf16 v[64:67], v[152:155], v[168:171], v[64:67]
	v_mfma_f32_16x16x32_bf16 v[60:63], v[144:147], v[176:179], v[60:63]
	v_mfma_f32_16x16x32_bf16 v[56:59], v[152:155], v[176:179], v[56:59]
	v_mfma_f32_16x16x32_bf16 v[52:55], v[144:147], v[184:187], v[52:55]
	v_mfma_f32_16x16x32_bf16 v[48:51], v[152:155], v[184:187], v[48:51]
	v_mfma_f32_16x16x32_bf16 v[76:79], v[148:151], v[164:167], v[76:79]
	v_mfma_f32_16x16x32_bf16 v[72:75], v[156:159], v[164:167], v[72:75]
	v_mfma_f32_16x16x32_bf16 v[68:71], v[148:151], v[172:175], v[68:71]
	v_mfma_f32_16x16x32_bf16 v[64:67], v[156:159], v[172:175], v[64:67]
	v_mfma_f32_16x16x32_bf16 v[60:63], v[148:151], v[180:183], v[60:63]
	v_mfma_f32_16x16x32_bf16 v[56:59], v[156:159], v[180:183], v[56:59]
	v_mfma_f32_16x16x32_bf16 v[52:55], v[148:151], v[188:191], v[52:55]
	v_mfma_f32_16x16x32_bf16 v[48:51], v[156:159], v[188:191], v[48:51]
	s_setprio 0
	s_barrier
; #define LDA(dst, b, h) for (int m = 0; m < 4; ++m) for (int k = 0; k < 2; ++k) \
;     dst[m][k] = *reinterpret_cast<const bf16x8*>((char*)SA(b, h) + lds_byte(wr * 64 + m * 16 + fr, k * 32 + fq * 8))
; #define LDB(dst, b, h) for (int n = 0; n < 2; ++n) for (int k = 0; k < 2; ++k) \
;     dst[n][k] = *reinterpret_cast<const bf16x8*>((char*)SB(b, h) + lds_byte(wc * 32 + n * 16 + fr, k * 32 + fq * 8))
; #define WAIT_V(n) asm volatile("s_waitcnt vmcnt(" #n ")" ::: "memory")
; #define WAIT_L(n) asm volatile("s_waitcnt lgkmcnt(" #n ")" ::: "memory")
; #define BAR __builtin_amdgcn_s_barrier()
; template <class Epi>
; DEVI void gemm_phase(const Params& p, const u16* __restrict__ A, const u16* __restrict__ Bt, const int M, const int N, const int K, const int Msplit, const Epi& epi) {
;     ...
;       STAGE(SB(1, 1), Bt, bcol + HALF, t + 3);
;       WAIT_V(6); BAR; MMA(1, 1, At, B1); BAR;
;     }
;     { LDB(B0, 0, 0); LDA(At, 0, 0); STAGE(SA(1, 1), A, brow + HALF, nt - 1);
;       BAR; WAIT_L(0); MMA(0, 0, At, B0); BAR;
;       LDB(B1, 0, 1); BAR; WAIT_L(0); MMA(0, 1, At, B1); BAR;
;       LDA(At, 0, 1); WAIT_V(4); BAR; WAIT_L(0); MMA(1, 0, At, B0); MMA(1, 1, At, B1); BAR; }
	ds_read_b128 v[144:147], v226
	ds_read_b128 v[148:151], v226 offset:1024
	ds_read_b128 v[152:155], v226 offset:2048
	ds_read_b128 v[156:159], v226 offset:3072
	s_add_u32 s54, s16, 0x180
	s_addc_u32 s55, s89, 0
	s_add_i32 s89, s56, 0x1c000
	s_mov_b32 m0, s89
	v_lshl_add_u64 v[216:217], s[54:55], 0, v[208:209]
	s_add_i32 s16, s56, 0x1e000
	global_load_lds_dwordx4 v[216:217], off
	v_lshl_add_u64 v[216:217], s[54:55], 0, v[210:211]
	s_mov_b32 m0, s16
	s_nop 0
	global_load_lds_dwordx4 v[216:217], off
	s_waitcnt vmcnt(6)
	s_barrier
	s_setprio 1
	v_mfma_f32_16x16x32_bf16 v[44:47], v[192:195], v[160:163], v[44:47]
	v_mfma_f32_16x16x32_bf16 v[40:43], v[200:203], v[160:163], v[40:43]
	v_mfma_f32_16x16x32_bf16 v[36:39], v[192:195], v[168:171], v[36:39]
	v_mfma_f32_16x16x32_bf16 v[32:35], v[200:203], v[168:171], v[32:35]
	v_mfma_f32_16x16x32_bf16 v[28:31], v[192:195], v[176:179], v[28:31]
	v_mfma_f32_16x16x32_bf16 v[24:27], v[200:203], v[176:179], v[24:27]
	v_mfma_f32_16x16x32_bf16 v[20:23], v[192:195], v[184:187], v[20:23]
	v_mfma_f32_16x16x32_bf16 v[16:19], v[200:203], v[184:187], v[16:19]
	v_mfma_f32_16x16x32_bf16 v[44:47], v[196:199], v[164:167], v[44:47]
	v_mfma_f32_16x16x32_bf16 v[40:43], v[204:207], v[164:167], v[40:43]
	v_mfma_f32_16x16x32_bf16 v[36:39], v[196:199], v[172:175], v[36:39]
	v_mfma_f32_16x16x32_bf16 v[32:35], v[204:207], v[172:175], v[32:35]
	v_mfma_f32_16x16x32_bf16 v[28:31], v[196:199], v[180:183], v[28:31]
	v_mfma_f32_16x16x32_bf16 v[24:27], v[204:207], v[180:183], v[24:27]
	v_mfma_f32_16x16x32_bf16 v[20:23], v[196:199], v[188:191], v[20:23]
	v_mfma_f32_16x16x32_bf16 v[16:19], v[204:207], v[188:191], v[16:19]
	s_setprio 0
	s_add_u32 s10, s10, 0x100
	s_addc_u32 s11, s11, 0
	s_cmp_ge_i32 s53, s42
	s_barrier
	s_cbranch_scc0 .LBB0_2080
	s_lshl_b64 s[10:11], s[90:91], 7
	s_add_u32 s24, s60, s10
	s_addc_u32 s25, s61, s11
	s_add_u32 s26, s12, s10
	s_addc_u32 s27, s13, s11
	s_add_i32 s10, s36, -1
	s_mov_b32 s11, s91
	s_lshl_b64 s[10:11], s[10:11], 7
	s_add_u32 s10, s40, s10
	s_addc_u32 s11, s41, s11
	s_mov_b32 m0, s47
	ds_read_b128 v[144:147], v226
	ds_read_b128 v[148:151], v226 offset:1024
	ds_read_b128 v[152:155], v226 offset:2048
	ds_read_b128 v[156:159], v226 offset:3072
	ds_read_b128 v[160:163], v227
	ds_read_b128 v[164:167], v227 offset:1024
	ds_read_b128 v[168:171], v228
	ds_read_b128 v[172:175], v228 offset:1024
	ds_read_b128 v[176:179], v229
	ds_read_b128 v[180:183], v229 offset:1024
	ds_read_b128 v[184:187], v232
	ds_read_b128 v[188:191], v232 offset:1024
	s_nop 0
	v_lshl_add_u64 v[192:193], s[10:11], 0, v[208:209]
	global_load_lds_dwordx4 v[192:193], off
	v_lshl_add_u64 v[192:193], s[10:11], 0, v[210:211]
	s_mov_b32 m0, s46
	s_nop 0
	global_load_lds_dwordx4 v[192:193], off
	s_barrier
	s_waitcnt lgkmcnt(0)
	s_setprio 1
	s_waitcnt lgkmcnt(0)
	v_mfma_f32_16x16x32_bf16 v[140:143], v[144:147], v[160:163], v[140:143]
	v_mfma_f32_16x16x32_bf16 v[136:139], v[152:155], v[160:163], v[136:139]
	v_mfma_f32_16x16x32_bf16 v[132:135], v[144:147], v[168:171], v[132:135]
	v_mfma_f32_16x16x32_bf16 v[128:131], v[152:155], v[168:171], v[128:131]
	v_mfma_f32_16x16x32_bf16 v[124:127], v[144:147], v[176:179], v[124:127]
	v_mfma_f32_16x16x32_bf16 v[120:123], v[152:155], v[176:179], v[120:123]
	v_mfma_f32_16x16x32_bf16 v[116:119], v[144:147], v[184:187], v[116:119]
	v_mfma_f32_16x16x32_bf16 v[112:115], v[152:155], v[184:187], v[112:115]
	v_mfma_f32_16x16x32_bf16 v[140:143], v[148:151], v[164:167], v[140:143]
	v_mfma_f32_16x16x32_bf16 v[136:139], v[156:159], v[164:167], v[136:139]
	v_mfma_f32_16x16x32_bf16 v[132:135], v[148:151], v[172:175], v[132:135]
	v_mfma_f32_16x16x32_bf16 v[128:131], v[156:159], v[172:175], v[128:131]
	v_mfma_f32_16x16x32_bf16 v[124:127], v[148:151], v[180:183], v[124:127]
	v_mfma_f32_16x16x32_bf16 v[120:123], v[156:159], v[180:183], v[120:123]
	v_mfma_f32_16x16x32_bf16 v[116:119], v[148:151], v[188:191], v[116:119]
	v_mfma_f32_16x16x32_bf16 v[112:115], v[156:159], v[188:191], v[112:115]
	s_setprio 0
	s_barrier
	ds_read_b128 v[192:195], v245
	ds_read_b128 v[196:199], v245 offset:1024
	ds_read_b128 v[200:203], v245 offset:2048
	ds_read_b128 v[204:207], v245 offset:3072
	s_barrier
	s_waitcnt lgkmcnt(0)
	s_setprio 1
	s_waitcnt lgkmcnt(0)
	v_mfma_f32_16x16x32_bf16 v[108:111], v[192:195], v[160:163], v[108:111]
	v_mfma_f32_16x16x32_bf16 v[104:107], v[200:203], v[160:163], v[104:107]
	v_mfma_f32_16x16x32_bf16 v[100:103], v[192:195], v[168:171], v[100:103]
	v_mfma_f32_16x16x32_bf16 v[96:99], v[200:203], v[168:171], v[96:99]
	v_mfma_f32_16x16x32_bf16 v[92:95], v[192:195], v[176:179], v[92:95]
	v_mfma_f32_16x16x32_bf16 v[88:91], v[200:203], v[176:179], v[88:91]
	v_mfma_f32_16x16x32_bf16 v[84:87], v[192:195], v[184:187], v[84:87]
	v_mfma_f32_16x16x32_bf16 v[80:83], v[200:203], v[184:187], v[80:83]
	v_mfma_f32_16x16x32_bf16 v[108:111], v[196:199], v[164:167], v[108:111]
	v_mfma_f32_16x16x32_bf16 v[104:107], v[204:207], v[164:167], v[104:107]
	v_mfma_f32_16x16x32_bf16 v[100:103], v[196:199], v[172:175], v[100:103]
	v_mfma_f32_16x16x32_bf16 v[96:99], v[204:207], v[172:175], v[96:99]
	v_mfma_f32_16x16x32_bf16 v[92:95], v[196:199], v[180:183], v[92:95]
	v_mfma_f32_16x16x32_bf16 v[88:91], v[204:207], v[180:183], v[88:91]
	v_mfma_f32_16x16x32_bf16 v[84:87], v[196:199], v[188:191], v[84:87]
	v_mfma_f32_16x16x32_bf16 v[80:83], v[204:207], v[188:191], v[80:83]
	s_setprio 0
	s_barrier
; #define LDA(dst, b, h) for (int m = 0; m < 4; ++m) for (int k = 0; k < 2; ++k) \
;     dst[m][k] = *reinterpret_cast<const bf16x8*>((char*)SA(b, h) + lds_byte(wr * 64 + m * 16 + fr, k * 32 + fq * 8))
; #define LDB(dst, b, h) for (int n = 0; n < 2; ++n) for (int k = 0; k < 2; ++k) \
;     dst[n][k] = *reinterpret_cast<const bf16x8*>((char*)SB(b, h) + lds_byte(wc * 32 + n * 16 + fr, k * 32 + fq * 8))
; #define WAIT_V(n) asm volatile("s_waitcnt vmcnt(" #n ")" ::: "memory")
; #define WAIT_L(n) asm volatile("s_waitcnt lgkmcnt(" #n ")" ::: "memory")
; #define BAR __builtin_amdgcn_s_barrier()
; #define PRO_K0(brow_, bcol_) do { STAGE(SB(0, 0), Bt, bcol_, 0); STAGE(SA(0, 0), A, brow_, 0); STAGE(SB(0, 1), Bt, (bcol_) + HALF, 0); STAGE(SA(0, 1), A, (brow_) + HALF, 0); } while (0)
; template <class Epi>
; DEVI void gemm_phase(const Params& p, const u16* __restrict__ A, const u16* __restrict__ Bt, const int M, const int N, const int K, const int Msplit, const Epi& epi) {
;     ...
;       LDA(At, 0, 1); WAIT_V(4); BAR; WAIT_L(0); MMA(1, 0, At, B0); MMA(1, 1, At, B1); BAR; }
;     { LDB(B0, 1, 0); LDA(At, 1, 0); WAIT_V(2); BAR;
;       if (have2) { const u16* Asv = A; const u16* Bsv = Bt; A = An; Bt = Bn; PRO_K0(pm * BM, pn * BM); A = Asv; Bt = Bsv; }
;       WAIT_L(0); MMA(0, 0, At, B0); BAR;
;       LDB(B1, 1, 1); if (have2) { WAIT_V(8); } else { WAIT_V(0); } BAR; WAIT_L(0); MMA(0, 1, At, B1); BAR;
	ds_read_b128 v[160:163], v227 offset:16384
	ds_read_b128 v[164:167], v227 offset:17408
	ds_read_b128 v[168:171], v228 offset:16384
	ds_read_b128 v[172:175], v228 offset:17408
	ds_read_b128 v[176:179], v229 offset:16384
	ds_read_b128 v[180:183], v229 offset:17408
	ds_read_b128 v[184:187], v232 offset:16384
	ds_read_b128 v[188:191], v232 offset:17408
	s_waitcnt vmcnt(4)
	s_barrier
	s_waitcnt lgkmcnt(0)
	s_setprio 1
	s_waitcnt lgkmcnt(0)
	v_mfma_f32_16x16x32_bf16 v[76:79], v[144:147], v[160:163], v[76:79]
	v_mfma_f32_16x16x32_bf16 v[72:75], v[152:155], v[160:163], v[72:75]
	v_mfma_f32_16x16x32_bf16 v[68:71], v[144:147], v[168:171], v[68:71]
	v_mfma_f32_16x16x32_bf16 v[64:67], v[152:155], v[168:171], v[64:67]
	v_mfma_f32_16x16x32_bf16 v[60:63], v[144:147], v[176:179], v[60:63]
	v_mfma_f32_16x16x32_bf16 v[56:59], v[152:155], v[176:179], v[56:59]
	v_mfma_f32_16x16x32_bf16 v[52:55], v[144:147], v[184:187], v[52:55]
	v_mfma_f32_16x16x32_bf16 v[48:51], v[152:155], v[184:187], v[48:51]
	v_mfma_f32_16x16x32_bf16 v[76:79], v[148:151], v[164:167], v[76:79]
	v_mfma_f32_16x16x32_bf16 v[72:75], v[156:159], v[164:167], v[72:75]
	v_mfma_f32_16x16x32_bf16 v[68:71], v[148:151], v[172:175], v[68:71]
	v_mfma_f32_16x16x32_bf16 v[64:67], v[156:159], v[172:175], v[64:67]
	v_mfma_f32_16x16x32_bf16 v[60:63], v[148:151], v[180:183], v[60:63]
	v_mfma_f32_16x16x32_bf16 v[56:59], v[156:159], v[180:183], v[56:59]
	v_mfma_f32_16x16x32_bf16 v[52:55], v[148:151], v[188:191], v[52:55]
	v_mfma_f32_16x16x32_bf16 v[48:51], v[156:159], v[188:191], v[48:51]
	s_setprio 0
	s_setprio 1
	v_mfma_f32_16x16x32_bf16 v[44:47], v[192:195], v[160:163], v[44:47]
	v_mfma_f32_16x16x32_bf16 v[40:43], v[200:203], v[160:163], v[40:43]
	v_mfma_f32_16x16x32_bf16 v[36:39], v[192:195], v[168:171], v[36:39]
	v_mfma_f32_16x16x32_bf16 v[32:35], v[200:203], v[168:171], v[32:35]
	v_mfma_f32_16x16x32_bf16 v[28:31], v[192:195], v[176:179], v[28:31]
	v_mfma_f32_16x16x32_bf16 v[24:27], v[200:203], v[176:179], v[24:27]
	v_mfma_f32_16x16x32_bf16 v[20:23], v[192:195], v[184:187], v[20:23]
	v_mfma_f32_16x16x32_bf16 v[16:19], v[200:203], v[184:187], v[16:19]
	v_mfma_f32_16x16x32_bf16 v[44:47], v[196:199], v[164:167], v[44:47]
	v_mfma_f32_16x16x32_bf16 v[40:43], v[204:207], v[164:167], v[40:43]
	v_mfma_f32_16x16x32_bf16 v[36:39], v[196:199], v[172:175], v[36:39]
	v_mfma_f32_16x16x32_bf16 v[32:35], v[204:207], v[172:175], v[32:35]
	v_mfma_f32_16x16x32_bf16 v[28:31], v[196:199], v[180:183], v[28:31]
	v_mfma_f32_16x16x32_bf16 v[24:27], v[204:207], v[180:183], v[24:27]
	v_mfma_f32_16x16x32_bf16 v[20:23], v[196:199], v[188:191], v[20:23]
	v_mfma_f32_16x16x32_bf16 v[16:19], v[204:207], v[188:191], v[16:19]
	s_setprio 0
	s_barrier
	ds_read_b128 v[144:147], v246
	ds_read_b128 v[148:151], v246 offset:1024
	ds_read_b128 v[152:155], v246 offset:2048
	ds_read_b128 v[156:159], v246 offset:3072
	ds_read_b128 v[184:187], v227 offset:32768
	ds_read_b128 v[188:191], v227 offset:33792
	ds_read_b128 v[176:179], v228 offset:32768
	ds_read_b128 v[180:183], v228 offset:33792
	ds_read_b128 v[168:171], v229 offset:32768
	ds_read_b128 v[172:175], v229 offset:33792
	ds_read_b128 v[160:163], v232 offset:32768
	ds_read_b128 v[164:167], v232 offset:33792
	s_waitcnt vmcnt(2)
	s_and_b64 vcc, exec, s[8:9]
	s_mul_i32 s40, s18, 0x160000
	s_mul_i32 s36, s49, 0x160000
	s_barrier
	s_cbranch_vccz .LBB0_2083
	s_lshl_b32 s41, s18, 8
	s_mul_hi_i32 s11, s41, 0x1600
	s_add_u32 s10, s26, s40
	s_addc_u32 s11, s27, s11
	s_mov_b32 m0, s88
	s_lshl_b32 s42, s49, 8
	v_lshl_add_u64 v[192:193], s[10:11], 0, v[208:209]
	global_load_lds_dwordx4 v[192:193], off
	v_lshl_add_u64 v[192:193], s[10:11], 0, v[210:211]
	s_mul_hi_i32 s11, s42, 0x1600
	s_add_u32 s10, s24, s36
	s_mov_b32 m0, s63
	s_addc_u32 s11, s25, s11
	global_load_lds_dwordx4 v[192:193], off
	s_mov_b32 m0, s56
	v_lshl_add_u64 v[192:193], s[10:11], 0, v[208:209]
	global_load_lds_dwordx4 v[192:193], off
	v_lshl_add_u64 v[192:193], s[10:11], 0, v[210:211]
	s_or_b32 s10, s41, 0x80
	s_mul_hi_i32 s11, s10, 0x1600
	s_mulk_i32 s10, 0x1600
	s_add_u32 s10, s26, s10
	s_mov_b32 m0, s17
	s_addc_u32 s11, s27, s11
	global_load_lds_dwordx4 v[192:193], off
	s_mov_b32 m0, s44
	v_lshl_add_u64 v[192:193], s[10:11], 0, v[208:209]
	global_load_lds_dwordx4 v[192:193], off
	v_lshl_add_u64 v[192:193], s[10:11], 0, v[210:211]
	s_or_b32 s10, s42, 0x80
	s_mul_hi_i32 s11, s10, 0x1600
	s_mulk_i32 s10, 0x1600
	s_add_u32 s10, s24, s10
	s_mov_b32 m0, s45
	s_addc_u32 s11, s25, s11
	global_load_lds_dwordx4 v[192:193], off
	s_mov_b32 m0, s38
	v_lshl_add_u64 v[192:193], s[10:11], 0, v[208:209]
	global_load_lds_dwordx4 v[192:193], off
	v_lshl_add_u64 v[192:193], s[10:11], 0, v[210:211]
	s_mov_b32 m0, s39
	s_nop 0
	global_load_lds_dwordx4 v[192:193], off
